# MT=6 GEMM K-loops rewritten: global_load_lds DMA into 2-stage XOR-swizzled LDS ring, rotated MFMA pipeline, static LDS 8192
# speedup vs baseline: 1.0747x; 1.0747x over previous
.LBB0_812:
	v_mov_b32_e32 v252, 0
	ds_read_b64 v[250:251], v252
	s_waitcnt lgkmcnt(0)
	v_lshlrev_b32_e32 v0, 3, v196
	s_cmp_lt_i32 s84, 0
	v_lshrrev_b32_e32 v148, 3, v196
	v_and_b32_e32 v149, 56, v0
	s_cbranch_scc1 .LBB0_822
	s_bitcmp0_b32 s84, 8
	s_cbranch_scc1 .LBB0_815
	s_sleep 15

.LBB0_819:
	s_bfe_u32 s4, s14, 0x30005
	s_mul_i32 s9, s4, 0xc0
	s_lshl_b32 s4, s16, 12
	s_and_b32 s4, s4, 0x380000
	s_lshl_b32 s6, s13, 5
	v_lshl_add_u64 v[144:145], v[142:143], 0, s[4:5]
	s_lshl_b32 s4, s8, 8
	s_and_b32 s6, s6, 0xe0
	s_or_b32 s4, s6, s4
	s_mul_i32 s6, s4, 6
	s_ashr_i32 s7, s6, 31
	s_lshl_b64 s[34:35], s[6:7], 12
	v_lshl_add_u64 v[0:1], v[138:139], 0, s[34:35]
	v_add_co_u32_e32 v2, vcc, s18, v0
	s_lshl_b32 s4, s13, 4
	s_nop 0
	v_addc_co_u32_e32 v3, vcc, 0, v1, vcc
	s_nop 0
	v_readfirstlane_b32 s98, v0
	v_readfirstlane_b32 s99, v1
	v_add_co_u32_e32 v2, vcc, s19, v0
	s_and_b32 s33, s4, 0x380
	s_nop 0
	v_addc_co_u32_e32 v3, vcc, 0, v1, vcc
	v_add_co_u32_e32 v4, vcc, s20, v0
	s_lshl_b32 s4, s33, 12
	s_nop 0
	v_addc_co_u32_e32 v5, vcc, 0, v1, vcc
	v_add_co_u32_e32 v2, vcc, s21, v0
	v_mov_b32_e32 v64, 0
	s_nop 0
	v_addc_co_u32_e32 v3, vcc, 0, v1, vcc
	v_add_co_u32_e32 v0, vcc, 0xa0000, v0
	v_mov_b32_e32 v65, v137
	s_nop 0
	v_addc_co_u32_e32 v1, vcc, 0, v1, vcc
	v_lshl_add_u64 v[0:1], v[140:141], 0, s[4:5]
	v_add_co_u32_e32 v2, vcc, s18, v0
	s_mul_i32 s4, s8, 0x600
	s_nop 0
	v_addc_co_u32_e32 v3, vcc, 0, v1, vcc
	s_nop 0
	v_readfirstlane_b32 s100, v0
	v_readfirstlane_b32 s101, v1
	v_add_co_u32_e32 v2, vcc, 0x40000, v0
	s_add_i32 s8, s4, s9
	s_nop 0
	v_addc_co_u32_e32 v3, vcc, 0, v1, vcc
	v_add_co_u32_e32 v0, vcc, 0x60000, v0
	s_ashr_i32 s9, s8, 31
	s_nop 0
	v_addc_co_u32_e32 v1, vcc, 0, v1, vcc
	s_lshl_b64 s[8:9], s[8:9], 12
	v_lshl_add_u64 v[146:147], v[142:143], 0, s[8:9]
	s_mov_b64 s[8:9], 0
	v_mov_b32_e32 v66, v137
	v_mov_b32_e32 v67, v137
	v_mov_b32_e32 v0, 0
	v_mov_b32_e32 v1, v137
	v_mov_b32_e32 v2, v137
	v_mov_b32_e32 v3, v137
	v_mov_b32_e32 v4, 0
	v_mov_b32_e32 v5, v137
	v_mov_b32_e32 v6, v137
	v_mov_b32_e32 v7, v137
	v_mov_b32_e32 v8, 0
	v_mov_b32_e32 v9, v137
	v_mov_b32_e32 v10, v137
	v_mov_b32_e32 v11, v137
	v_mov_b32_e32 v12, 0
	v_mov_b32_e32 v13, v137
	v_mov_b32_e32 v14, v137
	v_mov_b32_e32 v15, v137
	v_mov_b32_e32 v16, 0
	v_mov_b32_e32 v17, v137
	v_mov_b32_e32 v18, v137
	v_mov_b32_e32 v19, v137
	v_mov_b32_e32 v20, 0
	v_mov_b32_e32 v21, v137
	v_mov_b32_e32 v22, v137
	v_mov_b32_e32 v23, v137
	v_mov_b32_e32 v24, 0
	v_mov_b32_e32 v25, v137
	v_mov_b32_e32 v26, v137
	v_mov_b32_e32 v27, v137
	v_mov_b32_e32 v28, 0
	v_mov_b32_e32 v29, v137
	v_mov_b32_e32 v30, v137
	v_mov_b32_e32 v31, v137
	v_mov_b32_e32 v32, 0
	v_mov_b32_e32 v33, v137
	v_mov_b32_e32 v34, v137
	v_mov_b32_e32 v35, v137
	v_mov_b32_e32 v36, 0
	v_mov_b32_e32 v37, v137
	v_mov_b32_e32 v38, v137
	v_mov_b32_e32 v39, v137
	v_mov_b32_e32 v40, 0
	v_mov_b32_e32 v41, v137
	v_mov_b32_e32 v42, v137
	v_mov_b32_e32 v43, v137
	v_mov_b32_e32 v44, 0
	v_mov_b32_e32 v45, v137
	v_mov_b32_e32 v46, v137
	v_mov_b32_e32 v47, v137
	v_mov_b32_e32 v48, 0
	v_mov_b32_e32 v49, v137
	v_mov_b32_e32 v50, v137
	v_mov_b32_e32 v51, v137
	v_mov_b32_e32 v52, 0
	v_mov_b32_e32 v53, v137
	v_mov_b32_e32 v54, v137
	v_mov_b32_e32 v55, v137
	v_mov_b32_e32 v56, 0
	v_mov_b32_e32 v57, v137
	v_mov_b32_e32 v58, v137
	v_mov_b32_e32 v59, v137
	v_mov_b32_e32 v60, 0
	v_mov_b32_e32 v61, v137
	v_mov_b32_e32 v62, v137
	v_mov_b32_e32 v63, v137
	v_mov_b32_e32 v68, 0
	v_mov_b32_e32 v69, v137
	v_mov_b32_e32 v70, v137
	v_mov_b32_e32 v71, v137
	v_mov_b32_e32 v72, 0
	v_mov_b32_e32 v73, v137
	v_mov_b32_e32 v74, v137
	v_mov_b32_e32 v75, v137
	v_mov_b32_e32 v76, 0
	v_mov_b32_e32 v77, v137
	v_mov_b32_e32 v78, v137
	v_mov_b32_e32 v79, v137
	v_mov_b32_e32 v80, 0
	v_mov_b32_e32 v81, v137
	v_mov_b32_e32 v82, v137
	v_mov_b32_e32 v83, v137
	v_mov_b32_e32 v84, 0
	v_mov_b32_e32 v85, v137
	v_mov_b32_e32 v86, v137
	v_mov_b32_e32 v87, v137
	v_mov_b32_e32 v88, 0
	v_mov_b32_e32 v89, v137
	v_mov_b32_e32 v90, v137
	v_mov_b32_e32 v91, v137
	v_mov_b32_e32 v92, 0
	v_mov_b32_e32 v93, v137
	v_mov_b32_e32 v94, v137
	v_mov_b32_e32 v95, v137
	v_and_b32_e32 v197, 63, v196
	v_lshrrev_b32_e32 v198, 3, v197
	v_and_b32_e32 v199, 7, v197
	v_xor_b32_e32 v199, v199, v198
	v_lshlrev_b32_e32 v199, 4, v199
	v_mul_u32_u24_e32 v198, 4096, v198
	v_add_u32_e32 v240, v198, v199
	v_add_u32_e32 v241, 131072, v240
	v_add_u32_e32 v242, 262144, v240
	v_add_u32_e32 v243, 393216, v240
	v_add_u32_e32 v244, 524288, v240
	v_add_u32_e32 v245, 655360, v240
	v_lshrrev_b32_e32 v198, 6, v196
	v_lshrrev_b32_e32 v199, 1, v198
	v_and_b32_e32 v198, 1, v198
	v_and_b32_e32 v190, 15, v197
	v_lshrrev_b32_e32 v191, 4, v197
	v_and_b32_e32 v192, 7, v190
	v_xor_b32_e32 v191, v191, v192
	v_lshlrev_b32_e32 v191, 4, v191
	v_mul_u32_u24_e32 v199, 0x60, v199
	v_add_u32_e32 v199, v199, v190
	v_lshl_add_u32 v246, v199, 7, v191
	v_xor_b32_e32 v247, 64, v246
	v_lshlrev_b32_e32 v198, 6, v198
	v_add_u32_e32 v198, v198, v190
	v_lshl_add_u32 v248, v198, 7, v191
	v_add_u32_e32 v248, 0x6000, v248
	v_xor_b32_e32 v249, 64, v248
	v_lshrrev_b32_e32 v198, 6, v196
	v_lshlrev_b32_e32 v198, 10, v198
	s_nop 0
	v_readfirstlane_b32 s8, v198
	s_mov_b32 s9, 15
	s_waitcnt lgkmcnt(0)
	s_barrier
	s_add_u32 m0, s8, 0
	s_nop 0
	global_load_lds_dwordx4 v240, s[98:99]
	s_add_u32 m0, s8, 4096
	s_nop 0
	global_load_lds_dwordx4 v241, s[98:99]
	s_add_u32 m0, s8, 8192
	s_nop 0
	global_load_lds_dwordx4 v242, s[98:99]
	s_add_u32 m0, s8, 12288
	s_nop 0
	global_load_lds_dwordx4 v243, s[98:99]
	s_add_u32 m0, s8, 16384
	s_nop 0
	global_load_lds_dwordx4 v244, s[98:99]
	s_add_u32 m0, s8, 20480
	s_nop 0
	global_load_lds_dwordx4 v245, s[98:99]
	s_add_u32 m0, s8, 24576
	s_nop 0
	global_load_lds_dwordx4 v240, s[100:101]
	s_add_u32 m0, s8, 28672
	s_nop 0
	global_load_lds_dwordx4 v241, s[100:101]
	s_add_u32 m0, s8, 32768
	s_nop 0
	global_load_lds_dwordx4 v242, s[100:101]
	s_add_u32 m0, s8, 36864
	s_nop 0
	global_load_lds_dwordx4 v243, s[100:101]
	s_add_u32 s98, s98, 0x80
	s_addc_u32 s99, s99, 0
	s_add_u32 s100, s100, 0x80
	s_addc_u32 s101, s101, 0
	s_waitcnt vmcnt(0)
	s_barrier
	ds_read_b128 v[120:123], v248 offset:0
	ds_read_b128 v[124:127], v248 offset:2048
	ds_read_b128 v[128:131], v248 offset:4096
	ds_read_b128 v[132:135], v248 offset:6144
	ds_read_b128 v[96:99], v246 offset:0
	ds_read_b128 v[100:103], v246 offset:2048
	ds_read_b128 v[104:107], v246 offset:4096
	ds_read_b128 v[108:111], v246 offset:6144
	ds_read_b128 v[112:115], v246 offset:8192
	ds_read_b128 v[116:119], v246 offset:10240
	s_add_u32 m0, s8, 40960
	s_nop 0
	global_load_lds_dwordx4 v240, s[98:99]
	s_add_u32 m0, s8, 45056
	s_nop 0
	global_load_lds_dwordx4 v241, s[98:99]
	s_add_u32 m0, s8, 49152
	s_nop 0
	global_load_lds_dwordx4 v242, s[98:99]
	s_add_u32 m0, s8, 53248
	s_nop 0
	global_load_lds_dwordx4 v243, s[98:99]
	s_add_u32 m0, s8, 57344
	s_nop 0
	global_load_lds_dwordx4 v244, s[98:99]
	s_add_u32 m0, s8, 61440
	s_nop 0
	global_load_lds_dwordx4 v245, s[98:99]
	s_add_u32 m0, s8, 65536
	s_nop 0
	global_load_lds_dwordx4 v240, s[100:101]
	s_add_u32 m0, s8, 69632
	s_nop 0
	global_load_lds_dwordx4 v241, s[100:101]
	s_add_u32 m0, s8, 73728
	s_nop 0
	global_load_lds_dwordx4 v242, s[100:101]
	s_add_u32 m0, s8, 77824
	s_nop 0
	global_load_lds_dwordx4 v243, s[100:101]
	s_add_u32 s98, s98, 0x80
	s_addc_u32 s99, s99, 0
	s_add_u32 s100, s100, 0x80
	s_addc_u32 s101, s101, 0
	s_waitcnt lgkmcnt(0)
	v_mfma_f32_16x16x32_bf16 v[92:95], v[120:123], v[96:99], v[92:95]
	v_mfma_f32_16x16x32_bf16 v[88:91], v[124:127], v[96:99], v[88:91]
	ds_read_b128 v[224:227], v249 offset:0
	v_mfma_f32_16x16x32_bf16 v[84:87], v[128:131], v[96:99], v[84:87]
	v_mfma_f32_16x16x32_bf16 v[80:83], v[132:135], v[96:99], v[80:83]
	ds_read_b128 v[228:231], v249 offset:2048
	v_mfma_f32_16x16x32_bf16 v[76:79], v[120:123], v[100:103], v[76:79]
	v_mfma_f32_16x16x32_bf16 v[72:75], v[124:127], v[100:103], v[72:75]
	ds_read_b128 v[232:235], v249 offset:4096
	v_mfma_f32_16x16x32_bf16 v[68:71], v[128:131], v[100:103], v[68:71]
	v_mfma_f32_16x16x32_bf16 v[60:63], v[132:135], v[100:103], v[60:63]
	ds_read_b128 v[236:239], v249 offset:6144
	v_mfma_f32_16x16x32_bf16 v[56:59], v[120:123], v[104:107], v[56:59]
	v_mfma_f32_16x16x32_bf16 v[52:55], v[124:127], v[104:107], v[52:55]
	ds_read_b128 v[200:203], v247 offset:0
	v_mfma_f32_16x16x32_bf16 v[48:51], v[128:131], v[104:107], v[48:51]
	v_mfma_f32_16x16x32_bf16 v[44:47], v[132:135], v[104:107], v[44:47]
	ds_read_b128 v[204:207], v247 offset:2048
	v_mfma_f32_16x16x32_bf16 v[40:43], v[120:123], v[108:111], v[40:43]
	v_mfma_f32_16x16x32_bf16 v[36:39], v[124:127], v[108:111], v[36:39]
	ds_read_b128 v[208:211], v247 offset:4096
	v_mfma_f32_16x16x32_bf16 v[32:35], v[128:131], v[108:111], v[32:35]
	v_mfma_f32_16x16x32_bf16 v[28:31], v[132:135], v[108:111], v[28:31]
	ds_read_b128 v[212:215], v247 offset:6144
	v_mfma_f32_16x16x32_bf16 v[24:27], v[120:123], v[112:115], v[24:27]
	v_mfma_f32_16x16x32_bf16 v[20:23], v[124:127], v[112:115], v[20:23]
	ds_read_b128 v[216:219], v247 offset:8192
	v_mfma_f32_16x16x32_bf16 v[16:19], v[128:131], v[112:115], v[16:19]
	v_mfma_f32_16x16x32_bf16 v[12:15], v[132:135], v[112:115], v[12:15]
	ds_read_b128 v[220:223], v247 offset:10240
	v_mfma_f32_16x16x32_bf16 v[8:11], v[120:123], v[116:119], v[8:11]
	v_mfma_f32_16x16x32_bf16 v[4:7], v[124:127], v[116:119], v[4:7]
	v_mfma_f32_16x16x32_bf16 v[0:3], v[128:131], v[116:119], v[0:3]
	v_mfma_f32_16x16x32_bf16 v[64:67], v[132:135], v[116:119], v[64:67]
.Lg6p5_loop:
	s_waitcnt vmcnt(0) lgkmcnt(0)
	s_barrier
	ds_read_b128 v[120:123], v248 offset:40960
	ds_read_b128 v[124:127], v248 offset:43008
	ds_read_b128 v[128:131], v248 offset:45056
	ds_read_b128 v[132:135], v248 offset:47104
	ds_read_b128 v[96:99], v246 offset:40960
	ds_read_b128 v[100:103], v246 offset:43008
	ds_read_b128 v[104:107], v246 offset:45056
	ds_read_b128 v[108:111], v246 offset:47104
	ds_read_b128 v[112:115], v246 offset:49152
	ds_read_b128 v[116:119], v246 offset:51200
	s_add_u32 m0, s8, 0
	v_mfma_f32_16x16x32_bf16 v[92:95], v[224:227], v[200:203], v[92:95]
	global_load_lds_dwordx4 v240, s[98:99]
	v_mfma_f32_16x16x32_bf16 v[88:91], v[228:231], v[200:203], v[88:91]
	s_add_u32 m0, s8, 4096
	v_mfma_f32_16x16x32_bf16 v[84:87], v[232:235], v[200:203], v[84:87]
	global_load_lds_dwordx4 v241, s[98:99]
	v_mfma_f32_16x16x32_bf16 v[80:83], v[236:239], v[200:203], v[80:83]
	s_add_u32 m0, s8, 8192
	v_mfma_f32_16x16x32_bf16 v[76:79], v[224:227], v[204:207], v[76:79]
	global_load_lds_dwordx4 v242, s[98:99]
	v_mfma_f32_16x16x32_bf16 v[72:75], v[228:231], v[204:207], v[72:75]
	s_add_u32 m0, s8, 12288
	v_mfma_f32_16x16x32_bf16 v[68:71], v[232:235], v[204:207], v[68:71]
	global_load_lds_dwordx4 v243, s[98:99]
	v_mfma_f32_16x16x32_bf16 v[60:63], v[236:239], v[204:207], v[60:63]
	s_add_u32 m0, s8, 16384
	v_mfma_f32_16x16x32_bf16 v[56:59], v[224:227], v[208:211], v[56:59]
	global_load_lds_dwordx4 v244, s[98:99]
	v_mfma_f32_16x16x32_bf16 v[52:55], v[228:231], v[208:211], v[52:55]
	s_add_u32 m0, s8, 20480
	v_mfma_f32_16x16x32_bf16 v[48:51], v[232:235], v[208:211], v[48:51]
	global_load_lds_dwordx4 v245, s[98:99]
	v_mfma_f32_16x16x32_bf16 v[44:47], v[236:239], v[208:211], v[44:47]
	s_add_u32 m0, s8, 24576
	v_mfma_f32_16x16x32_bf16 v[40:43], v[224:227], v[212:215], v[40:43]
	global_load_lds_dwordx4 v240, s[100:101]
	v_mfma_f32_16x16x32_bf16 v[36:39], v[228:231], v[212:215], v[36:39]
	s_add_u32 m0, s8, 28672
	v_mfma_f32_16x16x32_bf16 v[32:35], v[232:235], v[212:215], v[32:35]
	global_load_lds_dwordx4 v241, s[100:101]
	v_mfma_f32_16x16x32_bf16 v[28:31], v[236:239], v[212:215], v[28:31]
	s_add_u32 m0, s8, 32768
	v_mfma_f32_16x16x32_bf16 v[24:27], v[224:227], v[216:219], v[24:27]
	global_load_lds_dwordx4 v242, s[100:101]
	v_mfma_f32_16x16x32_bf16 v[20:23], v[228:231], v[216:219], v[20:23]
	s_add_u32 m0, s8, 36864
	v_mfma_f32_16x16x32_bf16 v[16:19], v[232:235], v[216:219], v[16:19]
	global_load_lds_dwordx4 v243, s[100:101]
	v_mfma_f32_16x16x32_bf16 v[12:15], v[236:239], v[216:219], v[12:15]
	v_mfma_f32_16x16x32_bf16 v[8:11], v[224:227], v[220:223], v[8:11]
	v_mfma_f32_16x16x32_bf16 v[4:7], v[228:231], v[220:223], v[4:7]
	v_mfma_f32_16x16x32_bf16 v[0:3], v[232:235], v[220:223], v[0:3]
	v_mfma_f32_16x16x32_bf16 v[64:67], v[236:239], v[220:223], v[64:67]
	s_add_u32 s98, s98, 0x80
	s_addc_u32 s99, s99, 0
	s_add_u32 s100, s100, 0x80
	s_addc_u32 s101, s101, 0
	s_waitcnt lgkmcnt(0)
	v_mfma_f32_16x16x32_bf16 v[92:95], v[120:123], v[96:99], v[92:95]
	v_mfma_f32_16x16x32_bf16 v[88:91], v[124:127], v[96:99], v[88:91]
	ds_read_b128 v[224:227], v249 offset:40960
	v_mfma_f32_16x16x32_bf16 v[84:87], v[128:131], v[96:99], v[84:87]
	v_mfma_f32_16x16x32_bf16 v[80:83], v[132:135], v[96:99], v[80:83]
	ds_read_b128 v[228:231], v249 offset:43008
	v_mfma_f32_16x16x32_bf16 v[76:79], v[120:123], v[100:103], v[76:79]
	v_mfma_f32_16x16x32_bf16 v[72:75], v[124:127], v[100:103], v[72:75]
	ds_read_b128 v[232:235], v249 offset:45056
	v_mfma_f32_16x16x32_bf16 v[68:71], v[128:131], v[100:103], v[68:71]
	v_mfma_f32_16x16x32_bf16 v[60:63], v[132:135], v[100:103], v[60:63]
	ds_read_b128 v[236:239], v249 offset:47104
	v_mfma_f32_16x16x32_bf16 v[56:59], v[120:123], v[104:107], v[56:59]
	v_mfma_f32_16x16x32_bf16 v[52:55], v[124:127], v[104:107], v[52:55]
	ds_read_b128 v[200:203], v247 offset:40960
	v_mfma_f32_16x16x32_bf16 v[48:51], v[128:131], v[104:107], v[48:51]
	v_mfma_f32_16x16x32_bf16 v[44:47], v[132:135], v[104:107], v[44:47]
	ds_read_b128 v[204:207], v247 offset:43008
	v_mfma_f32_16x16x32_bf16 v[40:43], v[120:123], v[108:111], v[40:43]
	v_mfma_f32_16x16x32_bf16 v[36:39], v[124:127], v[108:111], v[36:39]
	ds_read_b128 v[208:211], v247 offset:45056
	v_mfma_f32_16x16x32_bf16 v[32:35], v[128:131], v[108:111], v[32:35]
	v_mfma_f32_16x16x32_bf16 v[28:31], v[132:135], v[108:111], v[28:31]
	ds_read_b128 v[212:215], v247 offset:47104
	v_mfma_f32_16x16x32_bf16 v[24:27], v[120:123], v[112:115], v[24:27]
	v_mfma_f32_16x16x32_bf16 v[20:23], v[124:127], v[112:115], v[20:23]
	ds_read_b128 v[216:219], v247 offset:49152
	v_mfma_f32_16x16x32_bf16 v[16:19], v[128:131], v[112:115], v[16:19]
	v_mfma_f32_16x16x32_bf16 v[12:15], v[132:135], v[112:115], v[12:15]
	ds_read_b128 v[220:223], v247 offset:51200
	v_mfma_f32_16x16x32_bf16 v[8:11], v[120:123], v[116:119], v[8:11]
	v_mfma_f32_16x16x32_bf16 v[4:7], v[124:127], v[116:119], v[4:7]
	v_mfma_f32_16x16x32_bf16 v[0:3], v[128:131], v[116:119], v[0:3]
	v_mfma_f32_16x16x32_bf16 v[64:67], v[132:135], v[116:119], v[64:67]
	s_waitcnt vmcnt(0) lgkmcnt(0)
	s_barrier
	ds_read_b128 v[120:123], v248 offset:0
	ds_read_b128 v[124:127], v248 offset:2048
	ds_read_b128 v[128:131], v248 offset:4096
	ds_read_b128 v[132:135], v248 offset:6144
	ds_read_b128 v[96:99], v246 offset:0
	ds_read_b128 v[100:103], v246 offset:2048
	ds_read_b128 v[104:107], v246 offset:4096
	ds_read_b128 v[108:111], v246 offset:6144
	ds_read_b128 v[112:115], v246 offset:8192
	ds_read_b128 v[116:119], v246 offset:10240
	s_add_u32 m0, s8, 40960
	v_mfma_f32_16x16x32_bf16 v[92:95], v[224:227], v[200:203], v[92:95]
	global_load_lds_dwordx4 v240, s[98:99]
	v_mfma_f32_16x16x32_bf16 v[88:91], v[228:231], v[200:203], v[88:91]
	s_add_u32 m0, s8, 45056
	v_mfma_f32_16x16x32_bf16 v[84:87], v[232:235], v[200:203], v[84:87]
	global_load_lds_dwordx4 v241, s[98:99]
	v_mfma_f32_16x16x32_bf16 v[80:83], v[236:239], v[200:203], v[80:83]
	s_add_u32 m0, s8, 49152
	v_mfma_f32_16x16x32_bf16 v[76:79], v[224:227], v[204:207], v[76:79]
	global_load_lds_dwordx4 v242, s[98:99]
	v_mfma_f32_16x16x32_bf16 v[72:75], v[228:231], v[204:207], v[72:75]
	s_add_u32 m0, s8, 53248
	v_mfma_f32_16x16x32_bf16 v[68:71], v[232:235], v[204:207], v[68:71]
	global_load_lds_dwordx4 v243, s[98:99]
	v_mfma_f32_16x16x32_bf16 v[60:63], v[236:239], v[204:207], v[60:63]
	s_add_u32 m0, s8, 57344
	v_mfma_f32_16x16x32_bf16 v[56:59], v[224:227], v[208:211], v[56:59]
	global_load_lds_dwordx4 v244, s[98:99]
	v_mfma_f32_16x16x32_bf16 v[52:55], v[228:231], v[208:211], v[52:55]
	s_add_u32 m0, s8, 61440
	v_mfma_f32_16x16x32_bf16 v[48:51], v[232:235], v[208:211], v[48:51]
	global_load_lds_dwordx4 v245, s[98:99]
	v_mfma_f32_16x16x32_bf16 v[44:47], v[236:239], v[208:211], v[44:47]
	s_add_u32 m0, s8, 65536
	v_mfma_f32_16x16x32_bf16 v[40:43], v[224:227], v[212:215], v[40:43]
	global_load_lds_dwordx4 v240, s[100:101]
	v_mfma_f32_16x16x32_bf16 v[36:39], v[228:231], v[212:215], v[36:39]
	s_add_u32 m0, s8, 69632
	v_mfma_f32_16x16x32_bf16 v[32:35], v[232:235], v[212:215], v[32:35]
	global_load_lds_dwordx4 v241, s[100:101]
	v_mfma_f32_16x16x32_bf16 v[28:31], v[236:239], v[212:215], v[28:31]
	s_add_u32 m0, s8, 73728
	v_mfma_f32_16x16x32_bf16 v[24:27], v[224:227], v[216:219], v[24:27]
	global_load_lds_dwordx4 v242, s[100:101]
	v_mfma_f32_16x16x32_bf16 v[20:23], v[228:231], v[216:219], v[20:23]
	s_add_u32 m0, s8, 77824
	v_mfma_f32_16x16x32_bf16 v[16:19], v[232:235], v[216:219], v[16:19]
	global_load_lds_dwordx4 v243, s[100:101]
	v_mfma_f32_16x16x32_bf16 v[12:15], v[236:239], v[216:219], v[12:15]
	v_mfma_f32_16x16x32_bf16 v[8:11], v[224:227], v[220:223], v[8:11]
	v_mfma_f32_16x16x32_bf16 v[4:7], v[228:231], v[220:223], v[4:7]
	v_mfma_f32_16x16x32_bf16 v[0:3], v[232:235], v[220:223], v[0:3]
	v_mfma_f32_16x16x32_bf16 v[64:67], v[236:239], v[220:223], v[64:67]
	s_add_u32 s98, s98, 0x80
	s_addc_u32 s99, s99, 0
	s_add_u32 s100, s100, 0x80
	s_addc_u32 s101, s101, 0
	s_waitcnt lgkmcnt(0)
	v_mfma_f32_16x16x32_bf16 v[92:95], v[120:123], v[96:99], v[92:95]
	v_mfma_f32_16x16x32_bf16 v[88:91], v[124:127], v[96:99], v[88:91]
	ds_read_b128 v[224:227], v249 offset:0
	v_mfma_f32_16x16x32_bf16 v[84:87], v[128:131], v[96:99], v[84:87]
	v_mfma_f32_16x16x32_bf16 v[80:83], v[132:135], v[96:99], v[80:83]
	ds_read_b128 v[228:231], v249 offset:2048
	v_mfma_f32_16x16x32_bf16 v[76:79], v[120:123], v[100:103], v[76:79]
	v_mfma_f32_16x16x32_bf16 v[72:75], v[124:127], v[100:103], v[72:75]
	ds_read_b128 v[232:235], v249 offset:4096
	v_mfma_f32_16x16x32_bf16 v[68:71], v[128:131], v[100:103], v[68:71]
	v_mfma_f32_16x16x32_bf16 v[60:63], v[132:135], v[100:103], v[60:63]
	ds_read_b128 v[236:239], v249 offset:6144
	v_mfma_f32_16x16x32_bf16 v[56:59], v[120:123], v[104:107], v[56:59]
	v_mfma_f32_16x16x32_bf16 v[52:55], v[124:127], v[104:107], v[52:55]
	ds_read_b128 v[200:203], v247 offset:0
	v_mfma_f32_16x16x32_bf16 v[48:51], v[128:131], v[104:107], v[48:51]
	v_mfma_f32_16x16x32_bf16 v[44:47], v[132:135], v[104:107], v[44:47]
	ds_read_b128 v[204:207], v247 offset:2048
	v_mfma_f32_16x16x32_bf16 v[40:43], v[120:123], v[108:111], v[40:43]
	v_mfma_f32_16x16x32_bf16 v[36:39], v[124:127], v[108:111], v[36:39]
	ds_read_b128 v[208:211], v247 offset:4096
	v_mfma_f32_16x16x32_bf16 v[32:35], v[128:131], v[108:111], v[32:35]
	v_mfma_f32_16x16x32_bf16 v[28:31], v[132:135], v[108:111], v[28:31]
	ds_read_b128 v[212:215], v247 offset:6144
	v_mfma_f32_16x16x32_bf16 v[24:27], v[120:123], v[112:115], v[24:27]
	v_mfma_f32_16x16x32_bf16 v[20:23], v[124:127], v[112:115], v[20:23]
	ds_read_b128 v[216:219], v247 offset:8192
	v_mfma_f32_16x16x32_bf16 v[16:19], v[128:131], v[112:115], v[16:19]
	v_mfma_f32_16x16x32_bf16 v[12:15], v[132:135], v[112:115], v[12:15]
	ds_read_b128 v[220:223], v247 offset:10240
	v_mfma_f32_16x16x32_bf16 v[8:11], v[120:123], v[116:119], v[8:11]
	v_mfma_f32_16x16x32_bf16 v[4:7], v[124:127], v[116:119], v[4:7]
	v_mfma_f32_16x16x32_bf16 v[0:3], v[128:131], v[116:119], v[0:3]
	v_mfma_f32_16x16x32_bf16 v[64:67], v[132:135], v[116:119], v[64:67]
	s_sub_u32 s9, s9, 1
	s_cmp_lg_u32 s9, 0
	s_cbranch_scc1 .Lg6p5_loop
	s_waitcnt vmcnt(0) lgkmcnt(0)
	s_barrier
	ds_read_b128 v[120:123], v248 offset:40960
	ds_read_b128 v[124:127], v248 offset:43008
	ds_read_b128 v[128:131], v248 offset:45056
	ds_read_b128 v[132:135], v248 offset:47104
	ds_read_b128 v[96:99], v246 offset:40960
	ds_read_b128 v[100:103], v246 offset:43008
	ds_read_b128 v[104:107], v246 offset:45056
	ds_read_b128 v[108:111], v246 offset:47104
	ds_read_b128 v[112:115], v246 offset:49152
	ds_read_b128 v[116:119], v246 offset:51200
	v_mfma_f32_16x16x32_bf16 v[92:95], v[224:227], v[200:203], v[92:95]
	v_mfma_f32_16x16x32_bf16 v[88:91], v[228:231], v[200:203], v[88:91]
	v_mfma_f32_16x16x32_bf16 v[84:87], v[232:235], v[200:203], v[84:87]
	v_mfma_f32_16x16x32_bf16 v[80:83], v[236:239], v[200:203], v[80:83]
	v_mfma_f32_16x16x32_bf16 v[76:79], v[224:227], v[204:207], v[76:79]
	v_mfma_f32_16x16x32_bf16 v[72:75], v[228:231], v[204:207], v[72:75]
	v_mfma_f32_16x16x32_bf16 v[68:71], v[232:235], v[204:207], v[68:71]
	v_mfma_f32_16x16x32_bf16 v[60:63], v[236:239], v[204:207], v[60:63]
	v_mfma_f32_16x16x32_bf16 v[56:59], v[224:227], v[208:211], v[56:59]
	v_mfma_f32_16x16x32_bf16 v[52:55], v[228:231], v[208:211], v[52:55]
	v_mfma_f32_16x16x32_bf16 v[48:51], v[232:235], v[208:211], v[48:51]
	v_mfma_f32_16x16x32_bf16 v[44:47], v[236:239], v[208:211], v[44:47]
	v_mfma_f32_16x16x32_bf16 v[40:43], v[224:227], v[212:215], v[40:43]
	v_mfma_f32_16x16x32_bf16 v[36:39], v[228:231], v[212:215], v[36:39]
	v_mfma_f32_16x16x32_bf16 v[32:35], v[232:235], v[212:215], v[32:35]
	v_mfma_f32_16x16x32_bf16 v[28:31], v[236:239], v[212:215], v[28:31]
	v_mfma_f32_16x16x32_bf16 v[24:27], v[224:227], v[216:219], v[24:27]
	v_mfma_f32_16x16x32_bf16 v[20:23], v[228:231], v[216:219], v[20:23]
	v_mfma_f32_16x16x32_bf16 v[16:19], v[232:235], v[216:219], v[16:19]
	v_mfma_f32_16x16x32_bf16 v[12:15], v[236:239], v[216:219], v[12:15]
	v_mfma_f32_16x16x32_bf16 v[8:11], v[224:227], v[220:223], v[8:11]
	v_mfma_f32_16x16x32_bf16 v[4:7], v[228:231], v[220:223], v[4:7]
	v_mfma_f32_16x16x32_bf16 v[0:3], v[232:235], v[220:223], v[0:3]
	v_mfma_f32_16x16x32_bf16 v[64:67], v[236:239], v[220:223], v[64:67]
	s_waitcnt lgkmcnt(0)
	v_mfma_f32_16x16x32_bf16 v[92:95], v[120:123], v[96:99], v[92:95]
	v_mfma_f32_16x16x32_bf16 v[88:91], v[124:127], v[96:99], v[88:91]
	ds_read_b128 v[224:227], v249 offset:40960
	v_mfma_f32_16x16x32_bf16 v[84:87], v[128:131], v[96:99], v[84:87]
	v_mfma_f32_16x16x32_bf16 v[80:83], v[132:135], v[96:99], v[80:83]
	ds_read_b128 v[228:231], v249 offset:43008
	v_mfma_f32_16x16x32_bf16 v[76:79], v[120:123], v[100:103], v[76:79]
	v_mfma_f32_16x16x32_bf16 v[72:75], v[124:127], v[100:103], v[72:75]
	ds_read_b128 v[232:235], v249 offset:45056
	v_mfma_f32_16x16x32_bf16 v[68:71], v[128:131], v[100:103], v[68:71]
	v_mfma_f32_16x16x32_bf16 v[60:63], v[132:135], v[100:103], v[60:63]
	ds_read_b128 v[236:239], v249 offset:47104
	v_mfma_f32_16x16x32_bf16 v[56:59], v[120:123], v[104:107], v[56:59]
	v_mfma_f32_16x16x32_bf16 v[52:55], v[124:127], v[104:107], v[52:55]
	ds_read_b128 v[200:203], v247 offset:40960
	v_mfma_f32_16x16x32_bf16 v[48:51], v[128:131], v[104:107], v[48:51]
	v_mfma_f32_16x16x32_bf16 v[44:47], v[132:135], v[104:107], v[44:47]
	ds_read_b128 v[204:207], v247 offset:43008
	v_mfma_f32_16x16x32_bf16 v[40:43], v[120:123], v[108:111], v[40:43]
	v_mfma_f32_16x16x32_bf16 v[36:39], v[124:127], v[108:111], v[36:39]
	ds_read_b128 v[208:211], v247 offset:45056
	v_mfma_f32_16x16x32_bf16 v[32:35], v[128:131], v[108:111], v[32:35]
	v_mfma_f32_16x16x32_bf16 v[28:31], v[132:135], v[108:111], v[28:31]
	ds_read_b128 v[212:215], v247 offset:47104
	v_mfma_f32_16x16x32_bf16 v[24:27], v[120:123], v[112:115], v[24:27]
	v_mfma_f32_16x16x32_bf16 v[20:23], v[124:127], v[112:115], v[20:23]
	ds_read_b128 v[216:219], v247 offset:49152
	v_mfma_f32_16x16x32_bf16 v[16:19], v[128:131], v[112:115], v[16:19]
	v_mfma_f32_16x16x32_bf16 v[12:15], v[132:135], v[112:115], v[12:15]
	ds_read_b128 v[220:223], v247 offset:51200
	v_mfma_f32_16x16x32_bf16 v[8:11], v[120:123], v[116:119], v[8:11]
	v_mfma_f32_16x16x32_bf16 v[4:7], v[124:127], v[116:119], v[4:7]
	v_mfma_f32_16x16x32_bf16 v[0:3], v[128:131], v[116:119], v[0:3]
	v_mfma_f32_16x16x32_bf16 v[64:67], v[132:135], v[116:119], v[64:67]
	s_waitcnt lgkmcnt(0)
	v_mfma_f32_16x16x32_bf16 v[92:95], v[224:227], v[200:203], v[92:95]
	v_mfma_f32_16x16x32_bf16 v[88:91], v[228:231], v[200:203], v[88:91]
	v_mfma_f32_16x16x32_bf16 v[84:87], v[232:235], v[200:203], v[84:87]
	v_mfma_f32_16x16x32_bf16 v[80:83], v[236:239], v[200:203], v[80:83]
	v_mfma_f32_16x16x32_bf16 v[76:79], v[224:227], v[204:207], v[76:79]
	v_mfma_f32_16x16x32_bf16 v[72:75], v[228:231], v[204:207], v[72:75]
	v_mfma_f32_16x16x32_bf16 v[68:71], v[232:235], v[204:207], v[68:71]
	v_mfma_f32_16x16x32_bf16 v[60:63], v[236:239], v[204:207], v[60:63]
	v_mfma_f32_16x16x32_bf16 v[56:59], v[224:227], v[208:211], v[56:59]
	v_mfma_f32_16x16x32_bf16 v[52:55], v[228:231], v[208:211], v[52:55]
	v_mfma_f32_16x16x32_bf16 v[48:51], v[232:235], v[208:211], v[48:51]
	v_mfma_f32_16x16x32_bf16 v[44:47], v[236:239], v[208:211], v[44:47]
	v_mfma_f32_16x16x32_bf16 v[40:43], v[224:227], v[212:215], v[40:43]
	v_mfma_f32_16x16x32_bf16 v[36:39], v[228:231], v[212:215], v[36:39]
	v_mfma_f32_16x16x32_bf16 v[32:35], v[232:235], v[212:215], v[32:35]
	v_mfma_f32_16x16x32_bf16 v[28:31], v[236:239], v[212:215], v[28:31]
	v_mfma_f32_16x16x32_bf16 v[24:27], v[224:227], v[216:219], v[24:27]
	v_mfma_f32_16x16x32_bf16 v[20:23], v[228:231], v[216:219], v[20:23]
	v_mfma_f32_16x16x32_bf16 v[16:19], v[232:235], v[216:219], v[16:19]
	v_mfma_f32_16x16x32_bf16 v[12:15], v[236:239], v[216:219], v[12:15]
	v_mfma_f32_16x16x32_bf16 v[8:11], v[224:227], v[220:223], v[8:11]
	v_mfma_f32_16x16x32_bf16 v[4:7], v[228:231], v[220:223], v[4:7]
	v_mfma_f32_16x16x32_bf16 v[0:3], v[232:235], v[220:223], v[0:3]
	v_mfma_f32_16x16x32_bf16 v[64:67], v[236:239], v[220:223], v[64:67]
	s_nop 7
	s_nop 7
	s_barrier
	ds_write_b64 v252, v[250:251]
	s_add_i32 s13, s13, s12
	s_ashr_i32 s4, s13, 6
	s_mul_i32 s4, s4, s11
	s_add_i32 s8, s4, s10
	s_add_i32 s14, s14, s15
	s_add_i32 s16, s16, s17
	s_cmp_lt_i32 s8, 8
	v_cvt_pk_bf16_f32 v8, v8, v9
	v_cvt_pk_bf16_f32 v9, v10, v11
	v_cvt_pk_bf16_f32 v4, v4, v5
	v_cvt_pk_bf16_f32 v5, v6, v7
	v_add_u32_e32 v6, 0x2800, v164
	ds_write2_b64 v6, v[8:9], v[4:5] offset0:160 offset1:164
	v_cvt_pk_bf16_f32 v4, v0, v1
	v_cvt_pk_bf16_f32 v5, v2, v3
	v_cvt_pk_bf16_f32 v92, v92, v93
	v_cvt_pk_bf16_f32 v93, v94, v95
	v_cvt_pk_bf16_f32 v88, v88, v89
	v_cvt_pk_bf16_f32 v89, v90, v91
	ds_write2_b64 v164, v[92:93], v[88:89] offset1:4
	v_cvt_pk_bf16_f32 v84, v84, v85
	v_cvt_pk_bf16_f32 v85, v86, v87
	v_cvt_pk_bf16_f32 v80, v80, v81
	v_cvt_pk_bf16_f32 v81, v82, v83
	v_cvt_pk_bf16_f32 v76, v76, v77
	v_cvt_pk_bf16_f32 v77, v78, v79
	v_cvt_pk_bf16_f32 v72, v72, v73
	v_cvt_pk_bf16_f32 v73, v74, v75
	v_add_u32_e32 v74, 0x800, v164
	v_cvt_pk_bf16_f32 v68, v68, v69
	v_cvt_pk_bf16_f32 v69, v70, v71
	ds_write2_b64 v164, v[84:85], v[80:81] offset0:8 offset1:12
	v_cvt_pk_bf16_f32 v60, v60, v61
	v_cvt_pk_bf16_f32 v61, v62, v63
	ds_write2_b64 v74, v[76:77], v[72:73] offset0:32 offset1:36
	v_cvt_pk_bf16_f32 v56, v56, v57
	v_cvt_pk_bf16_f32 v57, v58, v59
	ds_write2_b64 v74, v[68:69], v[60:61] offset0:40 offset1:44
	v_cvt_pk_bf16_f32 v52, v52, v53
	v_cvt_pk_bf16_f32 v53, v54, v55
	v_add_u32_e32 v54, 0x1000, v164
	v_cvt_pk_bf16_f32 v48, v48, v49
	v_cvt_pk_bf16_f32 v49, v50, v51
	ds_write2_b64 v54, v[56:57], v[52:53] offset0:64 offset1:68
	v_cvt_pk_bf16_f32 v44, v44, v45
	v_cvt_pk_bf16_f32 v45, v46, v47
	ds_write2_b64 v54, v[48:49], v[44:45] offset0:72 offset1:76
	v_cvt_pk_bf16_f32 v40, v40, v41
	v_cvt_pk_bf16_f32 v41, v42, v43
	v_cvt_pk_bf16_f32 v36, v36, v37
	v_cvt_pk_bf16_f32 v37, v38, v39
	v_add_u32_e32 v38, 0x1800, v164
	v_cvt_pk_bf16_f32 v32, v32, v33
	v_cvt_pk_bf16_f32 v33, v34, v35
	v_cvt_pk_bf16_f32 v28, v28, v29
	v_cvt_pk_bf16_f32 v29, v30, v31
	v_cvt_pk_bf16_f32 v24, v24, v25
	v_cvt_pk_bf16_f32 v25, v26, v27
	ds_write2_b64 v38, v[40:41], v[36:37] offset0:96 offset1:100
	v_cvt_pk_bf16_f32 v20, v20, v21
	v_cvt_pk_bf16_f32 v21, v22, v23
	v_add_u32_e32 v22, 0x2000, v164
	v_cvt_pk_bf16_f32 v16, v16, v17
	v_cvt_pk_bf16_f32 v17, v18, v19
	v_mov_b32_e32 v0, v64
	v_mov_b32_e32 v1, v65
	v_mov_b32_e32 v2, v66
	v_mov_b32_e32 v3, v67
	ds_write2_b64 v38, v[32:33], v[28:29] offset0:104 offset1:108
	s_nop 2
	v_cvt_pk_bf16_f32 v12, v12, v13
	v_cvt_pk_bf16_f32 v13, v14, v15
	ds_write2_b64 v22, v[24:25], v[20:21] offset0:128 offset1:132
	ds_write2_b64 v22, v[16:17], v[12:13] offset0:136 offset1:140
	v_cvt_pk_bf16_f32 v0, v0, v1
	v_cvt_pk_bf16_f32 v1, v2, v3
	ds_write2_b64 v6, v[4:5], v[0:1] offset0:168 offset1:172
	s_waitcnt lgkmcnt(0)
	v_or_b32_e32 v0, s33, v152
	v_add_u32_e32 v12, s6, v150
	v_lshlrev_b32_e32 v136, 1, v0
	ds_read_b128 v[0:3], v165
	v_or_b32_e32 v4, v12, v151
	v_ashrrev_i32_e32 v5, 31, v4
	v_lshl_add_u64 v[8:9], s[2:3], 0, v[136:137]
	v_lshlrev_b64 v[4:5], 11, v[4:5]
	v_lshl_add_u64 v[10:11], v[8:9], 0, v[4:5]
	ds_read_b128 v[4:7], v165 offset:1152
	s_waitcnt lgkmcnt(1)
	global_store_dwordx4 v[10:11], v[0:3], off
	s_nop 1
	v_or_b32_e32 v0, v12, v153
	v_ashrrev_i32_e32 v1, 31, v0
	v_lshlrev_b64 v[0:1], 11, v[0:1]
	v_lshl_add_u64 v[0:1], v[8:9], 0, v[0:1]
	s_waitcnt lgkmcnt(0)
	global_store_dwordx4 v[0:1], v[4:7], off
	ds_read_b128 v[0:3], v165 offset:2304
	s_nop 0
	v_or_b32_e32 v4, v12, v154
	v_ashrrev_i32_e32 v5, 31, v4
	v_lshlrev_b64 v[4:5], 11, v[4:5]
	v_lshl_add_u64 v[10:11], v[8:9], 0, v[4:5]
	ds_read_b128 v[4:7], v165 offset:3456
	s_waitcnt lgkmcnt(1)
	global_store_dwordx4 v[10:11], v[0:3], off
	s_nop 1
	v_or_b32_e32 v0, v12, v155
	v_ashrrev_i32_e32 v1, 31, v0
	v_lshlrev_b64 v[0:1], 11, v[0:1]
	v_lshl_add_u64 v[0:1], v[8:9], 0, v[0:1]
	s_waitcnt lgkmcnt(0)
	global_store_dwordx4 v[0:1], v[4:7], off
	ds_read_b128 v[0:3], v165 offset:4608
	s_nop 0
	v_add_u32_e32 v4, v12, v156
	v_ashrrev_i32_e32 v5, 31, v4
	v_lshlrev_b64 v[4:5], 11, v[4:5]
	v_lshl_add_u64 v[10:11], v[8:9], 0, v[4:5]
	ds_read_b128 v[4:7], v165 offset:5760
	s_waitcnt lgkmcnt(1)
	global_store_dwordx4 v[10:11], v[0:3], off
	s_nop 1
	v_add_u32_e32 v0, v12, v157
	v_ashrrev_i32_e32 v1, 31, v0
	v_lshlrev_b64 v[0:1], 11, v[0:1]
	v_lshl_add_u64 v[0:1], v[8:9], 0, v[0:1]
	s_waitcnt lgkmcnt(0)
	global_store_dwordx4 v[0:1], v[4:7], off
	ds_read_b128 v[0:3], v165 offset:6912
	s_nop 0
	v_add_u32_e32 v4, v12, v158
	v_ashrrev_i32_e32 v5, 31, v4
	v_lshlrev_b64 v[4:5], 11, v[4:5]
	v_lshl_add_u64 v[10:11], v[8:9], 0, v[4:5]
	ds_read_b128 v[4:7], v165 offset:8064
	s_waitcnt lgkmcnt(1)
	global_store_dwordx4 v[10:11], v[0:3], off
	s_nop 1
	v_add_u32_e32 v0, v12, v159
	v_ashrrev_i32_e32 v1, 31, v0
	v_lshlrev_b64 v[0:1], 11, v[0:1]
	v_lshl_add_u64 v[0:1], v[8:9], 0, v[0:1]
	s_waitcnt lgkmcnt(0)
	global_store_dwordx4 v[0:1], v[4:7], off
	ds_read_b128 v[0:3], v165 offset:9216
	s_nop 0
	v_add_u32_e32 v4, v12, v160
	v_ashrrev_i32_e32 v5, 31, v4
	v_lshlrev_b64 v[4:5], 11, v[4:5]
	v_lshl_add_u64 v[10:11], v[8:9], 0, v[4:5]
	ds_read_b128 v[4:7], v165 offset:10368
	s_waitcnt lgkmcnt(1)
	global_store_dwordx4 v[10:11], v[0:3], off
	s_nop 1
	v_add_u32_e32 v0, v12, v161
	v_ashrrev_i32_e32 v1, 31, v0
	v_lshlrev_b64 v[0:1], 11, v[0:1]
	v_lshl_add_u64 v[0:1], v[8:9], 0, v[0:1]
	s_waitcnt lgkmcnt(0)
	global_store_dwordx4 v[0:1], v[4:7], off
	ds_read_b128 v[0:3], v165 offset:11520
	s_nop 0
	v_add_u32_e32 v4, v12, v162
	v_ashrrev_i32_e32 v5, 31, v4
	v_lshlrev_b64 v[4:5], 11, v[4:5]
	v_lshl_add_u64 v[10:11], v[8:9], 0, v[4:5]
	ds_read_b128 v[4:7], v165 offset:12672
	s_waitcnt lgkmcnt(1)
	global_store_dwordx4 v[10:11], v[0:3], off
	s_nop 1
	v_add_u32_e32 v0, v12, v163
	v_ashrrev_i32_e32 v1, 31, v0
	v_lshlrev_b64 v[0:1], 11, v[0:1]
	v_lshl_add_u64 v[0:1], v[8:9], 0, v[0:1]
	s_waitcnt lgkmcnt(0)
	global_store_dwordx4 v[0:1], v[4:7], off
	s_cbranch_scc1 .LBB0_819

.LBB0_963:
	v_mov_b32_e32 v252, 0
	ds_read_b64 v[250:251], v252
	s_waitcnt lgkmcnt(0)
	s_cmp_lt_i32 s84, 0
	s_cbranch_scc1 .LBB0_979
	s_bitcmp0_b32 s84, 8
	s_cbranch_scc1 .LBB0_966
	s_sleep 15

.LBB0_970:
	s_ashr_i32 s4, s13, 6
	s_mul_i32 s8, s4, s11
	s_add_i32 s8, s8, s10
	s_cmp_gt_i32 s8, 47
	s_mov_b32 s34, 2
	s_cbranch_scc1 .LBB0_975
	s_mul_hi_i32 s9, s8, 0x2aaaaaab
	s_lshr_b32 s4, s9, 31
	s_add_i32 s9, s9, s4
	s_mul_i32 s4, s9, 6
	s_sub_i32 s4, s8, s4
	s_lshl_b32 s4, s4, 3
	s_bfe_u32 s33, s13, 0x30003
	s_or_b32 s6, s4, s33
	s_cmp_gt_i32 s6, 43
	s_mov_b32 s34, 4
	s_cbranch_scc1 .LBB0_975
	s_bfe_u32 s4, s14, 0x30005
	s_lshl_b32 s5, s13, 5
	s_mul_i32 s38, s4, 0xc0
	s_lshl_b32 s4, s9, 8
	s_and_b32 s5, s5, 0xe0
	s_or_b32 s4, s4, s5
	s_mul_i32 s4, s4, 6
	s_ashr_i32 s5, s4, 31
	s_lshl_b64 s[34:35], s[4:5], 11
	v_lshl_add_u64 v[0:1], v[136:137], 0, s[34:35]
	v_add_co_u32_e32 v2, vcc, s16, v0
	s_lshl_b32 s6, s6, 7
	s_nop 0
	v_addc_co_u32_e32 v3, vcc, 0, v1, vcc
	s_nop 0
	v_readfirstlane_b32 s98, v0
	v_readfirstlane_b32 s99, v1
	v_add_co_u32_e32 v2, vcc, s17, v0
	s_ashr_i32 s7, s6, 31
	s_nop 0
	v_addc_co_u32_e32 v3, vcc, 0, v1, vcc
	v_add_co_u32_e32 v4, vcc, s18, v0
	s_lshl_b64 s[36:37], s[6:7], 11
	s_nop 0
	v_addc_co_u32_e32 v5, vcc, 0, v1, vcc
	v_add_co_u32_e32 v2, vcc, s19, v0
	s_mul_i32 s5, s9, 0x600
	s_nop 0
	v_addc_co_u32_e32 v3, vcc, 0, v1, vcc
	v_add_co_u32_e32 v0, vcc, s20, v0
	s_add_i32 s34, s5, s38
	s_nop 0
	v_addc_co_u32_e32 v1, vcc, 0, v1, vcc
	v_lshl_add_u64 v[0:1], v[138:139], 0, s[36:37]
	v_add_co_u32_e32 v2, vcc, s16, v0
	s_lshl_b32 s5, s8, 3
	s_nop 0
	v_addc_co_u32_e32 v3, vcc, 0, v1, vcc
	s_nop 0
	v_readfirstlane_b32 s100, v0
	v_readfirstlane_b32 s101, v1
	v_add_co_u32_e32 v2, vcc, s17, v0
	s_or_b32 s5, s5, s33
	s_nop 0
	v_addc_co_u32_e32 v3, vcc, 0, v1, vcc
	v_add_co_u32_e32 v0, vcc, s18, v0
	s_mul_i32 s9, s9, 48
	s_nop 0
	v_addc_co_u32_e32 v1, vcc, 0, v1, vcc
	s_sub_i32 s5, s5, s9
	s_lshl_b32 s8, s5, 7
	s_ashr_i32 s35, s34, 31
	s_ashr_i32 s9, s8, 31
	s_lshl_b64 s[34:35], s[34:35], 11
	s_lshl_b64 s[8:9], s[8:9], 11
	v_mov_b32_e32 v60, 0
	v_lshl_add_u64 v[142:143], v[140:141], 0, s[34:35]
	v_lshl_add_u64 v[144:145], v[140:141], 0, s[8:9]
	s_mov_b64 s[8:9], 0
	v_mov_b32_e32 v61, v60
	v_mov_b32_e32 v62, v60
	v_mov_b32_e32 v63, v60
	v_mov_b32_e32 v0, v60
	v_mov_b32_e32 v1, v60
	v_mov_b32_e32 v2, v60
	v_mov_b32_e32 v3, v60
	v_mov_b32_e32 v4, v60
	v_mov_b32_e32 v5, v60
	v_mov_b32_e32 v6, v60
	v_mov_b32_e32 v7, v60
	v_mov_b32_e32 v8, v60
	v_mov_b32_e32 v9, v60
	v_mov_b32_e32 v10, v60
	v_mov_b32_e32 v11, v60
	v_mov_b32_e32 v12, v60
	v_mov_b32_e32 v13, v60
	v_mov_b32_e32 v14, v60
	v_mov_b32_e32 v15, v60
	v_mov_b32_e32 v16, v60
	v_mov_b32_e32 v17, v60
	v_mov_b32_e32 v18, v60
	v_mov_b32_e32 v19, v60
	v_mov_b32_e32 v20, v60
	v_mov_b32_e32 v21, v60
	v_mov_b32_e32 v22, v60
	v_mov_b32_e32 v23, v60
	v_mov_b32_e32 v24, v60
	v_mov_b32_e32 v25, v60
	v_mov_b32_e32 v26, v60
	v_mov_b32_e32 v27, v60
	v_mov_b32_e32 v28, v60
	v_mov_b32_e32 v29, v60
	v_mov_b32_e32 v30, v60
	v_mov_b32_e32 v31, v60
	v_mov_b32_e32 v32, v60
	v_mov_b32_e32 v33, v60
	v_mov_b32_e32 v34, v60
	v_mov_b32_e32 v35, v60
	s_waitcnt vmcnt(22)
	v_mov_b32_e32 v36, v60
	v_mov_b32_e32 v37, v60
	v_mov_b32_e32 v38, v60
	v_mov_b32_e32 v39, v60
	s_waitcnt vmcnt(21)
	v_mov_b32_e32 v40, v60
	v_mov_b32_e32 v41, v60
	v_mov_b32_e32 v42, v60
	v_mov_b32_e32 v43, v60
	s_waitcnt vmcnt(20)
	v_mov_b32_e32 v44, v60
	v_mov_b32_e32 v45, v60
	v_mov_b32_e32 v46, v60
	v_mov_b32_e32 v47, v60
	s_waitcnt vmcnt(19)
	v_mov_b32_e32 v48, v60
	v_mov_b32_e32 v49, v60
	v_mov_b32_e32 v50, v60
	v_mov_b32_e32 v51, v60
	s_waitcnt vmcnt(18)
	v_mov_b32_e32 v52, v60
	v_mov_b32_e32 v53, v60
	v_mov_b32_e32 v54, v60
	v_mov_b32_e32 v55, v60
	v_mov_b32_e32 v56, v60
	v_mov_b32_e32 v57, v60
	v_mov_b32_e32 v58, v60
	v_mov_b32_e32 v59, v60
	v_mov_b32_e32 v64, v60
	v_mov_b32_e32 v65, v60
	v_mov_b32_e32 v66, v60
	v_mov_b32_e32 v67, v60
	v_mov_b32_e32 v68, v60
	v_mov_b32_e32 v69, v60
	v_mov_b32_e32 v70, v60
	v_mov_b32_e32 v71, v60
	v_mov_b32_e32 v72, v60
	v_mov_b32_e32 v73, v60
	v_mov_b32_e32 v74, v60
	v_mov_b32_e32 v75, v60
	v_mov_b32_e32 v76, v60
	v_mov_b32_e32 v77, v60
	v_mov_b32_e32 v78, v60
	v_mov_b32_e32 v79, v60
	v_mov_b32_e32 v80, v60
	v_mov_b32_e32 v81, v60
	v_mov_b32_e32 v82, v60
	v_mov_b32_e32 v83, v60
	v_mov_b32_e32 v84, v60
	v_mov_b32_e32 v85, v60
	v_mov_b32_e32 v86, v60
	v_mov_b32_e32 v87, v60
	v_mov_b32_e32 v88, v60
	v_mov_b32_e32 v89, v60
	v_mov_b32_e32 v90, v60
	v_mov_b32_e32 v91, v60
	v_mov_b32_e32 v92, v60
	v_mov_b32_e32 v93, v60
	v_mov_b32_e32 v94, v60
	v_mov_b32_e32 v95, v60
	v_and_b32_e32 v197, 63, v196
	v_lshrrev_b32_e32 v198, 3, v197
	v_and_b32_e32 v199, 7, v197
	v_xor_b32_e32 v199, v199, v198
	v_lshlrev_b32_e32 v199, 4, v199
	v_mul_u32_u24_e32 v198, 2048, v198
	v_add_u32_e32 v240, v198, v199
	v_add_u32_e32 v241, 65536, v240
	v_add_u32_e32 v242, 131072, v240
	v_add_u32_e32 v243, 196608, v240
	v_add_u32_e32 v244, 262144, v240
	v_add_u32_e32 v245, 327680, v240
	v_lshrrev_b32_e32 v198, 6, v196
	v_lshrrev_b32_e32 v199, 1, v198
	v_and_b32_e32 v198, 1, v198
	v_and_b32_e32 v190, 15, v197
	v_lshrrev_b32_e32 v191, 4, v197
	v_and_b32_e32 v192, 7, v190
	v_xor_b32_e32 v191, v191, v192
	v_lshlrev_b32_e32 v191, 4, v191
	v_mul_u32_u24_e32 v199, 0x60, v199
	v_add_u32_e32 v199, v199, v190
	v_lshl_add_u32 v246, v199, 7, v191
	v_xor_b32_e32 v247, 64, v246
	v_lshlrev_b32_e32 v198, 6, v198
	v_add_u32_e32 v198, v198, v190
	v_lshl_add_u32 v248, v198, 7, v191
	v_add_u32_e32 v248, 0x6000, v248
	v_xor_b32_e32 v249, 64, v248
	v_lshrrev_b32_e32 v198, 6, v196
	v_lshlrev_b32_e32 v198, 10, v198
	s_nop 0
	v_readfirstlane_b32 s8, v198
	s_mov_b32 s9, 7
	s_waitcnt lgkmcnt(0)
	s_barrier
	s_add_u32 m0, s8, 0
	s_nop 0
	global_load_lds_dwordx4 v240, s[98:99]
	s_add_u32 m0, s8, 4096
	s_nop 0
	global_load_lds_dwordx4 v241, s[98:99]
	s_add_u32 m0, s8, 8192
	s_nop 0
	global_load_lds_dwordx4 v242, s[98:99]
	s_add_u32 m0, s8, 12288
	s_nop 0
	global_load_lds_dwordx4 v243, s[98:99]
	s_add_u32 m0, s8, 16384
	s_nop 0
	global_load_lds_dwordx4 v244, s[98:99]
	s_add_u32 m0, s8, 20480
	s_nop 0
	global_load_lds_dwordx4 v245, s[98:99]
	s_add_u32 m0, s8, 24576
	s_nop 0
	global_load_lds_dwordx4 v240, s[100:101]
	s_add_u32 m0, s8, 28672
	s_nop 0
	global_load_lds_dwordx4 v241, s[100:101]
	s_add_u32 m0, s8, 32768
	s_nop 0
	global_load_lds_dwordx4 v242, s[100:101]
	s_add_u32 m0, s8, 36864
	s_nop 0
	global_load_lds_dwordx4 v243, s[100:101]
	s_add_u32 s98, s98, 0x80
	s_addc_u32 s99, s99, 0
	s_add_u32 s100, s100, 0x80
	s_addc_u32 s101, s101, 0
	s_waitcnt vmcnt(0)
	s_barrier
	ds_read_b128 v[120:123], v248 offset:0
	ds_read_b128 v[124:127], v248 offset:2048
	ds_read_b128 v[128:131], v248 offset:4096
	ds_read_b128 v[132:135], v248 offset:6144
	ds_read_b128 v[96:99], v246 offset:0
	ds_read_b128 v[100:103], v246 offset:2048
	ds_read_b128 v[104:107], v246 offset:4096
	ds_read_b128 v[108:111], v246 offset:6144
	ds_read_b128 v[112:115], v246 offset:8192
	ds_read_b128 v[116:119], v246 offset:10240
	s_add_u32 m0, s8, 40960
	s_nop 0
	global_load_lds_dwordx4 v240, s[98:99]
	s_add_u32 m0, s8, 45056
	s_nop 0
	global_load_lds_dwordx4 v241, s[98:99]
	s_add_u32 m0, s8, 49152
	s_nop 0
	global_load_lds_dwordx4 v242, s[98:99]
	s_add_u32 m0, s8, 53248
	s_nop 0
	global_load_lds_dwordx4 v243, s[98:99]
	s_add_u32 m0, s8, 57344
	s_nop 0
	global_load_lds_dwordx4 v244, s[98:99]
	s_add_u32 m0, s8, 61440
	s_nop 0
	global_load_lds_dwordx4 v245, s[98:99]
	s_add_u32 m0, s8, 65536
	s_nop 0
	global_load_lds_dwordx4 v240, s[100:101]
	s_add_u32 m0, s8, 69632
	s_nop 0
	global_load_lds_dwordx4 v241, s[100:101]
	s_add_u32 m0, s8, 73728
	s_nop 0
	global_load_lds_dwordx4 v242, s[100:101]
	s_add_u32 m0, s8, 77824
	s_nop 0
	global_load_lds_dwordx4 v243, s[100:101]
	s_add_u32 s98, s98, 0x80
	s_addc_u32 s99, s99, 0
	s_add_u32 s100, s100, 0x80
	s_addc_u32 s101, s101, 0
	s_waitcnt lgkmcnt(0)
	v_mfma_f32_16x16x32_bf16 v[92:95], v[120:123], v[96:99], v[92:95]
	v_mfma_f32_16x16x32_bf16 v[88:91], v[124:127], v[96:99], v[88:91]
	ds_read_b128 v[224:227], v249 offset:0
	v_mfma_f32_16x16x32_bf16 v[84:87], v[128:131], v[96:99], v[84:87]
	v_mfma_f32_16x16x32_bf16 v[80:83], v[132:135], v[96:99], v[80:83]
	ds_read_b128 v[228:231], v249 offset:2048
	v_mfma_f32_16x16x32_bf16 v[76:79], v[120:123], v[100:103], v[76:79]
	v_mfma_f32_16x16x32_bf16 v[72:75], v[124:127], v[100:103], v[72:75]
	ds_read_b128 v[232:235], v249 offset:4096
	v_mfma_f32_16x16x32_bf16 v[68:71], v[128:131], v[100:103], v[68:71]
	v_mfma_f32_16x16x32_bf16 v[64:67], v[132:135], v[100:103], v[64:67]
	ds_read_b128 v[236:239], v249 offset:6144
	v_mfma_f32_16x16x32_bf16 v[56:59], v[120:123], v[104:107], v[56:59]
	v_mfma_f32_16x16x32_bf16 v[52:55], v[124:127], v[104:107], v[52:55]
	ds_read_b128 v[200:203], v247 offset:0
	v_mfma_f32_16x16x32_bf16 v[48:51], v[128:131], v[104:107], v[48:51]
	v_mfma_f32_16x16x32_bf16 v[44:47], v[132:135], v[104:107], v[44:47]
	ds_read_b128 v[204:207], v247 offset:2048
	v_mfma_f32_16x16x32_bf16 v[40:43], v[120:123], v[108:111], v[40:43]
	v_mfma_f32_16x16x32_bf16 v[36:39], v[124:127], v[108:111], v[36:39]
	ds_read_b128 v[208:211], v247 offset:4096
	v_mfma_f32_16x16x32_bf16 v[32:35], v[128:131], v[108:111], v[32:35]
	v_mfma_f32_16x16x32_bf16 v[28:31], v[132:135], v[108:111], v[28:31]
	ds_read_b128 v[212:215], v247 offset:6144
	v_mfma_f32_16x16x32_bf16 v[24:27], v[120:123], v[112:115], v[24:27]
	v_mfma_f32_16x16x32_bf16 v[20:23], v[124:127], v[112:115], v[20:23]
	ds_read_b128 v[216:219], v247 offset:8192
	v_mfma_f32_16x16x32_bf16 v[16:19], v[128:131], v[112:115], v[16:19]
	v_mfma_f32_16x16x32_bf16 v[12:15], v[132:135], v[112:115], v[12:15]
	ds_read_b128 v[220:223], v247 offset:10240
	v_mfma_f32_16x16x32_bf16 v[8:11], v[120:123], v[116:119], v[8:11]
	v_mfma_f32_16x16x32_bf16 v[4:7], v[124:127], v[116:119], v[4:7]
	v_mfma_f32_16x16x32_bf16 v[0:3], v[128:131], v[116:119], v[0:3]
	v_mfma_f32_16x16x32_bf16 v[60:63], v[132:135], v[116:119], v[60:63]
.Lg6p7_loop:
	s_waitcnt vmcnt(0) lgkmcnt(0)
	s_barrier
	ds_read_b128 v[120:123], v248 offset:40960
	ds_read_b128 v[124:127], v248 offset:43008
	ds_read_b128 v[128:131], v248 offset:45056
	ds_read_b128 v[132:135], v248 offset:47104
	ds_read_b128 v[96:99], v246 offset:40960
	ds_read_b128 v[100:103], v246 offset:43008
	ds_read_b128 v[104:107], v246 offset:45056
	ds_read_b128 v[108:111], v246 offset:47104
	ds_read_b128 v[112:115], v246 offset:49152
	ds_read_b128 v[116:119], v246 offset:51200
	s_add_u32 m0, s8, 0
	v_mfma_f32_16x16x32_bf16 v[92:95], v[224:227], v[200:203], v[92:95]
	global_load_lds_dwordx4 v240, s[98:99]
	v_mfma_f32_16x16x32_bf16 v[88:91], v[228:231], v[200:203], v[88:91]
	s_add_u32 m0, s8, 4096
	v_mfma_f32_16x16x32_bf16 v[84:87], v[232:235], v[200:203], v[84:87]
	global_load_lds_dwordx4 v241, s[98:99]
	v_mfma_f32_16x16x32_bf16 v[80:83], v[236:239], v[200:203], v[80:83]
	s_add_u32 m0, s8, 8192
	v_mfma_f32_16x16x32_bf16 v[76:79], v[224:227], v[204:207], v[76:79]
	global_load_lds_dwordx4 v242, s[98:99]
	v_mfma_f32_16x16x32_bf16 v[72:75], v[228:231], v[204:207], v[72:75]
	s_add_u32 m0, s8, 12288
	v_mfma_f32_16x16x32_bf16 v[68:71], v[232:235], v[204:207], v[68:71]
	global_load_lds_dwordx4 v243, s[98:99]
	v_mfma_f32_16x16x32_bf16 v[64:67], v[236:239], v[204:207], v[64:67]
	s_add_u32 m0, s8, 16384
	v_mfma_f32_16x16x32_bf16 v[56:59], v[224:227], v[208:211], v[56:59]
	global_load_lds_dwordx4 v244, s[98:99]
	v_mfma_f32_16x16x32_bf16 v[52:55], v[228:231], v[208:211], v[52:55]
	s_add_u32 m0, s8, 20480
	v_mfma_f32_16x16x32_bf16 v[48:51], v[232:235], v[208:211], v[48:51]
	global_load_lds_dwordx4 v245, s[98:99]
	v_mfma_f32_16x16x32_bf16 v[44:47], v[236:239], v[208:211], v[44:47]
	s_add_u32 m0, s8, 24576
	v_mfma_f32_16x16x32_bf16 v[40:43], v[224:227], v[212:215], v[40:43]
	global_load_lds_dwordx4 v240, s[100:101]
	v_mfma_f32_16x16x32_bf16 v[36:39], v[228:231], v[212:215], v[36:39]
	s_add_u32 m0, s8, 28672
	v_mfma_f32_16x16x32_bf16 v[32:35], v[232:235], v[212:215], v[32:35]
	global_load_lds_dwordx4 v241, s[100:101]
	v_mfma_f32_16x16x32_bf16 v[28:31], v[236:239], v[212:215], v[28:31]
	s_add_u32 m0, s8, 32768
	v_mfma_f32_16x16x32_bf16 v[24:27], v[224:227], v[216:219], v[24:27]
	global_load_lds_dwordx4 v242, s[100:101]
	v_mfma_f32_16x16x32_bf16 v[20:23], v[228:231], v[216:219], v[20:23]
	s_add_u32 m0, s8, 36864
	v_mfma_f32_16x16x32_bf16 v[16:19], v[232:235], v[216:219], v[16:19]
	global_load_lds_dwordx4 v243, s[100:101]
	v_mfma_f32_16x16x32_bf16 v[12:15], v[236:239], v[216:219], v[12:15]
	v_mfma_f32_16x16x32_bf16 v[8:11], v[224:227], v[220:223], v[8:11]
	v_mfma_f32_16x16x32_bf16 v[4:7], v[228:231], v[220:223], v[4:7]
	v_mfma_f32_16x16x32_bf16 v[0:3], v[232:235], v[220:223], v[0:3]
	v_mfma_f32_16x16x32_bf16 v[60:63], v[236:239], v[220:223], v[60:63]
	s_add_u32 s98, s98, 0x80
	s_addc_u32 s99, s99, 0
	s_add_u32 s100, s100, 0x80
	s_addc_u32 s101, s101, 0
	s_waitcnt lgkmcnt(0)
	v_mfma_f32_16x16x32_bf16 v[92:95], v[120:123], v[96:99], v[92:95]
	v_mfma_f32_16x16x32_bf16 v[88:91], v[124:127], v[96:99], v[88:91]
	ds_read_b128 v[224:227], v249 offset:40960
	v_mfma_f32_16x16x32_bf16 v[84:87], v[128:131], v[96:99], v[84:87]
	v_mfma_f32_16x16x32_bf16 v[80:83], v[132:135], v[96:99], v[80:83]
	ds_read_b128 v[228:231], v249 offset:43008
	v_mfma_f32_16x16x32_bf16 v[76:79], v[120:123], v[100:103], v[76:79]
	v_mfma_f32_16x16x32_bf16 v[72:75], v[124:127], v[100:103], v[72:75]
	ds_read_b128 v[232:235], v249 offset:45056
	v_mfma_f32_16x16x32_bf16 v[68:71], v[128:131], v[100:103], v[68:71]
	v_mfma_f32_16x16x32_bf16 v[64:67], v[132:135], v[100:103], v[64:67]
	ds_read_b128 v[236:239], v249 offset:47104
	v_mfma_f32_16x16x32_bf16 v[56:59], v[120:123], v[104:107], v[56:59]
	v_mfma_f32_16x16x32_bf16 v[52:55], v[124:127], v[104:107], v[52:55]
	ds_read_b128 v[200:203], v247 offset:40960
	v_mfma_f32_16x16x32_bf16 v[48:51], v[128:131], v[104:107], v[48:51]
	v_mfma_f32_16x16x32_bf16 v[44:47], v[132:135], v[104:107], v[44:47]
	ds_read_b128 v[204:207], v247 offset:43008
	v_mfma_f32_16x16x32_bf16 v[40:43], v[120:123], v[108:111], v[40:43]
	v_mfma_f32_16x16x32_bf16 v[36:39], v[124:127], v[108:111], v[36:39]
	ds_read_b128 v[208:211], v247 offset:45056
	v_mfma_f32_16x16x32_bf16 v[32:35], v[128:131], v[108:111], v[32:35]
	v_mfma_f32_16x16x32_bf16 v[28:31], v[132:135], v[108:111], v[28:31]
	ds_read_b128 v[212:215], v247 offset:47104
	v_mfma_f32_16x16x32_bf16 v[24:27], v[120:123], v[112:115], v[24:27]
	v_mfma_f32_16x16x32_bf16 v[20:23], v[124:127], v[112:115], v[20:23]
	ds_read_b128 v[216:219], v247 offset:49152
	v_mfma_f32_16x16x32_bf16 v[16:19], v[128:131], v[112:115], v[16:19]
	v_mfma_f32_16x16x32_bf16 v[12:15], v[132:135], v[112:115], v[12:15]
	ds_read_b128 v[220:223], v247 offset:51200
	v_mfma_f32_16x16x32_bf16 v[8:11], v[120:123], v[116:119], v[8:11]
	v_mfma_f32_16x16x32_bf16 v[4:7], v[124:127], v[116:119], v[4:7]
	v_mfma_f32_16x16x32_bf16 v[0:3], v[128:131], v[116:119], v[0:3]
	v_mfma_f32_16x16x32_bf16 v[60:63], v[132:135], v[116:119], v[60:63]
	s_waitcnt vmcnt(0) lgkmcnt(0)
	s_barrier
	ds_read_b128 v[120:123], v248 offset:0
	ds_read_b128 v[124:127], v248 offset:2048
	ds_read_b128 v[128:131], v248 offset:4096
	ds_read_b128 v[132:135], v248 offset:6144
	ds_read_b128 v[96:99], v246 offset:0
	ds_read_b128 v[100:103], v246 offset:2048
	ds_read_b128 v[104:107], v246 offset:4096
	ds_read_b128 v[108:111], v246 offset:6144
	ds_read_b128 v[112:115], v246 offset:8192
	ds_read_b128 v[116:119], v246 offset:10240
	s_add_u32 m0, s8, 40960
	v_mfma_f32_16x16x32_bf16 v[92:95], v[224:227], v[200:203], v[92:95]
	global_load_lds_dwordx4 v240, s[98:99]
	v_mfma_f32_16x16x32_bf16 v[88:91], v[228:231], v[200:203], v[88:91]
	s_add_u32 m0, s8, 45056
	v_mfma_f32_16x16x32_bf16 v[84:87], v[232:235], v[200:203], v[84:87]
	global_load_lds_dwordx4 v241, s[98:99]
	v_mfma_f32_16x16x32_bf16 v[80:83], v[236:239], v[200:203], v[80:83]
	s_add_u32 m0, s8, 49152
	v_mfma_f32_16x16x32_bf16 v[76:79], v[224:227], v[204:207], v[76:79]
	global_load_lds_dwordx4 v242, s[98:99]
	v_mfma_f32_16x16x32_bf16 v[72:75], v[228:231], v[204:207], v[72:75]
	s_add_u32 m0, s8, 53248
	v_mfma_f32_16x16x32_bf16 v[68:71], v[232:235], v[204:207], v[68:71]
	global_load_lds_dwordx4 v243, s[98:99]
	v_mfma_f32_16x16x32_bf16 v[64:67], v[236:239], v[204:207], v[64:67]
	s_add_u32 m0, s8, 57344
	v_mfma_f32_16x16x32_bf16 v[56:59], v[224:227], v[208:211], v[56:59]
	global_load_lds_dwordx4 v244, s[98:99]
	v_mfma_f32_16x16x32_bf16 v[52:55], v[228:231], v[208:211], v[52:55]
	s_add_u32 m0, s8, 61440
	v_mfma_f32_16x16x32_bf16 v[48:51], v[232:235], v[208:211], v[48:51]
	global_load_lds_dwordx4 v245, s[98:99]
	v_mfma_f32_16x16x32_bf16 v[44:47], v[236:239], v[208:211], v[44:47]
	s_add_u32 m0, s8, 65536
	v_mfma_f32_16x16x32_bf16 v[40:43], v[224:227], v[212:215], v[40:43]
	global_load_lds_dwordx4 v240, s[100:101]
	v_mfma_f32_16x16x32_bf16 v[36:39], v[228:231], v[212:215], v[36:39]
	s_add_u32 m0, s8, 69632
	v_mfma_f32_16x16x32_bf16 v[32:35], v[232:235], v[212:215], v[32:35]
	global_load_lds_dwordx4 v241, s[100:101]
	v_mfma_f32_16x16x32_bf16 v[28:31], v[236:239], v[212:215], v[28:31]
	s_add_u32 m0, s8, 73728
	v_mfma_f32_16x16x32_bf16 v[24:27], v[224:227], v[216:219], v[24:27]
	global_load_lds_dwordx4 v242, s[100:101]
	v_mfma_f32_16x16x32_bf16 v[20:23], v[228:231], v[216:219], v[20:23]
	s_add_u32 m0, s8, 77824
	v_mfma_f32_16x16x32_bf16 v[16:19], v[232:235], v[216:219], v[16:19]
	global_load_lds_dwordx4 v243, s[100:101]
	v_mfma_f32_16x16x32_bf16 v[12:15], v[236:239], v[216:219], v[12:15]
	v_mfma_f32_16x16x32_bf16 v[8:11], v[224:227], v[220:223], v[8:11]
	v_mfma_f32_16x16x32_bf16 v[4:7], v[228:231], v[220:223], v[4:7]
	v_mfma_f32_16x16x32_bf16 v[0:3], v[232:235], v[220:223], v[0:3]
	v_mfma_f32_16x16x32_bf16 v[60:63], v[236:239], v[220:223], v[60:63]
	s_add_u32 s98, s98, 0x80
	s_addc_u32 s99, s99, 0
	s_add_u32 s100, s100, 0x80
	s_addc_u32 s101, s101, 0
	s_waitcnt lgkmcnt(0)
	v_mfma_f32_16x16x32_bf16 v[92:95], v[120:123], v[96:99], v[92:95]
	v_mfma_f32_16x16x32_bf16 v[88:91], v[124:127], v[96:99], v[88:91]
	ds_read_b128 v[224:227], v249 offset:0
	v_mfma_f32_16x16x32_bf16 v[84:87], v[128:131], v[96:99], v[84:87]
	v_mfma_f32_16x16x32_bf16 v[80:83], v[132:135], v[96:99], v[80:83]
	ds_read_b128 v[228:231], v249 offset:2048
	v_mfma_f32_16x16x32_bf16 v[76:79], v[120:123], v[100:103], v[76:79]
	v_mfma_f32_16x16x32_bf16 v[72:75], v[124:127], v[100:103], v[72:75]
	ds_read_b128 v[232:235], v249 offset:4096
	v_mfma_f32_16x16x32_bf16 v[68:71], v[128:131], v[100:103], v[68:71]
	v_mfma_f32_16x16x32_bf16 v[64:67], v[132:135], v[100:103], v[64:67]
	ds_read_b128 v[236:239], v249 offset:6144
	v_mfma_f32_16x16x32_bf16 v[56:59], v[120:123], v[104:107], v[56:59]
	v_mfma_f32_16x16x32_bf16 v[52:55], v[124:127], v[104:107], v[52:55]
	ds_read_b128 v[200:203], v247 offset:0
	v_mfma_f32_16x16x32_bf16 v[48:51], v[128:131], v[104:107], v[48:51]
	v_mfma_f32_16x16x32_bf16 v[44:47], v[132:135], v[104:107], v[44:47]
	ds_read_b128 v[204:207], v247 offset:2048
	v_mfma_f32_16x16x32_bf16 v[40:43], v[120:123], v[108:111], v[40:43]
	v_mfma_f32_16x16x32_bf16 v[36:39], v[124:127], v[108:111], v[36:39]
	ds_read_b128 v[208:211], v247 offset:4096
	v_mfma_f32_16x16x32_bf16 v[32:35], v[128:131], v[108:111], v[32:35]
	v_mfma_f32_16x16x32_bf16 v[28:31], v[132:135], v[108:111], v[28:31]
	ds_read_b128 v[212:215], v247 offset:6144
	v_mfma_f32_16x16x32_bf16 v[24:27], v[120:123], v[112:115], v[24:27]
	v_mfma_f32_16x16x32_bf16 v[20:23], v[124:127], v[112:115], v[20:23]
	ds_read_b128 v[216:219], v247 offset:8192
	v_mfma_f32_16x16x32_bf16 v[16:19], v[128:131], v[112:115], v[16:19]
	v_mfma_f32_16x16x32_bf16 v[12:15], v[132:135], v[112:115], v[12:15]
	ds_read_b128 v[220:223], v247 offset:10240
	v_mfma_f32_16x16x32_bf16 v[8:11], v[120:123], v[116:119], v[8:11]
	v_mfma_f32_16x16x32_bf16 v[4:7], v[124:127], v[116:119], v[4:7]
	v_mfma_f32_16x16x32_bf16 v[0:3], v[128:131], v[116:119], v[0:3]
	v_mfma_f32_16x16x32_bf16 v[60:63], v[132:135], v[116:119], v[60:63]
	s_sub_u32 s9, s9, 1
	s_cmp_lg_u32 s9, 0
	s_cbranch_scc1 .Lg6p7_loop
	s_waitcnt vmcnt(0) lgkmcnt(0)
	s_barrier
	ds_read_b128 v[120:123], v248 offset:40960
	ds_read_b128 v[124:127], v248 offset:43008
	ds_read_b128 v[128:131], v248 offset:45056
	ds_read_b128 v[132:135], v248 offset:47104
	ds_read_b128 v[96:99], v246 offset:40960
	ds_read_b128 v[100:103], v246 offset:43008
	ds_read_b128 v[104:107], v246 offset:45056
	ds_read_b128 v[108:111], v246 offset:47104
	ds_read_b128 v[112:115], v246 offset:49152
	ds_read_b128 v[116:119], v246 offset:51200
	v_mfma_f32_16x16x32_bf16 v[92:95], v[224:227], v[200:203], v[92:95]
	v_mfma_f32_16x16x32_bf16 v[88:91], v[228:231], v[200:203], v[88:91]
	v_mfma_f32_16x16x32_bf16 v[84:87], v[232:235], v[200:203], v[84:87]
	v_mfma_f32_16x16x32_bf16 v[80:83], v[236:239], v[200:203], v[80:83]
	v_mfma_f32_16x16x32_bf16 v[76:79], v[224:227], v[204:207], v[76:79]
	v_mfma_f32_16x16x32_bf16 v[72:75], v[228:231], v[204:207], v[72:75]
	v_mfma_f32_16x16x32_bf16 v[68:71], v[232:235], v[204:207], v[68:71]
	v_mfma_f32_16x16x32_bf16 v[64:67], v[236:239], v[204:207], v[64:67]
	v_mfma_f32_16x16x32_bf16 v[56:59], v[224:227], v[208:211], v[56:59]
	v_mfma_f32_16x16x32_bf16 v[52:55], v[228:231], v[208:211], v[52:55]
	v_mfma_f32_16x16x32_bf16 v[48:51], v[232:235], v[208:211], v[48:51]
	v_mfma_f32_16x16x32_bf16 v[44:47], v[236:239], v[208:211], v[44:47]
	v_mfma_f32_16x16x32_bf16 v[40:43], v[224:227], v[212:215], v[40:43]
	v_mfma_f32_16x16x32_bf16 v[36:39], v[228:231], v[212:215], v[36:39]
	v_mfma_f32_16x16x32_bf16 v[32:35], v[232:235], v[212:215], v[32:35]
	v_mfma_f32_16x16x32_bf16 v[28:31], v[236:239], v[212:215], v[28:31]
	v_mfma_f32_16x16x32_bf16 v[24:27], v[224:227], v[216:219], v[24:27]
	v_mfma_f32_16x16x32_bf16 v[20:23], v[228:231], v[216:219], v[20:23]
	v_mfma_f32_16x16x32_bf16 v[16:19], v[232:235], v[216:219], v[16:19]
	v_mfma_f32_16x16x32_bf16 v[12:15], v[236:239], v[216:219], v[12:15]
	v_mfma_f32_16x16x32_bf16 v[8:11], v[224:227], v[220:223], v[8:11]
	v_mfma_f32_16x16x32_bf16 v[4:7], v[228:231], v[220:223], v[4:7]
	v_mfma_f32_16x16x32_bf16 v[0:3], v[232:235], v[220:223], v[0:3]
	v_mfma_f32_16x16x32_bf16 v[60:63], v[236:239], v[220:223], v[60:63]
	s_waitcnt lgkmcnt(0)
	v_mfma_f32_16x16x32_bf16 v[92:95], v[120:123], v[96:99], v[92:95]
	v_mfma_f32_16x16x32_bf16 v[88:91], v[124:127], v[96:99], v[88:91]
	ds_read_b128 v[224:227], v249 offset:40960
	v_mfma_f32_16x16x32_bf16 v[84:87], v[128:131], v[96:99], v[84:87]
	v_mfma_f32_16x16x32_bf16 v[80:83], v[132:135], v[96:99], v[80:83]
	ds_read_b128 v[228:231], v249 offset:43008
	v_mfma_f32_16x16x32_bf16 v[76:79], v[120:123], v[100:103], v[76:79]
	v_mfma_f32_16x16x32_bf16 v[72:75], v[124:127], v[100:103], v[72:75]
	ds_read_b128 v[232:235], v249 offset:45056
	v_mfma_f32_16x16x32_bf16 v[68:71], v[128:131], v[100:103], v[68:71]
	v_mfma_f32_16x16x32_bf16 v[64:67], v[132:135], v[100:103], v[64:67]
	ds_read_b128 v[236:239], v249 offset:47104
	v_mfma_f32_16x16x32_bf16 v[56:59], v[120:123], v[104:107], v[56:59]
	v_mfma_f32_16x16x32_bf16 v[52:55], v[124:127], v[104:107], v[52:55]
	ds_read_b128 v[200:203], v247 offset:40960
	v_mfma_f32_16x16x32_bf16 v[48:51], v[128:131], v[104:107], v[48:51]
	v_mfma_f32_16x16x32_bf16 v[44:47], v[132:135], v[104:107], v[44:47]
	ds_read_b128 v[204:207], v247 offset:43008
	v_mfma_f32_16x16x32_bf16 v[40:43], v[120:123], v[108:111], v[40:43]
	v_mfma_f32_16x16x32_bf16 v[36:39], v[124:127], v[108:111], v[36:39]
	ds_read_b128 v[208:211], v247 offset:45056
	v_mfma_f32_16x16x32_bf16 v[32:35], v[128:131], v[108:111], v[32:35]
	v_mfma_f32_16x16x32_bf16 v[28:31], v[132:135], v[108:111], v[28:31]
	ds_read_b128 v[212:215], v247 offset:47104
	v_mfma_f32_16x16x32_bf16 v[24:27], v[120:123], v[112:115], v[24:27]
	v_mfma_f32_16x16x32_bf16 v[20:23], v[124:127], v[112:115], v[20:23]
	ds_read_b128 v[216:219], v247 offset:49152
	v_mfma_f32_16x16x32_bf16 v[16:19], v[128:131], v[112:115], v[16:19]
	v_mfma_f32_16x16x32_bf16 v[12:15], v[132:135], v[112:115], v[12:15]
	ds_read_b128 v[220:223], v247 offset:51200
	v_mfma_f32_16x16x32_bf16 v[8:11], v[120:123], v[116:119], v[8:11]
	v_mfma_f32_16x16x32_bf16 v[4:7], v[124:127], v[116:119], v[4:7]
	v_mfma_f32_16x16x32_bf16 v[0:3], v[128:131], v[116:119], v[0:3]
	v_mfma_f32_16x16x32_bf16 v[60:63], v[132:135], v[116:119], v[60:63]
	s_waitcnt lgkmcnt(0)
	v_mfma_f32_16x16x32_bf16 v[92:95], v[224:227], v[200:203], v[92:95]
	v_mfma_f32_16x16x32_bf16 v[88:91], v[228:231], v[200:203], v[88:91]
	v_mfma_f32_16x16x32_bf16 v[84:87], v[232:235], v[200:203], v[84:87]
	v_mfma_f32_16x16x32_bf16 v[80:83], v[236:239], v[200:203], v[80:83]
	v_mfma_f32_16x16x32_bf16 v[76:79], v[224:227], v[204:207], v[76:79]
	v_mfma_f32_16x16x32_bf16 v[72:75], v[228:231], v[204:207], v[72:75]
	v_mfma_f32_16x16x32_bf16 v[68:71], v[232:235], v[204:207], v[68:71]
	v_mfma_f32_16x16x32_bf16 v[64:67], v[236:239], v[204:207], v[64:67]
	v_mfma_f32_16x16x32_bf16 v[56:59], v[224:227], v[208:211], v[56:59]
	v_mfma_f32_16x16x32_bf16 v[52:55], v[228:231], v[208:211], v[52:55]
	v_mfma_f32_16x16x32_bf16 v[48:51], v[232:235], v[208:211], v[48:51]
	v_mfma_f32_16x16x32_bf16 v[44:47], v[236:239], v[208:211], v[44:47]
	v_mfma_f32_16x16x32_bf16 v[40:43], v[224:227], v[212:215], v[40:43]
	v_mfma_f32_16x16x32_bf16 v[36:39], v[228:231], v[212:215], v[36:39]
	v_mfma_f32_16x16x32_bf16 v[32:35], v[232:235], v[212:215], v[32:35]
	v_mfma_f32_16x16x32_bf16 v[28:31], v[236:239], v[212:215], v[28:31]
	v_mfma_f32_16x16x32_bf16 v[24:27], v[224:227], v[216:219], v[24:27]
	v_mfma_f32_16x16x32_bf16 v[20:23], v[228:231], v[216:219], v[20:23]
	v_mfma_f32_16x16x32_bf16 v[16:19], v[232:235], v[216:219], v[16:19]
	v_mfma_f32_16x16x32_bf16 v[12:15], v[236:239], v[216:219], v[12:15]
	v_mfma_f32_16x16x32_bf16 v[8:11], v[224:227], v[220:223], v[8:11]
	v_mfma_f32_16x16x32_bf16 v[4:7], v[228:231], v[220:223], v[4:7]
	v_mfma_f32_16x16x32_bf16 v[0:3], v[232:235], v[220:223], v[0:3]
	v_mfma_f32_16x16x32_bf16 v[60:63], v[236:239], v[220:223], v[60:63]
	s_nop 7
	s_nop 7
	s_barrier
	ds_write_b64 v252, v[250:251]
	s_mov_b32 s34, 0
	v_cvt_pk_bf16_f32 v8, v8, v9
	v_cvt_pk_bf16_f32 v9, v10, v11
	v_cvt_pk_bf16_f32 v4, v4, v5
	v_cvt_pk_bf16_f32 v5, v6, v7
	v_add_u32_e32 v6, 0x2800, v160
	ds_write2_b64 v6, v[8:9], v[4:5] offset0:160 offset1:164
	v_cvt_pk_bf16_f32 v4, v0, v1
	v_cvt_pk_bf16_f32 v5, v2, v3
	v_cvt_pk_bf16_f32 v92, v92, v93
	v_cvt_pk_bf16_f32 v93, v94, v95
	v_cvt_pk_bf16_f32 v88, v88, v89
	v_cvt_pk_bf16_f32 v89, v90, v91
	ds_write2_b64 v160, v[92:93], v[88:89] offset1:4
	v_cvt_pk_bf16_f32 v84, v84, v85
	v_cvt_pk_bf16_f32 v85, v86, v87
	v_cvt_pk_bf16_f32 v80, v80, v81
	v_cvt_pk_bf16_f32 v81, v82, v83
	v_cvt_pk_bf16_f32 v76, v76, v77
	v_cvt_pk_bf16_f32 v77, v78, v79
	v_cvt_pk_bf16_f32 v72, v72, v73
	v_cvt_pk_bf16_f32 v73, v74, v75
	v_add_u32_e32 v74, 0x800, v160
	v_cvt_pk_bf16_f32 v68, v68, v69
	v_cvt_pk_bf16_f32 v69, v70, v71
	ds_write2_b64 v160, v[84:85], v[80:81] offset0:8 offset1:12
	v_cvt_pk_bf16_f32 v64, v64, v65
	v_cvt_pk_bf16_f32 v65, v66, v67
	ds_write2_b64 v74, v[76:77], v[72:73] offset0:32 offset1:36
	v_cvt_pk_bf16_f32 v56, v56, v57
	v_cvt_pk_bf16_f32 v57, v58, v59
	ds_write2_b64 v74, v[68:69], v[64:65] offset0:40 offset1:44
	v_cvt_pk_bf16_f32 v52, v52, v53
	v_cvt_pk_bf16_f32 v53, v54, v55
	v_add_u32_e32 v54, 0x1000, v160
	v_cvt_pk_bf16_f32 v48, v48, v49
	v_cvt_pk_bf16_f32 v49, v50, v51
	ds_write2_b64 v54, v[56:57], v[52:53] offset0:64 offset1:68
	v_cvt_pk_bf16_f32 v44, v44, v45
	v_cvt_pk_bf16_f32 v45, v46, v47
	ds_write2_b64 v54, v[48:49], v[44:45] offset0:72 offset1:76
	v_cvt_pk_bf16_f32 v40, v40, v41
	v_cvt_pk_bf16_f32 v41, v42, v43
	v_cvt_pk_bf16_f32 v36, v36, v37
	v_cvt_pk_bf16_f32 v37, v38, v39
	v_add_u32_e32 v38, 0x1800, v160
	v_cvt_pk_bf16_f32 v32, v32, v33
	v_cvt_pk_bf16_f32 v33, v34, v35
	v_cvt_pk_bf16_f32 v28, v28, v29
	v_cvt_pk_bf16_f32 v29, v30, v31
	v_cvt_pk_bf16_f32 v24, v24, v25
	v_cvt_pk_bf16_f32 v25, v26, v27
	ds_write2_b64 v38, v[40:41], v[36:37] offset0:96 offset1:100
	v_cvt_pk_bf16_f32 v20, v20, v21
	v_cvt_pk_bf16_f32 v21, v22, v23
	v_add_u32_e32 v22, 0x2000, v160
	v_cvt_pk_bf16_f32 v16, v16, v17
	v_cvt_pk_bf16_f32 v17, v18, v19
	v_mov_b32_e32 v0, v60
	v_mov_b32_e32 v1, v61
	v_mov_b32_e32 v2, v62
	v_mov_b32_e32 v3, v63
	ds_write2_b64 v38, v[32:33], v[28:29] offset0:104 offset1:108
	s_nop 2
	v_cvt_pk_bf16_f32 v12, v12, v13
	v_cvt_pk_bf16_f32 v13, v14, v15
	ds_write2_b64 v22, v[24:25], v[20:21] offset0:128 offset1:132
	ds_write2_b64 v22, v[16:17], v[12:13] offset0:136 offset1:140
	v_cvt_pk_bf16_f32 v0, v0, v1
	v_cvt_pk_bf16_f32 v1, v2, v3
	ds_write2_b64 v6, v[4:5], v[0:1] offset0:168 offset1:172
	v_or_b32_e32 v0, s6, v148
	s_waitcnt lgkmcnt(0)
	v_ashrrev_i32_e32 v1, 31, v0
	v_add_u32_e32 v12, s4, v146
	v_lshl_add_u64 v[8:9], v[0:1], 1, s[2:3]
	ds_read_b128 v[0:3], v161
	v_or_b32_e32 v4, v12, v147
	v_mad_i64_i32 v[10:11], s[4:5], v4, s31, v[8:9]
	ds_read_b128 v[4:7], v161 offset:1152
	s_waitcnt lgkmcnt(1)
	global_store_dwordx4 v[10:11], v[0:3], off
	s_nop 1
	v_or_b32_e32 v0, v12, v149
	v_mad_i64_i32 v[0:1], s[4:5], v0, s31, v[8:9]
	s_waitcnt lgkmcnt(0)
	global_store_dwordx4 v[0:1], v[4:7], off
	ds_read_b128 v[0:3], v161 offset:2304
	s_nop 0
	v_or_b32_e32 v4, v12, v150
	v_mad_i64_i32 v[10:11], s[4:5], v4, s31, v[8:9]
	ds_read_b128 v[4:7], v161 offset:3456
	s_waitcnt lgkmcnt(1)
	global_store_dwordx4 v[10:11], v[0:3], off
	s_nop 1
	v_or_b32_e32 v0, v12, v151
	v_mad_i64_i32 v[0:1], s[4:5], v0, s31, v[8:9]
	s_waitcnt lgkmcnt(0)
	global_store_dwordx4 v[0:1], v[4:7], off
	ds_read_b128 v[0:3], v161 offset:4608
	s_nop 0
	v_add_u32_e32 v4, v12, v152
	v_mad_i64_i32 v[10:11], s[4:5], v4, s31, v[8:9]
	ds_read_b128 v[4:7], v161 offset:5760
	s_waitcnt lgkmcnt(1)
	global_store_dwordx4 v[10:11], v[0:3], off
	s_nop 1
	v_add_u32_e32 v0, v12, v153
	v_mad_i64_i32 v[0:1], s[4:5], v0, s31, v[8:9]
	s_waitcnt lgkmcnt(0)
	global_store_dwordx4 v[0:1], v[4:7], off
	ds_read_b128 v[0:3], v161 offset:6912
	s_nop 0
	v_add_u32_e32 v4, v12, v154
	v_mad_i64_i32 v[10:11], s[4:5], v4, s31, v[8:9]
	ds_read_b128 v[4:7], v161 offset:8064
	s_waitcnt lgkmcnt(1)
	global_store_dwordx4 v[10:11], v[0:3], off
	s_nop 1
	v_add_u32_e32 v0, v12, v155
	v_mad_i64_i32 v[0:1], s[4:5], v0, s31, v[8:9]
	s_waitcnt lgkmcnt(0)
	global_store_dwordx4 v[0:1], v[4:7], off
	ds_read_b128 v[0:3], v161 offset:9216
	s_nop 0
	v_add_u32_e32 v4, v12, v156
	v_mad_i64_i32 v[10:11], s[4:5], v4, s31, v[8:9]
	ds_read_b128 v[4:7], v161 offset:10368
	s_waitcnt lgkmcnt(1)
	global_store_dwordx4 v[10:11], v[0:3], off
	s_nop 1
	v_add_u32_e32 v0, v12, v157
	v_mad_i64_i32 v[0:1], s[4:5], v0, s31, v[8:9]
	s_waitcnt lgkmcnt(0)
	global_store_dwordx4 v[0:1], v[4:7], off
	ds_read_b128 v[0:3], v161 offset:11520
	s_nop 0
	v_add_u32_e32 v4, v12, v158
	v_mad_i64_i32 v[10:11], s[4:5], v4, s31, v[8:9]
	ds_read_b128 v[4:7], v161 offset:12672
	s_waitcnt lgkmcnt(1)
	global_store_dwordx4 v[10:11], v[0:3], off
	s_nop 1
	v_add_u32_e32 v0, v12, v159
	v_mad_i64_i32 v[0:1], s[4:5], v0, s31, v[8:9]
	s_waitcnt lgkmcnt(0)
	global_store_dwordx4 v[0:1], v[4:7], off

.LBB0_1118:
	s_bfe_u32 s4, s12, 0x30005
	s_mul_i32 s7, s4, 0xc0
	s_bfe_u32 s4, s14, 0x30007
	v_mad_u64_u32 v[144:145], s[30:31], s4, v162, v[142:143]
	s_lshl_b32 s30, s11, 5
	s_lshl_b32 s4, s6, 8
	s_and_b32 s30, s30, 0xe0
	s_or_b32 s30, s30, s4
	s_mul_i32 s30, s30, 6
	v_mad_i64_i32 v[0:1], s[34:35], s30, v163, v[138:139]
	v_add_co_u32_e32 v2, vcc, s17, v0
	s_lshl_b32 s4, s11, 4
	s_nop 0
	v_addc_co_u32_e32 v3, vcc, 0, v1, vcc
	s_nop 0
	v_readfirstlane_b32 s98, v0
	v_readfirstlane_b32 s99, v1
	v_add_co_u32_e32 v2, vcc, s18, v0
	s_and_b32 s31, s4, 0x380
	s_nop 0
	v_addc_co_u32_e32 v3, vcc, 0, v1, vcc
	v_add_co_u32_e32 v4, vcc, s19, v0
	s_mul_i32 s4, s31, 0x1600
	s_nop 0
	v_addc_co_u32_e32 v5, vcc, 0, v1, vcc
	v_add_co_u32_e32 v2, vcc, s16, v0
	v_mov_b32_e32 v64, 0
	s_nop 0
	v_addc_co_u32_e32 v3, vcc, 0, v1, vcc
	v_add_co_u32_e32 v0, vcc, 0xdc000, v0
	v_mov_b32_e32 v65, v137
	s_nop 0
	v_addc_co_u32_e32 v1, vcc, 0, v1, vcc
	v_lshl_add_u64 v[0:1], v[140:141], 0, s[4:5]
	v_add_co_u32_e32 v2, vcc, s17, v0
	s_mul_i32 s4, s6, 0x600
	s_nop 0
	v_addc_co_u32_e32 v3, vcc, 0, v1, vcc
	s_nop 0
	v_readfirstlane_b32 s100, v0
	v_readfirstlane_b32 s101, v1
	v_add_co_u32_e32 v2, vcc, 0x58000, v0
	s_add_i32 s4, s4, s7
	s_nop 0
	v_addc_co_u32_e32 v3, vcc, 0, v1, vcc
	v_add_co_u32_e32 v0, vcc, 0x84000, v0
	v_mad_i64_i32 v[146:147], s[6:7], s4, v163, v[142:143]
	s_nop 0
	v_addc_co_u32_e32 v1, vcc, 0, v1, vcc
	s_mov_b64 s[6:7], 0
	v_mov_b32_e32 v66, v137
	v_mov_b32_e32 v67, v137
	v_mov_b32_e32 v0, 0
	v_mov_b32_e32 v1, v137
	v_mov_b32_e32 v2, v137
	v_mov_b32_e32 v3, v137
	v_mov_b32_e32 v4, 0
	v_mov_b32_e32 v5, v137
	v_mov_b32_e32 v6, v137
	v_mov_b32_e32 v7, v137
	v_mov_b32_e32 v8, 0
	v_mov_b32_e32 v9, v137
	v_mov_b32_e32 v10, v137
	v_mov_b32_e32 v11, v137
	v_mov_b32_e32 v12, 0
	v_mov_b32_e32 v13, v137
	v_mov_b32_e32 v14, v137
	v_mov_b32_e32 v15, v137
	v_mov_b32_e32 v16, 0
	v_mov_b32_e32 v17, v137
	v_mov_b32_e32 v18, v137
	v_mov_b32_e32 v19, v137
	v_mov_b32_e32 v20, 0
	v_mov_b32_e32 v21, v137
	v_mov_b32_e32 v22, v137
	v_mov_b32_e32 v23, v137
	v_mov_b32_e32 v24, 0
	v_mov_b32_e32 v25, v137
	v_mov_b32_e32 v26, v137
	v_mov_b32_e32 v27, v137
	v_mov_b32_e32 v28, 0
	v_mov_b32_e32 v29, v137
	v_mov_b32_e32 v30, v137
	v_mov_b32_e32 v31, v137
	v_mov_b32_e32 v32, 0
	v_mov_b32_e32 v33, v137
	v_mov_b32_e32 v34, v137
	v_mov_b32_e32 v35, v137
	v_mov_b32_e32 v36, 0
	v_mov_b32_e32 v37, v137
	v_mov_b32_e32 v38, v137
	v_mov_b32_e32 v39, v137
	v_mov_b32_e32 v40, 0
	v_mov_b32_e32 v41, v137
	v_mov_b32_e32 v42, v137
	v_mov_b32_e32 v43, v137
	v_mov_b32_e32 v44, 0
	v_mov_b32_e32 v45, v137
	v_mov_b32_e32 v46, v137
	v_mov_b32_e32 v47, v137
	v_mov_b32_e32 v48, 0
	v_mov_b32_e32 v49, v137
	v_mov_b32_e32 v50, v137
	v_mov_b32_e32 v51, v137
	v_mov_b32_e32 v52, 0
	v_mov_b32_e32 v53, v137
	v_mov_b32_e32 v54, v137
	v_mov_b32_e32 v55, v137
	v_mov_b32_e32 v56, 0
	v_mov_b32_e32 v57, v137
	v_mov_b32_e32 v58, v137
	v_mov_b32_e32 v59, v137
	v_mov_b32_e32 v60, 0
	v_mov_b32_e32 v61, v137
	v_mov_b32_e32 v62, v137
	v_mov_b32_e32 v63, v137
	v_mov_b32_e32 v68, 0
	v_mov_b32_e32 v69, v137
	v_mov_b32_e32 v70, v137
	v_mov_b32_e32 v71, v137
	v_mov_b32_e32 v72, 0
	v_mov_b32_e32 v73, v137
	v_mov_b32_e32 v74, v137
	v_mov_b32_e32 v75, v137
	v_mov_b32_e32 v76, 0
	v_mov_b32_e32 v77, v137
	v_mov_b32_e32 v78, v137
	v_mov_b32_e32 v79, v137
	v_mov_b32_e32 v80, 0
	v_mov_b32_e32 v81, v137
	v_mov_b32_e32 v82, v137
	v_mov_b32_e32 v83, v137
	v_mov_b32_e32 v84, 0
	v_mov_b32_e32 v85, v137
	v_mov_b32_e32 v86, v137
	v_mov_b32_e32 v87, v137
	v_mov_b32_e32 v88, 0
	v_mov_b32_e32 v89, v137
	v_mov_b32_e32 v90, v137
	v_mov_b32_e32 v91, v137
	v_mov_b32_e32 v92, 0
	v_mov_b32_e32 v93, v137
	v_mov_b32_e32 v94, v137
	v_mov_b32_e32 v95, v137
	v_and_b32_e32 v197, 63, v196
	v_lshrrev_b32_e32 v198, 3, v197
	v_and_b32_e32 v199, 7, v197
	v_xor_b32_e32 v199, v199, v198
	v_lshlrev_b32_e32 v199, 4, v199
	v_mul_u32_u24_e32 v198, 5632, v198
	v_add_u32_e32 v240, v198, v199
	v_add_u32_e32 v241, 180224, v240
	v_add_u32_e32 v242, 360448, v240
	v_add_u32_e32 v243, 540672, v240
	v_add_u32_e32 v244, 720896, v240
	v_add_u32_e32 v245, 901120, v240
	v_lshrrev_b32_e32 v198, 6, v196
	v_lshrrev_b32_e32 v199, 1, v198
	v_and_b32_e32 v198, 1, v198
	v_and_b32_e32 v190, 15, v197
	v_lshrrev_b32_e32 v191, 4, v197
	v_and_b32_e32 v192, 7, v190
	v_xor_b32_e32 v191, v191, v192
	v_lshlrev_b32_e32 v191, 4, v191
	v_mul_u32_u24_e32 v199, 0x60, v199
	v_add_u32_e32 v199, v199, v190
	v_lshl_add_u32 v246, v199, 7, v191
	v_xor_b32_e32 v247, 64, v246
	v_lshlrev_b32_e32 v198, 6, v198
	v_add_u32_e32 v198, v198, v190
	v_lshl_add_u32 v248, v198, 7, v191
	v_add_u32_e32 v248, 0x6000, v248
	v_xor_b32_e32 v249, 64, v248
	v_lshrrev_b32_e32 v198, 6, v196
	v_lshlrev_b32_e32 v198, 10, v198
	s_nop 0
	v_readfirstlane_b32 s6, v198
	s_mov_b32 s7, 21
	s_waitcnt lgkmcnt(0)
	s_barrier
	s_add_u32 m0, s6, 0
	s_nop 0
	global_load_lds_dwordx4 v240, s[98:99]
	s_add_u32 m0, s6, 4096
	s_nop 0
	global_load_lds_dwordx4 v241, s[98:99]
	s_add_u32 m0, s6, 8192
	s_nop 0
	global_load_lds_dwordx4 v242, s[98:99]
	s_add_u32 m0, s6, 12288
	s_nop 0
	global_load_lds_dwordx4 v243, s[98:99]
	s_add_u32 m0, s6, 16384
	s_nop 0
	global_load_lds_dwordx4 v244, s[98:99]
	s_add_u32 m0, s6, 20480
	s_nop 0
	global_load_lds_dwordx4 v245, s[98:99]
	s_add_u32 m0, s6, 24576
	s_nop 0
	global_load_lds_dwordx4 v240, s[100:101]
	s_add_u32 m0, s6, 28672
	s_nop 0
	global_load_lds_dwordx4 v241, s[100:101]
	s_add_u32 m0, s6, 32768
	s_nop 0
	global_load_lds_dwordx4 v242, s[100:101]
	s_add_u32 m0, s6, 36864
	s_nop 0
	global_load_lds_dwordx4 v243, s[100:101]
	s_add_u32 s98, s98, 0x80
	s_addc_u32 s99, s99, 0
	s_add_u32 s100, s100, 0x80
	s_addc_u32 s101, s101, 0
	s_waitcnt vmcnt(0)
	s_barrier
	ds_read_b128 v[120:123], v248 offset:0
	ds_read_b128 v[124:127], v248 offset:2048
	ds_read_b128 v[128:131], v248 offset:4096
	ds_read_b128 v[132:135], v248 offset:6144
	ds_read_b128 v[96:99], v246 offset:0
	ds_read_b128 v[100:103], v246 offset:2048
	ds_read_b128 v[104:107], v246 offset:4096
	ds_read_b128 v[108:111], v246 offset:6144
	ds_read_b128 v[112:115], v246 offset:8192
	ds_read_b128 v[116:119], v246 offset:10240
	s_add_u32 m0, s6, 40960
	s_nop 0
	global_load_lds_dwordx4 v240, s[98:99]
	s_add_u32 m0, s6, 45056
	s_nop 0
	global_load_lds_dwordx4 v241, s[98:99]
	s_add_u32 m0, s6, 49152
	s_nop 0
	global_load_lds_dwordx4 v242, s[98:99]
	s_add_u32 m0, s6, 53248
	s_nop 0
	global_load_lds_dwordx4 v243, s[98:99]
	s_add_u32 m0, s6, 57344
	s_nop 0
	global_load_lds_dwordx4 v244, s[98:99]
	s_add_u32 m0, s6, 61440
	s_nop 0
	global_load_lds_dwordx4 v245, s[98:99]
	s_add_u32 m0, s6, 65536
	s_nop 0
	global_load_lds_dwordx4 v240, s[100:101]
	s_add_u32 m0, s6, 69632
	s_nop 0
	global_load_lds_dwordx4 v241, s[100:101]
	s_add_u32 m0, s6, 73728
	s_nop 0
	global_load_lds_dwordx4 v242, s[100:101]
	s_add_u32 m0, s6, 77824
	s_nop 0
	global_load_lds_dwordx4 v243, s[100:101]
	s_add_u32 s98, s98, 0x80
	s_addc_u32 s99, s99, 0
	s_add_u32 s100, s100, 0x80
	s_addc_u32 s101, s101, 0
	s_waitcnt lgkmcnt(0)
	v_mfma_f32_16x16x32_bf16 v[92:95], v[120:123], v[96:99], v[92:95]
	v_mfma_f32_16x16x32_bf16 v[88:91], v[124:127], v[96:99], v[88:91]
	ds_read_b128 v[224:227], v249 offset:0
	v_mfma_f32_16x16x32_bf16 v[84:87], v[128:131], v[96:99], v[84:87]
	v_mfma_f32_16x16x32_bf16 v[80:83], v[132:135], v[96:99], v[80:83]
	ds_read_b128 v[228:231], v249 offset:2048
	v_mfma_f32_16x16x32_bf16 v[76:79], v[120:123], v[100:103], v[76:79]
	v_mfma_f32_16x16x32_bf16 v[72:75], v[124:127], v[100:103], v[72:75]
	ds_read_b128 v[232:235], v249 offset:4096
	v_mfma_f32_16x16x32_bf16 v[68:71], v[128:131], v[100:103], v[68:71]
	v_mfma_f32_16x16x32_bf16 v[60:63], v[132:135], v[100:103], v[60:63]
	ds_read_b128 v[236:239], v249 offset:6144
	v_mfma_f32_16x16x32_bf16 v[56:59], v[120:123], v[104:107], v[56:59]
	v_mfma_f32_16x16x32_bf16 v[52:55], v[124:127], v[104:107], v[52:55]
	ds_read_b128 v[200:203], v247 offset:0
	v_mfma_f32_16x16x32_bf16 v[48:51], v[128:131], v[104:107], v[48:51]
	v_mfma_f32_16x16x32_bf16 v[44:47], v[132:135], v[104:107], v[44:47]
	ds_read_b128 v[204:207], v247 offset:2048
	v_mfma_f32_16x16x32_bf16 v[40:43], v[120:123], v[108:111], v[40:43]
	v_mfma_f32_16x16x32_bf16 v[36:39], v[124:127], v[108:111], v[36:39]
	ds_read_b128 v[208:211], v247 offset:4096
	v_mfma_f32_16x16x32_bf16 v[32:35], v[128:131], v[108:111], v[32:35]
	v_mfma_f32_16x16x32_bf16 v[28:31], v[132:135], v[108:111], v[28:31]
	ds_read_b128 v[212:215], v247 offset:6144
	v_mfma_f32_16x16x32_bf16 v[24:27], v[120:123], v[112:115], v[24:27]
	v_mfma_f32_16x16x32_bf16 v[20:23], v[124:127], v[112:115], v[20:23]
	ds_read_b128 v[216:219], v247 offset:8192
	v_mfma_f32_16x16x32_bf16 v[16:19], v[128:131], v[112:115], v[16:19]
	v_mfma_f32_16x16x32_bf16 v[12:15], v[132:135], v[112:115], v[12:15]
	ds_read_b128 v[220:223], v247 offset:10240
	v_mfma_f32_16x16x32_bf16 v[8:11], v[120:123], v[116:119], v[8:11]
	v_mfma_f32_16x16x32_bf16 v[4:7], v[124:127], v[116:119], v[4:7]
	v_mfma_f32_16x16x32_bf16 v[0:3], v[128:131], v[116:119], v[0:3]
	v_mfma_f32_16x16x32_bf16 v[64:67], v[132:135], v[116:119], v[64:67]
.Lg6p9_loop:
	s_waitcnt vmcnt(0) lgkmcnt(0)
	s_barrier
	ds_read_b128 v[120:123], v248 offset:40960
	ds_read_b128 v[124:127], v248 offset:43008
	ds_read_b128 v[128:131], v248 offset:45056
	ds_read_b128 v[132:135], v248 offset:47104
	ds_read_b128 v[96:99], v246 offset:40960
	ds_read_b128 v[100:103], v246 offset:43008
	ds_read_b128 v[104:107], v246 offset:45056
	ds_read_b128 v[108:111], v246 offset:47104
	ds_read_b128 v[112:115], v246 offset:49152
	ds_read_b128 v[116:119], v246 offset:51200
	s_add_u32 m0, s6, 0
	v_mfma_f32_16x16x32_bf16 v[92:95], v[224:227], v[200:203], v[92:95]
	global_load_lds_dwordx4 v240, s[98:99]
	v_mfma_f32_16x16x32_bf16 v[88:91], v[228:231], v[200:203], v[88:91]
	s_add_u32 m0, s6, 4096
	v_mfma_f32_16x16x32_bf16 v[84:87], v[232:235], v[200:203], v[84:87]
	global_load_lds_dwordx4 v241, s[98:99]
	v_mfma_f32_16x16x32_bf16 v[80:83], v[236:239], v[200:203], v[80:83]
	s_add_u32 m0, s6, 8192
	v_mfma_f32_16x16x32_bf16 v[76:79], v[224:227], v[204:207], v[76:79]
	global_load_lds_dwordx4 v242, s[98:99]
	v_mfma_f32_16x16x32_bf16 v[72:75], v[228:231], v[204:207], v[72:75]
	s_add_u32 m0, s6, 12288
	v_mfma_f32_16x16x32_bf16 v[68:71], v[232:235], v[204:207], v[68:71]
	global_load_lds_dwordx4 v243, s[98:99]
	v_mfma_f32_16x16x32_bf16 v[60:63], v[236:239], v[204:207], v[60:63]
	s_add_u32 m0, s6, 16384
	v_mfma_f32_16x16x32_bf16 v[56:59], v[224:227], v[208:211], v[56:59]
	global_load_lds_dwordx4 v244, s[98:99]
	v_mfma_f32_16x16x32_bf16 v[52:55], v[228:231], v[208:211], v[52:55]
	s_add_u32 m0, s6, 20480
	v_mfma_f32_16x16x32_bf16 v[48:51], v[232:235], v[208:211], v[48:51]
	global_load_lds_dwordx4 v245, s[98:99]
	v_mfma_f32_16x16x32_bf16 v[44:47], v[236:239], v[208:211], v[44:47]
	s_add_u32 m0, s6, 24576
	v_mfma_f32_16x16x32_bf16 v[40:43], v[224:227], v[212:215], v[40:43]
	global_load_lds_dwordx4 v240, s[100:101]
	v_mfma_f32_16x16x32_bf16 v[36:39], v[228:231], v[212:215], v[36:39]
	s_add_u32 m0, s6, 28672
	v_mfma_f32_16x16x32_bf16 v[32:35], v[232:235], v[212:215], v[32:35]
	global_load_lds_dwordx4 v241, s[100:101]
	v_mfma_f32_16x16x32_bf16 v[28:31], v[236:239], v[212:215], v[28:31]
	s_add_u32 m0, s6, 32768
	v_mfma_f32_16x16x32_bf16 v[24:27], v[224:227], v[216:219], v[24:27]
	global_load_lds_dwordx4 v242, s[100:101]
	v_mfma_f32_16x16x32_bf16 v[20:23], v[228:231], v[216:219], v[20:23]
	s_add_u32 m0, s6, 36864
	v_mfma_f32_16x16x32_bf16 v[16:19], v[232:235], v[216:219], v[16:19]
	global_load_lds_dwordx4 v243, s[100:101]
	v_mfma_f32_16x16x32_bf16 v[12:15], v[236:239], v[216:219], v[12:15]
	v_mfma_f32_16x16x32_bf16 v[8:11], v[224:227], v[220:223], v[8:11]
	v_mfma_f32_16x16x32_bf16 v[4:7], v[228:231], v[220:223], v[4:7]
	v_mfma_f32_16x16x32_bf16 v[0:3], v[232:235], v[220:223], v[0:3]
	v_mfma_f32_16x16x32_bf16 v[64:67], v[236:239], v[220:223], v[64:67]
	s_add_u32 s98, s98, 0x80
	s_addc_u32 s99, s99, 0
	s_add_u32 s100, s100, 0x80
	s_addc_u32 s101, s101, 0
	s_waitcnt lgkmcnt(0)
	v_mfma_f32_16x16x32_bf16 v[92:95], v[120:123], v[96:99], v[92:95]
	v_mfma_f32_16x16x32_bf16 v[88:91], v[124:127], v[96:99], v[88:91]
	ds_read_b128 v[224:227], v249 offset:40960
	v_mfma_f32_16x16x32_bf16 v[84:87], v[128:131], v[96:99], v[84:87]
	v_mfma_f32_16x16x32_bf16 v[80:83], v[132:135], v[96:99], v[80:83]
	ds_read_b128 v[228:231], v249 offset:43008
	v_mfma_f32_16x16x32_bf16 v[76:79], v[120:123], v[100:103], v[76:79]
	v_mfma_f32_16x16x32_bf16 v[72:75], v[124:127], v[100:103], v[72:75]
	ds_read_b128 v[232:235], v249 offset:45056
	v_mfma_f32_16x16x32_bf16 v[68:71], v[128:131], v[100:103], v[68:71]
	v_mfma_f32_16x16x32_bf16 v[60:63], v[132:135], v[100:103], v[60:63]
	ds_read_b128 v[236:239], v249 offset:47104
	v_mfma_f32_16x16x32_bf16 v[56:59], v[120:123], v[104:107], v[56:59]
	v_mfma_f32_16x16x32_bf16 v[52:55], v[124:127], v[104:107], v[52:55]
	ds_read_b128 v[200:203], v247 offset:40960
	v_mfma_f32_16x16x32_bf16 v[48:51], v[128:131], v[104:107], v[48:51]
	v_mfma_f32_16x16x32_bf16 v[44:47], v[132:135], v[104:107], v[44:47]
	ds_read_b128 v[204:207], v247 offset:43008
	v_mfma_f32_16x16x32_bf16 v[40:43], v[120:123], v[108:111], v[40:43]
	v_mfma_f32_16x16x32_bf16 v[36:39], v[124:127], v[108:111], v[36:39]
	ds_read_b128 v[208:211], v247 offset:45056
	v_mfma_f32_16x16x32_bf16 v[32:35], v[128:131], v[108:111], v[32:35]
	v_mfma_f32_16x16x32_bf16 v[28:31], v[132:135], v[108:111], v[28:31]
	ds_read_b128 v[212:215], v247 offset:47104
	v_mfma_f32_16x16x32_bf16 v[24:27], v[120:123], v[112:115], v[24:27]
	v_mfma_f32_16x16x32_bf16 v[20:23], v[124:127], v[112:115], v[20:23]
	ds_read_b128 v[216:219], v247 offset:49152
	v_mfma_f32_16x16x32_bf16 v[16:19], v[128:131], v[112:115], v[16:19]
	v_mfma_f32_16x16x32_bf16 v[12:15], v[132:135], v[112:115], v[12:15]
	ds_read_b128 v[220:223], v247 offset:51200
	v_mfma_f32_16x16x32_bf16 v[8:11], v[120:123], v[116:119], v[8:11]
	v_mfma_f32_16x16x32_bf16 v[4:7], v[124:127], v[116:119], v[4:7]
	v_mfma_f32_16x16x32_bf16 v[0:3], v[128:131], v[116:119], v[0:3]
	v_mfma_f32_16x16x32_bf16 v[64:67], v[132:135], v[116:119], v[64:67]
	s_waitcnt vmcnt(0) lgkmcnt(0)
	s_barrier
	ds_read_b128 v[120:123], v248 offset:0
	ds_read_b128 v[124:127], v248 offset:2048
	ds_read_b128 v[128:131], v248 offset:4096
	ds_read_b128 v[132:135], v248 offset:6144
	ds_read_b128 v[96:99], v246 offset:0
	ds_read_b128 v[100:103], v246 offset:2048
	ds_read_b128 v[104:107], v246 offset:4096
	ds_read_b128 v[108:111], v246 offset:6144
	ds_read_b128 v[112:115], v246 offset:8192
	ds_read_b128 v[116:119], v246 offset:10240
	s_add_u32 m0, s6, 40960
	v_mfma_f32_16x16x32_bf16 v[92:95], v[224:227], v[200:203], v[92:95]
	global_load_lds_dwordx4 v240, s[98:99]
	v_mfma_f32_16x16x32_bf16 v[88:91], v[228:231], v[200:203], v[88:91]
	s_add_u32 m0, s6, 45056
	v_mfma_f32_16x16x32_bf16 v[84:87], v[232:235], v[200:203], v[84:87]
	global_load_lds_dwordx4 v241, s[98:99]
	v_mfma_f32_16x16x32_bf16 v[80:83], v[236:239], v[200:203], v[80:83]
	s_add_u32 m0, s6, 49152
	v_mfma_f32_16x16x32_bf16 v[76:79], v[224:227], v[204:207], v[76:79]
	global_load_lds_dwordx4 v242, s[98:99]
	v_mfma_f32_16x16x32_bf16 v[72:75], v[228:231], v[204:207], v[72:75]
	s_add_u32 m0, s6, 53248
	v_mfma_f32_16x16x32_bf16 v[68:71], v[232:235], v[204:207], v[68:71]
	global_load_lds_dwordx4 v243, s[98:99]
	v_mfma_f32_16x16x32_bf16 v[60:63], v[236:239], v[204:207], v[60:63]
	s_add_u32 m0, s6, 57344
	v_mfma_f32_16x16x32_bf16 v[56:59], v[224:227], v[208:211], v[56:59]
	global_load_lds_dwordx4 v244, s[98:99]
	v_mfma_f32_16x16x32_bf16 v[52:55], v[228:231], v[208:211], v[52:55]
	s_add_u32 m0, s6, 61440
	v_mfma_f32_16x16x32_bf16 v[48:51], v[232:235], v[208:211], v[48:51]
	global_load_lds_dwordx4 v245, s[98:99]
	v_mfma_f32_16x16x32_bf16 v[44:47], v[236:239], v[208:211], v[44:47]
	s_add_u32 m0, s6, 65536
	v_mfma_f32_16x16x32_bf16 v[40:43], v[224:227], v[212:215], v[40:43]
	global_load_lds_dwordx4 v240, s[100:101]
	v_mfma_f32_16x16x32_bf16 v[36:39], v[228:231], v[212:215], v[36:39]
	s_add_u32 m0, s6, 69632
	v_mfma_f32_16x16x32_bf16 v[32:35], v[232:235], v[212:215], v[32:35]
	global_load_lds_dwordx4 v241, s[100:101]
	v_mfma_f32_16x16x32_bf16 v[28:31], v[236:239], v[212:215], v[28:31]
	s_add_u32 m0, s6, 73728
	v_mfma_f32_16x16x32_bf16 v[24:27], v[224:227], v[216:219], v[24:27]
	global_load_lds_dwordx4 v242, s[100:101]
	v_mfma_f32_16x16x32_bf16 v[20:23], v[228:231], v[216:219], v[20:23]
	s_add_u32 m0, s6, 77824
	v_mfma_f32_16x16x32_bf16 v[16:19], v[232:235], v[216:219], v[16:19]
	global_load_lds_dwordx4 v243, s[100:101]
	v_mfma_f32_16x16x32_bf16 v[12:15], v[236:239], v[216:219], v[12:15]
	v_mfma_f32_16x16x32_bf16 v[8:11], v[224:227], v[220:223], v[8:11]
	v_mfma_f32_16x16x32_bf16 v[4:7], v[228:231], v[220:223], v[4:7]
	v_mfma_f32_16x16x32_bf16 v[0:3], v[232:235], v[220:223], v[0:3]
	v_mfma_f32_16x16x32_bf16 v[64:67], v[236:239], v[220:223], v[64:67]
	s_add_u32 s98, s98, 0x80
	s_addc_u32 s99, s99, 0
	s_add_u32 s100, s100, 0x80
	s_addc_u32 s101, s101, 0
	s_waitcnt lgkmcnt(0)
	v_mfma_f32_16x16x32_bf16 v[92:95], v[120:123], v[96:99], v[92:95]
	v_mfma_f32_16x16x32_bf16 v[88:91], v[124:127], v[96:99], v[88:91]
	ds_read_b128 v[224:227], v249 offset:0
	v_mfma_f32_16x16x32_bf16 v[84:87], v[128:131], v[96:99], v[84:87]
	v_mfma_f32_16x16x32_bf16 v[80:83], v[132:135], v[96:99], v[80:83]
	ds_read_b128 v[228:231], v249 offset:2048
	v_mfma_f32_16x16x32_bf16 v[76:79], v[120:123], v[100:103], v[76:79]
	v_mfma_f32_16x16x32_bf16 v[72:75], v[124:127], v[100:103], v[72:75]
	ds_read_b128 v[232:235], v249 offset:4096
	v_mfma_f32_16x16x32_bf16 v[68:71], v[128:131], v[100:103], v[68:71]
	v_mfma_f32_16x16x32_bf16 v[60:63], v[132:135], v[100:103], v[60:63]
	ds_read_b128 v[236:239], v249 offset:6144
	v_mfma_f32_16x16x32_bf16 v[56:59], v[120:123], v[104:107], v[56:59]
	v_mfma_f32_16x16x32_bf16 v[52:55], v[124:127], v[104:107], v[52:55]
	ds_read_b128 v[200:203], v247 offset:0
	v_mfma_f32_16x16x32_bf16 v[48:51], v[128:131], v[104:107], v[48:51]
	v_mfma_f32_16x16x32_bf16 v[44:47], v[132:135], v[104:107], v[44:47]
	ds_read_b128 v[204:207], v247 offset:2048
	v_mfma_f32_16x16x32_bf16 v[40:43], v[120:123], v[108:111], v[40:43]
	v_mfma_f32_16x16x32_bf16 v[36:39], v[124:127], v[108:111], v[36:39]
	ds_read_b128 v[208:211], v247 offset:4096
	v_mfma_f32_16x16x32_bf16 v[32:35], v[128:131], v[108:111], v[32:35]
	v_mfma_f32_16x16x32_bf16 v[28:31], v[132:135], v[108:111], v[28:31]
	ds_read_b128 v[212:215], v247 offset:6144
	v_mfma_f32_16x16x32_bf16 v[24:27], v[120:123], v[112:115], v[24:27]
	v_mfma_f32_16x16x32_bf16 v[20:23], v[124:127], v[112:115], v[20:23]
	ds_read_b128 v[216:219], v247 offset:8192
	v_mfma_f32_16x16x32_bf16 v[16:19], v[128:131], v[112:115], v[16:19]
	v_mfma_f32_16x16x32_bf16 v[12:15], v[132:135], v[112:115], v[12:15]
	ds_read_b128 v[220:223], v247 offset:10240
	v_mfma_f32_16x16x32_bf16 v[8:11], v[120:123], v[116:119], v[8:11]
	v_mfma_f32_16x16x32_bf16 v[4:7], v[124:127], v[116:119], v[4:7]
	v_mfma_f32_16x16x32_bf16 v[0:3], v[128:131], v[116:119], v[0:3]
	v_mfma_f32_16x16x32_bf16 v[64:67], v[132:135], v[116:119], v[64:67]
	s_sub_u32 s7, s7, 1
	s_cmp_lg_u32 s7, 0
	s_cbranch_scc1 .Lg6p9_loop
	s_waitcnt vmcnt(0) lgkmcnt(0)
	s_barrier
	ds_read_b128 v[120:123], v248 offset:40960
	ds_read_b128 v[124:127], v248 offset:43008
	ds_read_b128 v[128:131], v248 offset:45056
	ds_read_b128 v[132:135], v248 offset:47104
	ds_read_b128 v[96:99], v246 offset:40960
	ds_read_b128 v[100:103], v246 offset:43008
	ds_read_b128 v[104:107], v246 offset:45056
	ds_read_b128 v[108:111], v246 offset:47104
	ds_read_b128 v[112:115], v246 offset:49152
	ds_read_b128 v[116:119], v246 offset:51200
	v_mfma_f32_16x16x32_bf16 v[92:95], v[224:227], v[200:203], v[92:95]
	v_mfma_f32_16x16x32_bf16 v[88:91], v[228:231], v[200:203], v[88:91]
	v_mfma_f32_16x16x32_bf16 v[84:87], v[232:235], v[200:203], v[84:87]
	v_mfma_f32_16x16x32_bf16 v[80:83], v[236:239], v[200:203], v[80:83]
	v_mfma_f32_16x16x32_bf16 v[76:79], v[224:227], v[204:207], v[76:79]
	v_mfma_f32_16x16x32_bf16 v[72:75], v[228:231], v[204:207], v[72:75]
	v_mfma_f32_16x16x32_bf16 v[68:71], v[232:235], v[204:207], v[68:71]
	v_mfma_f32_16x16x32_bf16 v[60:63], v[236:239], v[204:207], v[60:63]
	v_mfma_f32_16x16x32_bf16 v[56:59], v[224:227], v[208:211], v[56:59]
	v_mfma_f32_16x16x32_bf16 v[52:55], v[228:231], v[208:211], v[52:55]
	v_mfma_f32_16x16x32_bf16 v[48:51], v[232:235], v[208:211], v[48:51]
	v_mfma_f32_16x16x32_bf16 v[44:47], v[236:239], v[208:211], v[44:47]
	v_mfma_f32_16x16x32_bf16 v[40:43], v[224:227], v[212:215], v[40:43]
	v_mfma_f32_16x16x32_bf16 v[36:39], v[228:231], v[212:215], v[36:39]
	v_mfma_f32_16x16x32_bf16 v[32:35], v[232:235], v[212:215], v[32:35]
	v_mfma_f32_16x16x32_bf16 v[28:31], v[236:239], v[212:215], v[28:31]
	v_mfma_f32_16x16x32_bf16 v[24:27], v[224:227], v[216:219], v[24:27]
	v_mfma_f32_16x16x32_bf16 v[20:23], v[228:231], v[216:219], v[20:23]
	v_mfma_f32_16x16x32_bf16 v[16:19], v[232:235], v[216:219], v[16:19]
	v_mfma_f32_16x16x32_bf16 v[12:15], v[236:239], v[216:219], v[12:15]
	v_mfma_f32_16x16x32_bf16 v[8:11], v[224:227], v[220:223], v[8:11]
	v_mfma_f32_16x16x32_bf16 v[4:7], v[228:231], v[220:223], v[4:7]
	v_mfma_f32_16x16x32_bf16 v[0:3], v[232:235], v[220:223], v[0:3]
	v_mfma_f32_16x16x32_bf16 v[64:67], v[236:239], v[220:223], v[64:67]
	s_waitcnt lgkmcnt(0)
	v_mfma_f32_16x16x32_bf16 v[92:95], v[120:123], v[96:99], v[92:95]
	v_mfma_f32_16x16x32_bf16 v[88:91], v[124:127], v[96:99], v[88:91]
	ds_read_b128 v[224:227], v249 offset:40960
	v_mfma_f32_16x16x32_bf16 v[84:87], v[128:131], v[96:99], v[84:87]
	v_mfma_f32_16x16x32_bf16 v[80:83], v[132:135], v[96:99], v[80:83]
	ds_read_b128 v[228:231], v249 offset:43008
	v_mfma_f32_16x16x32_bf16 v[76:79], v[120:123], v[100:103], v[76:79]
	v_mfma_f32_16x16x32_bf16 v[72:75], v[124:127], v[100:103], v[72:75]
	ds_read_b128 v[232:235], v249 offset:45056
	v_mfma_f32_16x16x32_bf16 v[68:71], v[128:131], v[100:103], v[68:71]
	v_mfma_f32_16x16x32_bf16 v[60:63], v[132:135], v[100:103], v[60:63]
	ds_read_b128 v[236:239], v249 offset:47104
	v_mfma_f32_16x16x32_bf16 v[56:59], v[120:123], v[104:107], v[56:59]
	v_mfma_f32_16x16x32_bf16 v[52:55], v[124:127], v[104:107], v[52:55]
	ds_read_b128 v[200:203], v247 offset:40960
	v_mfma_f32_16x16x32_bf16 v[48:51], v[128:131], v[104:107], v[48:51]
	v_mfma_f32_16x16x32_bf16 v[44:47], v[132:135], v[104:107], v[44:47]
	ds_read_b128 v[204:207], v247 offset:43008
	v_mfma_f32_16x16x32_bf16 v[40:43], v[120:123], v[108:111], v[40:43]
	v_mfma_f32_16x16x32_bf16 v[36:39], v[124:127], v[108:111], v[36:39]
	ds_read_b128 v[208:211], v247 offset:45056
	v_mfma_f32_16x16x32_bf16 v[32:35], v[128:131], v[108:111], v[32:35]
	v_mfma_f32_16x16x32_bf16 v[28:31], v[132:135], v[108:111], v[28:31]
	ds_read_b128 v[212:215], v247 offset:47104
	v_mfma_f32_16x16x32_bf16 v[24:27], v[120:123], v[112:115], v[24:27]
	v_mfma_f32_16x16x32_bf16 v[20:23], v[124:127], v[112:115], v[20:23]
	ds_read_b128 v[216:219], v247 offset:49152
	v_mfma_f32_16x16x32_bf16 v[16:19], v[128:131], v[112:115], v[16:19]
	v_mfma_f32_16x16x32_bf16 v[12:15], v[132:135], v[112:115], v[12:15]
	ds_read_b128 v[220:223], v247 offset:51200
	v_mfma_f32_16x16x32_bf16 v[8:11], v[120:123], v[116:119], v[8:11]
	v_mfma_f32_16x16x32_bf16 v[4:7], v[124:127], v[116:119], v[4:7]
	v_mfma_f32_16x16x32_bf16 v[0:3], v[128:131], v[116:119], v[0:3]
	v_mfma_f32_16x16x32_bf16 v[64:67], v[132:135], v[116:119], v[64:67]
	s_waitcnt lgkmcnt(0)
	v_mfma_f32_16x16x32_bf16 v[92:95], v[224:227], v[200:203], v[92:95]
	v_mfma_f32_16x16x32_bf16 v[88:91], v[228:231], v[200:203], v[88:91]
	v_mfma_f32_16x16x32_bf16 v[84:87], v[232:235], v[200:203], v[84:87]
	v_mfma_f32_16x16x32_bf16 v[80:83], v[236:239], v[200:203], v[80:83]
	v_mfma_f32_16x16x32_bf16 v[76:79], v[224:227], v[204:207], v[76:79]
	v_mfma_f32_16x16x32_bf16 v[72:75], v[228:231], v[204:207], v[72:75]
	v_mfma_f32_16x16x32_bf16 v[68:71], v[232:235], v[204:207], v[68:71]
	v_mfma_f32_16x16x32_bf16 v[60:63], v[236:239], v[204:207], v[60:63]
	v_mfma_f32_16x16x32_bf16 v[56:59], v[224:227], v[208:211], v[56:59]
	v_mfma_f32_16x16x32_bf16 v[52:55], v[228:231], v[208:211], v[52:55]
	v_mfma_f32_16x16x32_bf16 v[48:51], v[232:235], v[208:211], v[48:51]
	v_mfma_f32_16x16x32_bf16 v[44:47], v[236:239], v[208:211], v[44:47]
	v_mfma_f32_16x16x32_bf16 v[40:43], v[224:227], v[212:215], v[40:43]
	v_mfma_f32_16x16x32_bf16 v[36:39], v[228:231], v[212:215], v[36:39]
	v_mfma_f32_16x16x32_bf16 v[32:35], v[232:235], v[212:215], v[32:35]
	v_mfma_f32_16x16x32_bf16 v[28:31], v[236:239], v[212:215], v[28:31]
	v_mfma_f32_16x16x32_bf16 v[24:27], v[224:227], v[216:219], v[24:27]
	v_mfma_f32_16x16x32_bf16 v[20:23], v[228:231], v[216:219], v[20:23]
	v_mfma_f32_16x16x32_bf16 v[16:19], v[232:235], v[216:219], v[16:19]
	v_mfma_f32_16x16x32_bf16 v[12:15], v[236:239], v[216:219], v[12:15]
	v_mfma_f32_16x16x32_bf16 v[8:11], v[224:227], v[220:223], v[8:11]
	v_mfma_f32_16x16x32_bf16 v[4:7], v[228:231], v[220:223], v[4:7]
	v_mfma_f32_16x16x32_bf16 v[0:3], v[232:235], v[220:223], v[0:3]
	v_mfma_f32_16x16x32_bf16 v[64:67], v[236:239], v[220:223], v[64:67]
	s_nop 7
	s_nop 7
	s_barrier
	ds_write_b64 v252, v[250:251]
	s_add_i32 s11, s11, s10
	s_ashr_i32 s4, s11, 6
	s_mul_i32 s4, s4, s9
	s_add_i32 s6, s4, s8
	s_add_i32 s12, s12, s13
	s_add_i32 s14, s14, s15
	s_cmp_lt_i32 s6, 8
	v_cvt_pk_bf16_f32 v8, v8, v9
	v_cvt_pk_bf16_f32 v9, v10, v11
	v_cvt_pk_bf16_f32 v4, v4, v5
	v_cvt_pk_bf16_f32 v5, v6, v7
	v_add_u32_e32 v6, 0x2800, v164
	ds_write2_b64 v6, v[8:9], v[4:5] offset0:160 offset1:164
	v_cvt_pk_bf16_f32 v4, v0, v1
	v_cvt_pk_bf16_f32 v5, v2, v3
	v_cvt_pk_bf16_f32 v92, v92, v93
	v_cvt_pk_bf16_f32 v93, v94, v95
	v_cvt_pk_bf16_f32 v88, v88, v89
	v_cvt_pk_bf16_f32 v89, v90, v91
	ds_write2_b64 v164, v[92:93], v[88:89] offset1:4
	v_cvt_pk_bf16_f32 v84, v84, v85
	v_cvt_pk_bf16_f32 v85, v86, v87
	v_cvt_pk_bf16_f32 v80, v80, v81
	v_cvt_pk_bf16_f32 v81, v82, v83
	v_cvt_pk_bf16_f32 v76, v76, v77
	v_cvt_pk_bf16_f32 v77, v78, v79
	v_cvt_pk_bf16_f32 v72, v72, v73
	v_cvt_pk_bf16_f32 v73, v74, v75
	v_add_u32_e32 v74, 0x800, v164
	v_cvt_pk_bf16_f32 v68, v68, v69
	v_cvt_pk_bf16_f32 v69, v70, v71
	ds_write2_b64 v164, v[84:85], v[80:81] offset0:8 offset1:12
	v_cvt_pk_bf16_f32 v60, v60, v61
	v_cvt_pk_bf16_f32 v61, v62, v63
	ds_write2_b64 v74, v[76:77], v[72:73] offset0:32 offset1:36
	v_cvt_pk_bf16_f32 v56, v56, v57
	v_cvt_pk_bf16_f32 v57, v58, v59
	ds_write2_b64 v74, v[68:69], v[60:61] offset0:40 offset1:44
	v_cvt_pk_bf16_f32 v52, v52, v53
	v_cvt_pk_bf16_f32 v53, v54, v55
	v_add_u32_e32 v54, 0x1000, v164
	v_cvt_pk_bf16_f32 v48, v48, v49
	v_cvt_pk_bf16_f32 v49, v50, v51
	ds_write2_b64 v54, v[56:57], v[52:53] offset0:64 offset1:68
	v_cvt_pk_bf16_f32 v44, v44, v45
	v_cvt_pk_bf16_f32 v45, v46, v47
	ds_write2_b64 v54, v[48:49], v[44:45] offset0:72 offset1:76
	v_cvt_pk_bf16_f32 v40, v40, v41
	v_cvt_pk_bf16_f32 v41, v42, v43
	v_cvt_pk_bf16_f32 v36, v36, v37
	v_cvt_pk_bf16_f32 v37, v38, v39
	v_add_u32_e32 v38, 0x1800, v164
	v_cvt_pk_bf16_f32 v32, v32, v33
	v_cvt_pk_bf16_f32 v33, v34, v35
	v_cvt_pk_bf16_f32 v28, v28, v29
	v_cvt_pk_bf16_f32 v29, v30, v31
	v_cvt_pk_bf16_f32 v24, v24, v25
	v_cvt_pk_bf16_f32 v25, v26, v27
	ds_write2_b64 v38, v[40:41], v[36:37] offset0:96 offset1:100
	v_cvt_pk_bf16_f32 v20, v20, v21
	v_cvt_pk_bf16_f32 v21, v22, v23
	v_add_u32_e32 v22, 0x2000, v164
	v_cvt_pk_bf16_f32 v16, v16, v17
	v_cvt_pk_bf16_f32 v17, v18, v19
	v_mov_b32_e32 v0, v64
	v_mov_b32_e32 v1, v65
	v_mov_b32_e32 v2, v66
	v_mov_b32_e32 v3, v67
	ds_write2_b64 v38, v[32:33], v[28:29] offset0:104 offset1:108
	s_nop 2
	v_cvt_pk_bf16_f32 v12, v12, v13
	v_cvt_pk_bf16_f32 v13, v14, v15
	ds_write2_b64 v22, v[24:25], v[20:21] offset0:128 offset1:132
	ds_write2_b64 v22, v[16:17], v[12:13] offset0:136 offset1:140
	v_cvt_pk_bf16_f32 v0, v0, v1
	v_cvt_pk_bf16_f32 v1, v2, v3
	ds_write2_b64 v6, v[4:5], v[0:1] offset0:168 offset1:172
	s_waitcnt lgkmcnt(0)
	v_or_b32_e32 v0, s31, v150
	v_add_u32_e32 v12, s30, v148
	v_lshlrev_b32_e32 v136, 1, v0
	ds_read_b128 v[0:3], v165
	v_or_b32_e32 v4, v12, v149
	v_ashrrev_i32_e32 v5, 31, v4
	v_lshl_add_u64 v[8:9], s[2:3], 0, v[136:137]
	v_lshlrev_b64 v[4:5], 11, v[4:5]
	v_lshl_add_u64 v[10:11], v[8:9], 0, v[4:5]
	ds_read_b128 v[4:7], v165 offset:1152
	s_waitcnt lgkmcnt(1)
	global_store_dwordx4 v[10:11], v[0:3], off
	s_nop 1
	v_or_b32_e32 v0, v12, v151
	v_ashrrev_i32_e32 v1, 31, v0
	v_lshlrev_b64 v[0:1], 11, v[0:1]
	v_lshl_add_u64 v[0:1], v[8:9], 0, v[0:1]
	s_waitcnt lgkmcnt(0)
	global_store_dwordx4 v[0:1], v[4:7], off
	ds_read_b128 v[0:3], v165 offset:2304
	s_nop 0
	v_or_b32_e32 v4, v12, v152
	v_ashrrev_i32_e32 v5, 31, v4
	v_lshlrev_b64 v[4:5], 11, v[4:5]
	v_lshl_add_u64 v[10:11], v[8:9], 0, v[4:5]
	ds_read_b128 v[4:7], v165 offset:3456
	s_waitcnt lgkmcnt(1)
	global_store_dwordx4 v[10:11], v[0:3], off
	s_nop 1
	v_or_b32_e32 v0, v12, v153
	v_ashrrev_i32_e32 v1, 31, v0
	v_lshlrev_b64 v[0:1], 11, v[0:1]
	v_lshl_add_u64 v[0:1], v[8:9], 0, v[0:1]
	s_waitcnt lgkmcnt(0)
	global_store_dwordx4 v[0:1], v[4:7], off
	ds_read_b128 v[0:3], v165 offset:4608
	s_nop 0
	v_add_u32_e32 v4, v12, v154
	v_ashrrev_i32_e32 v5, 31, v4
	v_lshlrev_b64 v[4:5], 11, v[4:5]
	v_lshl_add_u64 v[10:11], v[8:9], 0, v[4:5]
	ds_read_b128 v[4:7], v165 offset:5760
	s_waitcnt lgkmcnt(1)
	global_store_dwordx4 v[10:11], v[0:3], off
	s_nop 1
	v_add_u32_e32 v0, v12, v155
	v_ashrrev_i32_e32 v1, 31, v0
	v_lshlrev_b64 v[0:1], 11, v[0:1]
	v_lshl_add_u64 v[0:1], v[8:9], 0, v[0:1]
	s_waitcnt lgkmcnt(0)
	global_store_dwordx4 v[0:1], v[4:7], off
	ds_read_b128 v[0:3], v165 offset:6912
	s_nop 0
	v_add_u32_e32 v4, v12, v156
	v_ashrrev_i32_e32 v5, 31, v4
	v_lshlrev_b64 v[4:5], 11, v[4:5]
	v_lshl_add_u64 v[10:11], v[8:9], 0, v[4:5]
	ds_read_b128 v[4:7], v165 offset:8064
	s_waitcnt lgkmcnt(1)
	global_store_dwordx4 v[10:11], v[0:3], off
	s_nop 1
	v_add_u32_e32 v0, v12, v157
	v_ashrrev_i32_e32 v1, 31, v0
	v_lshlrev_b64 v[0:1], 11, v[0:1]
	v_lshl_add_u64 v[0:1], v[8:9], 0, v[0:1]
	s_waitcnt lgkmcnt(0)
	global_store_dwordx4 v[0:1], v[4:7], off
	ds_read_b128 v[0:3], v165 offset:9216
	s_nop 0
	v_add_u32_e32 v4, v12, v158
	v_ashrrev_i32_e32 v5, 31, v4
	v_lshlrev_b64 v[4:5], 11, v[4:5]
	v_lshl_add_u64 v[10:11], v[8:9], 0, v[4:5]
	ds_read_b128 v[4:7], v165 offset:10368
	s_waitcnt lgkmcnt(1)
	global_store_dwordx4 v[10:11], v[0:3], off
	s_nop 1
	v_add_u32_e32 v0, v12, v159
	v_ashrrev_i32_e32 v1, 31, v0
	v_lshlrev_b64 v[0:1], 11, v[0:1]
	v_lshl_add_u64 v[0:1], v[8:9], 0, v[0:1]
	s_waitcnt lgkmcnt(0)
	global_store_dwordx4 v[0:1], v[4:7], off
	ds_read_b128 v[0:3], v165 offset:11520
	s_nop 0
	v_add_u32_e32 v4, v12, v160
	v_ashrrev_i32_e32 v5, 31, v4
	v_lshlrev_b64 v[4:5], 11, v[4:5]
	v_lshl_add_u64 v[10:11], v[8:9], 0, v[4:5]
	ds_read_b128 v[4:7], v165 offset:12672
	s_waitcnt lgkmcnt(1)
	global_store_dwordx4 v[10:11], v[0:3], off
	s_nop 1
	v_add_u32_e32 v0, v12, v161
	v_ashrrev_i32_e32 v1, 31, v0
	v_lshlrev_b64 v[0:1], 11, v[0:1]
	v_lshl_add_u64 v[0:1], v[8:9], 0, v[0:1]
	s_waitcnt lgkmcnt(0)
	global_store_dwordx4 v[0:1], v[4:7], off
	s_cbranch_scc1 .LBB0_1118

.LBB0_1774:
	s_bfe_u32 s4, s14, 0x30005
	s_mul_i32 s9, s4, 0xc0
	s_lshl_b32 s4, s16, 12
	s_and_b32 s4, s4, 0x380000
	s_lshl_b32 s6, s13, 5
	v_lshl_add_u64 v[144:145], v[142:143], 0, s[4:5]
	s_lshl_b32 s4, s8, 8
	s_and_b32 s6, s6, 0xe0
	s_or_b32 s4, s6, s4
	s_mul_i32 s6, s4, 6
	s_ashr_i32 s7, s6, 31
	s_lshl_b64 s[34:35], s[6:7], 12
	v_lshl_add_u64 v[0:1], v[138:139], 0, s[34:35]
	v_add_co_u32_e32 v2, vcc, s18, v0
	s_lshl_b32 s4, s13, 4
	s_nop 0
	v_addc_co_u32_e32 v3, vcc, 0, v1, vcc
	s_nop 0
	v_readfirstlane_b32 s98, v0
	v_readfirstlane_b32 s99, v1
	v_add_co_u32_e32 v2, vcc, s19, v0
	s_and_b32 s33, s4, 0x380
	s_nop 0
	v_addc_co_u32_e32 v3, vcc, 0, v1, vcc
	v_add_co_u32_e32 v4, vcc, s20, v0
	s_lshl_b32 s4, s33, 12
	s_nop 0
	v_addc_co_u32_e32 v5, vcc, 0, v1, vcc
	v_add_co_u32_e32 v2, vcc, s21, v0
	v_mov_b32_e32 v64, 0
	s_nop 0
	v_addc_co_u32_e32 v3, vcc, 0, v1, vcc
	v_add_co_u32_e32 v0, vcc, 0xa0000, v0
	v_mov_b32_e32 v65, v137
	s_nop 0
	v_addc_co_u32_e32 v1, vcc, 0, v1, vcc
	v_lshl_add_u64 v[0:1], v[140:141], 0, s[4:5]
	v_add_co_u32_e32 v2, vcc, s18, v0
	s_mul_i32 s4, s8, 0x600
	s_nop 0
	v_addc_co_u32_e32 v3, vcc, 0, v1, vcc
	s_nop 0
	v_readfirstlane_b32 s100, v0
	v_readfirstlane_b32 s101, v1
	v_add_co_u32_e32 v2, vcc, 0x40000, v0
	s_add_i32 s8, s4, s9
	s_nop 0
	v_addc_co_u32_e32 v3, vcc, 0, v1, vcc
	v_add_co_u32_e32 v0, vcc, 0x60000, v0
	s_ashr_i32 s9, s8, 31
	s_nop 0
	v_addc_co_u32_e32 v1, vcc, 0, v1, vcc
	s_lshl_b64 s[8:9], s[8:9], 12
	v_lshl_add_u64 v[146:147], v[142:143], 0, s[8:9]
	s_mov_b64 s[8:9], 0
	v_mov_b32_e32 v66, v137
	v_mov_b32_e32 v67, v137
	v_mov_b32_e32 v0, 0
	v_mov_b32_e32 v1, v137
	v_mov_b32_e32 v2, v137
	v_mov_b32_e32 v3, v137
	v_mov_b32_e32 v4, 0
	v_mov_b32_e32 v5, v137
	v_mov_b32_e32 v6, v137
	v_mov_b32_e32 v7, v137
	v_mov_b32_e32 v8, 0
	v_mov_b32_e32 v9, v137
	v_mov_b32_e32 v10, v137
	v_mov_b32_e32 v11, v137
	v_mov_b32_e32 v12, 0
	v_mov_b32_e32 v13, v137
	v_mov_b32_e32 v14, v137
	v_mov_b32_e32 v15, v137
	v_mov_b32_e32 v16, 0
	v_mov_b32_e32 v17, v137
	v_mov_b32_e32 v18, v137
	v_mov_b32_e32 v19, v137
	v_mov_b32_e32 v20, 0
	v_mov_b32_e32 v21, v137
	v_mov_b32_e32 v22, v137
	v_mov_b32_e32 v23, v137
	v_mov_b32_e32 v24, 0
	v_mov_b32_e32 v25, v137
	v_mov_b32_e32 v26, v137
	v_mov_b32_e32 v27, v137
	v_mov_b32_e32 v28, 0
	v_mov_b32_e32 v29, v137
	v_mov_b32_e32 v30, v137
	v_mov_b32_e32 v31, v137
	v_mov_b32_e32 v32, 0
	v_mov_b32_e32 v33, v137
	v_mov_b32_e32 v34, v137
	v_mov_b32_e32 v35, v137
	s_waitcnt vmcnt(22)
	v_mov_b32_e32 v36, 0
	v_mov_b32_e32 v37, v137
	v_mov_b32_e32 v38, v137
	v_mov_b32_e32 v39, v137
	s_waitcnt vmcnt(21)
	v_mov_b32_e32 v40, 0
	v_mov_b32_e32 v41, v137
	v_mov_b32_e32 v42, v137
	v_mov_b32_e32 v43, v137
	s_waitcnt vmcnt(20)
	v_mov_b32_e32 v44, 0
	v_mov_b32_e32 v45, v137
	v_mov_b32_e32 v46, v137
	v_mov_b32_e32 v47, v137
	s_waitcnt vmcnt(19)
	v_mov_b32_e32 v48, 0
	v_mov_b32_e32 v49, v137
	v_mov_b32_e32 v50, v137
	v_mov_b32_e32 v51, v137
	s_waitcnt vmcnt(18)
	v_mov_b32_e32 v52, 0
	v_mov_b32_e32 v53, v137
	v_mov_b32_e32 v54, v137
	v_mov_b32_e32 v55, v137
	v_mov_b32_e32 v56, 0
	v_mov_b32_e32 v57, v137
	v_mov_b32_e32 v58, v137
	v_mov_b32_e32 v59, v137
	v_mov_b32_e32 v60, 0
	v_mov_b32_e32 v61, v137
	v_mov_b32_e32 v62, v137
	v_mov_b32_e32 v63, v137
	v_mov_b32_e32 v68, 0
	v_mov_b32_e32 v69, v137
	v_mov_b32_e32 v70, v137
	v_mov_b32_e32 v71, v137
	v_mov_b32_e32 v72, 0
	v_mov_b32_e32 v73, v137
	v_mov_b32_e32 v74, v137
	v_mov_b32_e32 v75, v137
	v_mov_b32_e32 v76, 0
	v_mov_b32_e32 v77, v137
	v_mov_b32_e32 v78, v137
	v_mov_b32_e32 v79, v137
	v_mov_b32_e32 v80, 0
	v_mov_b32_e32 v81, v137
	v_mov_b32_e32 v82, v137
	v_mov_b32_e32 v83, v137
	v_mov_b32_e32 v84, 0
	v_mov_b32_e32 v85, v137
	v_mov_b32_e32 v86, v137
	v_mov_b32_e32 v87, v137
	v_mov_b32_e32 v88, 0
	v_mov_b32_e32 v89, v137
	v_mov_b32_e32 v90, v137
	v_mov_b32_e32 v91, v137
	v_mov_b32_e32 v92, 0
	v_mov_b32_e32 v93, v137
	v_mov_b32_e32 v94, v137
	v_mov_b32_e32 v95, v137
	v_and_b32_e32 v197, 63, v196
	v_lshrrev_b32_e32 v198, 3, v197
	v_and_b32_e32 v199, 7, v197
	v_xor_b32_e32 v199, v199, v198
	v_lshlrev_b32_e32 v199, 4, v199
	v_mul_u32_u24_e32 v198, 4096, v198
	v_add_u32_e32 v240, v198, v199
	v_add_u32_e32 v241, 131072, v240
	v_add_u32_e32 v242, 262144, v240
	v_add_u32_e32 v243, 393216, v240
	v_add_u32_e32 v244, 524288, v240
	v_add_u32_e32 v245, 655360, v240
	v_lshrrev_b32_e32 v198, 6, v196
	v_lshrrev_b32_e32 v199, 1, v198
	v_and_b32_e32 v198, 1, v198
	v_and_b32_e32 v190, 15, v197
	v_lshrrev_b32_e32 v191, 4, v197
	v_and_b32_e32 v192, 7, v190
	v_xor_b32_e32 v191, v191, v192
	v_lshlrev_b32_e32 v191, 4, v191
	v_mul_u32_u24_e32 v199, 0x60, v199
	v_add_u32_e32 v199, v199, v190
	v_lshl_add_u32 v246, v199, 7, v191
	v_xor_b32_e32 v247, 64, v246
	v_lshlrev_b32_e32 v198, 6, v198
	v_add_u32_e32 v198, v198, v190
	v_lshl_add_u32 v248, v198, 7, v191
	v_add_u32_e32 v248, 0x6000, v248
	v_xor_b32_e32 v249, 64, v248
	v_lshrrev_b32_e32 v198, 6, v196
	v_lshlrev_b32_e32 v198, 10, v198
	s_nop 0
	v_readfirstlane_b32 s8, v198
	s_mov_b32 s9, 15
	s_waitcnt lgkmcnt(0)
	s_barrier
	s_add_u32 m0, s8, 0
	s_nop 0
	global_load_lds_dwordx4 v240, s[98:99]
	s_add_u32 m0, s8, 4096
	s_nop 0
	global_load_lds_dwordx4 v241, s[98:99]
	s_add_u32 m0, s8, 8192
	s_nop 0
	global_load_lds_dwordx4 v242, s[98:99]
	s_add_u32 m0, s8, 12288
	s_nop 0
	global_load_lds_dwordx4 v243, s[98:99]
	s_add_u32 m0, s8, 16384
	s_nop 0
	global_load_lds_dwordx4 v244, s[98:99]
	s_add_u32 m0, s8, 20480
	s_nop 0
	global_load_lds_dwordx4 v245, s[98:99]
	s_add_u32 m0, s8, 24576
	s_nop 0
	global_load_lds_dwordx4 v240, s[100:101]
	s_add_u32 m0, s8, 28672
	s_nop 0
	global_load_lds_dwordx4 v241, s[100:101]
	s_add_u32 m0, s8, 32768
	s_nop 0
	global_load_lds_dwordx4 v242, s[100:101]
	s_add_u32 m0, s8, 36864
	s_nop 0
	global_load_lds_dwordx4 v243, s[100:101]
	s_add_u32 s98, s98, 0x80
	s_addc_u32 s99, s99, 0
	s_add_u32 s100, s100, 0x80
	s_addc_u32 s101, s101, 0
	s_waitcnt vmcnt(0)
	s_barrier
	ds_read_b128 v[120:123], v248 offset:0
	ds_read_b128 v[124:127], v248 offset:2048
	ds_read_b128 v[128:131], v248 offset:4096
	ds_read_b128 v[132:135], v248 offset:6144
	ds_read_b128 v[96:99], v246 offset:0
	ds_read_b128 v[100:103], v246 offset:2048
	ds_read_b128 v[104:107], v246 offset:4096
	ds_read_b128 v[108:111], v246 offset:6144
	ds_read_b128 v[112:115], v246 offset:8192
	ds_read_b128 v[116:119], v246 offset:10240
	s_add_u32 m0, s8, 40960
	s_nop 0
	global_load_lds_dwordx4 v240, s[98:99]
	s_add_u32 m0, s8, 45056
	s_nop 0
	global_load_lds_dwordx4 v241, s[98:99]
	s_add_u32 m0, s8, 49152
	s_nop 0
	global_load_lds_dwordx4 v242, s[98:99]
	s_add_u32 m0, s8, 53248
	s_nop 0
	global_load_lds_dwordx4 v243, s[98:99]
	s_add_u32 m0, s8, 57344
	s_nop 0
	global_load_lds_dwordx4 v244, s[98:99]
	s_add_u32 m0, s8, 61440
	s_nop 0
	global_load_lds_dwordx4 v245, s[98:99]
	s_add_u32 m0, s8, 65536
	s_nop 0
	global_load_lds_dwordx4 v240, s[100:101]
	s_add_u32 m0, s8, 69632
	s_nop 0
	global_load_lds_dwordx4 v241, s[100:101]
	s_add_u32 m0, s8, 73728
	s_nop 0
	global_load_lds_dwordx4 v242, s[100:101]
	s_add_u32 m0, s8, 77824
	s_nop 0
	global_load_lds_dwordx4 v243, s[100:101]
	s_add_u32 s98, s98, 0x80
	s_addc_u32 s99, s99, 0
	s_add_u32 s100, s100, 0x80
	s_addc_u32 s101, s101, 0
	s_waitcnt lgkmcnt(0)
	v_mfma_f32_16x16x32_bf16 v[92:95], v[120:123], v[96:99], v[92:95]
	v_mfma_f32_16x16x32_bf16 v[88:91], v[124:127], v[96:99], v[88:91]
	ds_read_b128 v[224:227], v249 offset:0
	v_mfma_f32_16x16x32_bf16 v[84:87], v[128:131], v[96:99], v[84:87]
	v_mfma_f32_16x16x32_bf16 v[80:83], v[132:135], v[96:99], v[80:83]
	ds_read_b128 v[228:231], v249 offset:2048
	v_mfma_f32_16x16x32_bf16 v[76:79], v[120:123], v[100:103], v[76:79]
	v_mfma_f32_16x16x32_bf16 v[72:75], v[124:127], v[100:103], v[72:75]
	ds_read_b128 v[232:235], v249 offset:4096
	v_mfma_f32_16x16x32_bf16 v[68:71], v[128:131], v[100:103], v[68:71]
	v_mfma_f32_16x16x32_bf16 v[60:63], v[132:135], v[100:103], v[60:63]
	ds_read_b128 v[236:239], v249 offset:6144
	v_mfma_f32_16x16x32_bf16 v[56:59], v[120:123], v[104:107], v[56:59]
	v_mfma_f32_16x16x32_bf16 v[52:55], v[124:127], v[104:107], v[52:55]
	ds_read_b128 v[200:203], v247 offset:0
	v_mfma_f32_16x16x32_bf16 v[48:51], v[128:131], v[104:107], v[48:51]
	v_mfma_f32_16x16x32_bf16 v[44:47], v[132:135], v[104:107], v[44:47]
	ds_read_b128 v[204:207], v247 offset:2048
	v_mfma_f32_16x16x32_bf16 v[40:43], v[120:123], v[108:111], v[40:43]
	v_mfma_f32_16x16x32_bf16 v[36:39], v[124:127], v[108:111], v[36:39]
	ds_read_b128 v[208:211], v247 offset:4096
	v_mfma_f32_16x16x32_bf16 v[32:35], v[128:131], v[108:111], v[32:35]
	v_mfma_f32_16x16x32_bf16 v[28:31], v[132:135], v[108:111], v[28:31]
	ds_read_b128 v[212:215], v247 offset:6144
	v_mfma_f32_16x16x32_bf16 v[24:27], v[120:123], v[112:115], v[24:27]
	v_mfma_f32_16x16x32_bf16 v[20:23], v[124:127], v[112:115], v[20:23]
	ds_read_b128 v[216:219], v247 offset:8192
	v_mfma_f32_16x16x32_bf16 v[16:19], v[128:131], v[112:115], v[16:19]
	v_mfma_f32_16x16x32_bf16 v[12:15], v[132:135], v[112:115], v[12:15]
	ds_read_b128 v[220:223], v247 offset:10240
	v_mfma_f32_16x16x32_bf16 v[8:11], v[120:123], v[116:119], v[8:11]
	v_mfma_f32_16x16x32_bf16 v[4:7], v[124:127], v[116:119], v[4:7]
	v_mfma_f32_16x16x32_bf16 v[0:3], v[128:131], v[116:119], v[0:3]
	v_mfma_f32_16x16x32_bf16 v[64:67], v[132:135], v[116:119], v[64:67]
.Lg6p13_loop:
	s_waitcnt vmcnt(0) lgkmcnt(0)
	s_barrier
	ds_read_b128 v[120:123], v248 offset:40960
	ds_read_b128 v[124:127], v248 offset:43008
	ds_read_b128 v[128:131], v248 offset:45056
	ds_read_b128 v[132:135], v248 offset:47104
	ds_read_b128 v[96:99], v246 offset:40960
	ds_read_b128 v[100:103], v246 offset:43008
	ds_read_b128 v[104:107], v246 offset:45056
	ds_read_b128 v[108:111], v246 offset:47104
	ds_read_b128 v[112:115], v246 offset:49152
	ds_read_b128 v[116:119], v246 offset:51200
	s_add_u32 m0, s8, 0
	v_mfma_f32_16x16x32_bf16 v[92:95], v[224:227], v[200:203], v[92:95]
	global_load_lds_dwordx4 v240, s[98:99]
	v_mfma_f32_16x16x32_bf16 v[88:91], v[228:231], v[200:203], v[88:91]
	s_add_u32 m0, s8, 4096
	v_mfma_f32_16x16x32_bf16 v[84:87], v[232:235], v[200:203], v[84:87]
	global_load_lds_dwordx4 v241, s[98:99]
	v_mfma_f32_16x16x32_bf16 v[80:83], v[236:239], v[200:203], v[80:83]
	s_add_u32 m0, s8, 8192
	v_mfma_f32_16x16x32_bf16 v[76:79], v[224:227], v[204:207], v[76:79]
	global_load_lds_dwordx4 v242, s[98:99]
	v_mfma_f32_16x16x32_bf16 v[72:75], v[228:231], v[204:207], v[72:75]
	s_add_u32 m0, s8, 12288
	v_mfma_f32_16x16x32_bf16 v[68:71], v[232:235], v[204:207], v[68:71]
	global_load_lds_dwordx4 v243, s[98:99]
	v_mfma_f32_16x16x32_bf16 v[60:63], v[236:239], v[204:207], v[60:63]
	s_add_u32 m0, s8, 16384
	v_mfma_f32_16x16x32_bf16 v[56:59], v[224:227], v[208:211], v[56:59]
	global_load_lds_dwordx4 v244, s[98:99]
	v_mfma_f32_16x16x32_bf16 v[52:55], v[228:231], v[208:211], v[52:55]
	s_add_u32 m0, s8, 20480
	v_mfma_f32_16x16x32_bf16 v[48:51], v[232:235], v[208:211], v[48:51]
	global_load_lds_dwordx4 v245, s[98:99]
	v_mfma_f32_16x16x32_bf16 v[44:47], v[236:239], v[208:211], v[44:47]
	s_add_u32 m0, s8, 24576
	v_mfma_f32_16x16x32_bf16 v[40:43], v[224:227], v[212:215], v[40:43]
	global_load_lds_dwordx4 v240, s[100:101]
	v_mfma_f32_16x16x32_bf16 v[36:39], v[228:231], v[212:215], v[36:39]
	s_add_u32 m0, s8, 28672
	v_mfma_f32_16x16x32_bf16 v[32:35], v[232:235], v[212:215], v[32:35]
	global_load_lds_dwordx4 v241, s[100:101]
	v_mfma_f32_16x16x32_bf16 v[28:31], v[236:239], v[212:215], v[28:31]
	s_add_u32 m0, s8, 32768
	v_mfma_f32_16x16x32_bf16 v[24:27], v[224:227], v[216:219], v[24:27]
	global_load_lds_dwordx4 v242, s[100:101]
	v_mfma_f32_16x16x32_bf16 v[20:23], v[228:231], v[216:219], v[20:23]
	s_add_u32 m0, s8, 36864
	v_mfma_f32_16x16x32_bf16 v[16:19], v[232:235], v[216:219], v[16:19]
	global_load_lds_dwordx4 v243, s[100:101]
	v_mfma_f32_16x16x32_bf16 v[12:15], v[236:239], v[216:219], v[12:15]
	v_mfma_f32_16x16x32_bf16 v[8:11], v[224:227], v[220:223], v[8:11]
	v_mfma_f32_16x16x32_bf16 v[4:7], v[228:231], v[220:223], v[4:7]
	v_mfma_f32_16x16x32_bf16 v[0:3], v[232:235], v[220:223], v[0:3]
	v_mfma_f32_16x16x32_bf16 v[64:67], v[236:239], v[220:223], v[64:67]
	s_add_u32 s98, s98, 0x80
	s_addc_u32 s99, s99, 0
	s_add_u32 s100, s100, 0x80
	s_addc_u32 s101, s101, 0
	s_waitcnt lgkmcnt(0)
	v_mfma_f32_16x16x32_bf16 v[92:95], v[120:123], v[96:99], v[92:95]
	v_mfma_f32_16x16x32_bf16 v[88:91], v[124:127], v[96:99], v[88:91]
	ds_read_b128 v[224:227], v249 offset:40960
	v_mfma_f32_16x16x32_bf16 v[84:87], v[128:131], v[96:99], v[84:87]
	v_mfma_f32_16x16x32_bf16 v[80:83], v[132:135], v[96:99], v[80:83]
	ds_read_b128 v[228:231], v249 offset:43008
	v_mfma_f32_16x16x32_bf16 v[76:79], v[120:123], v[100:103], v[76:79]
	v_mfma_f32_16x16x32_bf16 v[72:75], v[124:127], v[100:103], v[72:75]
	ds_read_b128 v[232:235], v249 offset:45056
	v_mfma_f32_16x16x32_bf16 v[68:71], v[128:131], v[100:103], v[68:71]
	v_mfma_f32_16x16x32_bf16 v[60:63], v[132:135], v[100:103], v[60:63]
	ds_read_b128 v[236:239], v249 offset:47104
	v_mfma_f32_16x16x32_bf16 v[56:59], v[120:123], v[104:107], v[56:59]
	v_mfma_f32_16x16x32_bf16 v[52:55], v[124:127], v[104:107], v[52:55]
	ds_read_b128 v[200:203], v247 offset:40960
	v_mfma_f32_16x16x32_bf16 v[48:51], v[128:131], v[104:107], v[48:51]
	v_mfma_f32_16x16x32_bf16 v[44:47], v[132:135], v[104:107], v[44:47]
	ds_read_b128 v[204:207], v247 offset:43008
	v_mfma_f32_16x16x32_bf16 v[40:43], v[120:123], v[108:111], v[40:43]
	v_mfma_f32_16x16x32_bf16 v[36:39], v[124:127], v[108:111], v[36:39]
	ds_read_b128 v[208:211], v247 offset:45056
	v_mfma_f32_16x16x32_bf16 v[32:35], v[128:131], v[108:111], v[32:35]
	v_mfma_f32_16x16x32_bf16 v[28:31], v[132:135], v[108:111], v[28:31]
	ds_read_b128 v[212:215], v247 offset:47104
	v_mfma_f32_16x16x32_bf16 v[24:27], v[120:123], v[112:115], v[24:27]
	v_mfma_f32_16x16x32_bf16 v[20:23], v[124:127], v[112:115], v[20:23]
	ds_read_b128 v[216:219], v247 offset:49152
	v_mfma_f32_16x16x32_bf16 v[16:19], v[128:131], v[112:115], v[16:19]
	v_mfma_f32_16x16x32_bf16 v[12:15], v[132:135], v[112:115], v[12:15]
	ds_read_b128 v[220:223], v247 offset:51200
	v_mfma_f32_16x16x32_bf16 v[8:11], v[120:123], v[116:119], v[8:11]
	v_mfma_f32_16x16x32_bf16 v[4:7], v[124:127], v[116:119], v[4:7]
	v_mfma_f32_16x16x32_bf16 v[0:3], v[128:131], v[116:119], v[0:3]
	v_mfma_f32_16x16x32_bf16 v[64:67], v[132:135], v[116:119], v[64:67]
	s_waitcnt vmcnt(0) lgkmcnt(0)
	s_barrier
	ds_read_b128 v[120:123], v248 offset:0
	ds_read_b128 v[124:127], v248 offset:2048
	ds_read_b128 v[128:131], v248 offset:4096
	ds_read_b128 v[132:135], v248 offset:6144
	ds_read_b128 v[96:99], v246 offset:0
	ds_read_b128 v[100:103], v246 offset:2048
	ds_read_b128 v[104:107], v246 offset:4096
	ds_read_b128 v[108:111], v246 offset:6144
	ds_read_b128 v[112:115], v246 offset:8192
	ds_read_b128 v[116:119], v246 offset:10240
	s_add_u32 m0, s8, 40960
	v_mfma_f32_16x16x32_bf16 v[92:95], v[224:227], v[200:203], v[92:95]
	global_load_lds_dwordx4 v240, s[98:99]
	v_mfma_f32_16x16x32_bf16 v[88:91], v[228:231], v[200:203], v[88:91]
	s_add_u32 m0, s8, 45056
	v_mfma_f32_16x16x32_bf16 v[84:87], v[232:235], v[200:203], v[84:87]
	global_load_lds_dwordx4 v241, s[98:99]
	v_mfma_f32_16x16x32_bf16 v[80:83], v[236:239], v[200:203], v[80:83]
	s_add_u32 m0, s8, 49152
	v_mfma_f32_16x16x32_bf16 v[76:79], v[224:227], v[204:207], v[76:79]
	global_load_lds_dwordx4 v242, s[98:99]
	v_mfma_f32_16x16x32_bf16 v[72:75], v[228:231], v[204:207], v[72:75]
	s_add_u32 m0, s8, 53248
	v_mfma_f32_16x16x32_bf16 v[68:71], v[232:235], v[204:207], v[68:71]
	global_load_lds_dwordx4 v243, s[98:99]
	v_mfma_f32_16x16x32_bf16 v[60:63], v[236:239], v[204:207], v[60:63]
	s_add_u32 m0, s8, 57344
	v_mfma_f32_16x16x32_bf16 v[56:59], v[224:227], v[208:211], v[56:59]
	global_load_lds_dwordx4 v244, s[98:99]
	v_mfma_f32_16x16x32_bf16 v[52:55], v[228:231], v[208:211], v[52:55]
	s_add_u32 m0, s8, 61440
	v_mfma_f32_16x16x32_bf16 v[48:51], v[232:235], v[208:211], v[48:51]
	global_load_lds_dwordx4 v245, s[98:99]
	v_mfma_f32_16x16x32_bf16 v[44:47], v[236:239], v[208:211], v[44:47]
	s_add_u32 m0, s8, 65536
	v_mfma_f32_16x16x32_bf16 v[40:43], v[224:227], v[212:215], v[40:43]
	global_load_lds_dwordx4 v240, s[100:101]
	v_mfma_f32_16x16x32_bf16 v[36:39], v[228:231], v[212:215], v[36:39]
	s_add_u32 m0, s8, 69632
	v_mfma_f32_16x16x32_bf16 v[32:35], v[232:235], v[212:215], v[32:35]
	global_load_lds_dwordx4 v241, s[100:101]
	v_mfma_f32_16x16x32_bf16 v[28:31], v[236:239], v[212:215], v[28:31]
	s_add_u32 m0, s8, 73728
	v_mfma_f32_16x16x32_bf16 v[24:27], v[224:227], v[216:219], v[24:27]
	global_load_lds_dwordx4 v242, s[100:101]
	v_mfma_f32_16x16x32_bf16 v[20:23], v[228:231], v[216:219], v[20:23]
	s_add_u32 m0, s8, 77824
	v_mfma_f32_16x16x32_bf16 v[16:19], v[232:235], v[216:219], v[16:19]
	global_load_lds_dwordx4 v243, s[100:101]
	v_mfma_f32_16x16x32_bf16 v[12:15], v[236:239], v[216:219], v[12:15]
	v_mfma_f32_16x16x32_bf16 v[8:11], v[224:227], v[220:223], v[8:11]
	v_mfma_f32_16x16x32_bf16 v[4:7], v[228:231], v[220:223], v[4:7]
	v_mfma_f32_16x16x32_bf16 v[0:3], v[232:235], v[220:223], v[0:3]
	v_mfma_f32_16x16x32_bf16 v[64:67], v[236:239], v[220:223], v[64:67]
	s_add_u32 s98, s98, 0x80
	s_addc_u32 s99, s99, 0
	s_add_u32 s100, s100, 0x80
	s_addc_u32 s101, s101, 0
	s_waitcnt lgkmcnt(0)
	v_mfma_f32_16x16x32_bf16 v[92:95], v[120:123], v[96:99], v[92:95]
	v_mfma_f32_16x16x32_bf16 v[88:91], v[124:127], v[96:99], v[88:91]
	ds_read_b128 v[224:227], v249 offset:0
	v_mfma_f32_16x16x32_bf16 v[84:87], v[128:131], v[96:99], v[84:87]
	v_mfma_f32_16x16x32_bf16 v[80:83], v[132:135], v[96:99], v[80:83]
	ds_read_b128 v[228:231], v249 offset:2048
	v_mfma_f32_16x16x32_bf16 v[76:79], v[120:123], v[100:103], v[76:79]
	v_mfma_f32_16x16x32_bf16 v[72:75], v[124:127], v[100:103], v[72:75]
	ds_read_b128 v[232:235], v249 offset:4096
	v_mfma_f32_16x16x32_bf16 v[68:71], v[128:131], v[100:103], v[68:71]
	v_mfma_f32_16x16x32_bf16 v[60:63], v[132:135], v[100:103], v[60:63]
	ds_read_b128 v[236:239], v249 offset:6144
	v_mfma_f32_16x16x32_bf16 v[56:59], v[120:123], v[104:107], v[56:59]
	v_mfma_f32_16x16x32_bf16 v[52:55], v[124:127], v[104:107], v[52:55]
	ds_read_b128 v[200:203], v247 offset:0
	v_mfma_f32_16x16x32_bf16 v[48:51], v[128:131], v[104:107], v[48:51]
	v_mfma_f32_16x16x32_bf16 v[44:47], v[132:135], v[104:107], v[44:47]
	ds_read_b128 v[204:207], v247 offset:2048
	v_mfma_f32_16x16x32_bf16 v[40:43], v[120:123], v[108:111], v[40:43]
	v_mfma_f32_16x16x32_bf16 v[36:39], v[124:127], v[108:111], v[36:39]
	ds_read_b128 v[208:211], v247 offset:4096
	v_mfma_f32_16x16x32_bf16 v[32:35], v[128:131], v[108:111], v[32:35]
	v_mfma_f32_16x16x32_bf16 v[28:31], v[132:135], v[108:111], v[28:31]
	ds_read_b128 v[212:215], v247 offset:6144
	v_mfma_f32_16x16x32_bf16 v[24:27], v[120:123], v[112:115], v[24:27]
	v_mfma_f32_16x16x32_bf16 v[20:23], v[124:127], v[112:115], v[20:23]
	ds_read_b128 v[216:219], v247 offset:8192
	v_mfma_f32_16x16x32_bf16 v[16:19], v[128:131], v[112:115], v[16:19]
	v_mfma_f32_16x16x32_bf16 v[12:15], v[132:135], v[112:115], v[12:15]
	ds_read_b128 v[220:223], v247 offset:10240
	v_mfma_f32_16x16x32_bf16 v[8:11], v[120:123], v[116:119], v[8:11]
	v_mfma_f32_16x16x32_bf16 v[4:7], v[124:127], v[116:119], v[4:7]
	v_mfma_f32_16x16x32_bf16 v[0:3], v[128:131], v[116:119], v[0:3]
	v_mfma_f32_16x16x32_bf16 v[64:67], v[132:135], v[116:119], v[64:67]
	s_sub_u32 s9, s9, 1
	s_cmp_lg_u32 s9, 0
	s_cbranch_scc1 .Lg6p13_loop
	s_waitcnt vmcnt(0) lgkmcnt(0)
	s_barrier
	ds_read_b128 v[120:123], v248 offset:40960
	ds_read_b128 v[124:127], v248 offset:43008
	ds_read_b128 v[128:131], v248 offset:45056
	ds_read_b128 v[132:135], v248 offset:47104
	ds_read_b128 v[96:99], v246 offset:40960
	ds_read_b128 v[100:103], v246 offset:43008
	ds_read_b128 v[104:107], v246 offset:45056
	ds_read_b128 v[108:111], v246 offset:47104
	ds_read_b128 v[112:115], v246 offset:49152
	ds_read_b128 v[116:119], v246 offset:51200
	v_mfma_f32_16x16x32_bf16 v[92:95], v[224:227], v[200:203], v[92:95]
	v_mfma_f32_16x16x32_bf16 v[88:91], v[228:231], v[200:203], v[88:91]
	v_mfma_f32_16x16x32_bf16 v[84:87], v[232:235], v[200:203], v[84:87]
	v_mfma_f32_16x16x32_bf16 v[80:83], v[236:239], v[200:203], v[80:83]
	v_mfma_f32_16x16x32_bf16 v[76:79], v[224:227], v[204:207], v[76:79]
	v_mfma_f32_16x16x32_bf16 v[72:75], v[228:231], v[204:207], v[72:75]
	v_mfma_f32_16x16x32_bf16 v[68:71], v[232:235], v[204:207], v[68:71]
	v_mfma_f32_16x16x32_bf16 v[60:63], v[236:239], v[204:207], v[60:63]
	v_mfma_f32_16x16x32_bf16 v[56:59], v[224:227], v[208:211], v[56:59]
	v_mfma_f32_16x16x32_bf16 v[52:55], v[228:231], v[208:211], v[52:55]
	v_mfma_f32_16x16x32_bf16 v[48:51], v[232:235], v[208:211], v[48:51]
	v_mfma_f32_16x16x32_bf16 v[44:47], v[236:239], v[208:211], v[44:47]
	v_mfma_f32_16x16x32_bf16 v[40:43], v[224:227], v[212:215], v[40:43]
	v_mfma_f32_16x16x32_bf16 v[36:39], v[228:231], v[212:215], v[36:39]
	v_mfma_f32_16x16x32_bf16 v[32:35], v[232:235], v[212:215], v[32:35]
	v_mfma_f32_16x16x32_bf16 v[28:31], v[236:239], v[212:215], v[28:31]
	v_mfma_f32_16x16x32_bf16 v[24:27], v[224:227], v[216:219], v[24:27]
	v_mfma_f32_16x16x32_bf16 v[20:23], v[228:231], v[216:219], v[20:23]
	v_mfma_f32_16x16x32_bf16 v[16:19], v[232:235], v[216:219], v[16:19]
	v_mfma_f32_16x16x32_bf16 v[12:15], v[236:239], v[216:219], v[12:15]
	v_mfma_f32_16x16x32_bf16 v[8:11], v[224:227], v[220:223], v[8:11]
	v_mfma_f32_16x16x32_bf16 v[4:7], v[228:231], v[220:223], v[4:7]
	v_mfma_f32_16x16x32_bf16 v[0:3], v[232:235], v[220:223], v[0:3]
	v_mfma_f32_16x16x32_bf16 v[64:67], v[236:239], v[220:223], v[64:67]
	s_waitcnt lgkmcnt(0)
	v_mfma_f32_16x16x32_bf16 v[92:95], v[120:123], v[96:99], v[92:95]
	v_mfma_f32_16x16x32_bf16 v[88:91], v[124:127], v[96:99], v[88:91]
	ds_read_b128 v[224:227], v249 offset:40960
	v_mfma_f32_16x16x32_bf16 v[84:87], v[128:131], v[96:99], v[84:87]
	v_mfma_f32_16x16x32_bf16 v[80:83], v[132:135], v[96:99], v[80:83]
	ds_read_b128 v[228:231], v249 offset:43008
	v_mfma_f32_16x16x32_bf16 v[76:79], v[120:123], v[100:103], v[76:79]
	v_mfma_f32_16x16x32_bf16 v[72:75], v[124:127], v[100:103], v[72:75]
	ds_read_b128 v[232:235], v249 offset:45056
	v_mfma_f32_16x16x32_bf16 v[68:71], v[128:131], v[100:103], v[68:71]
	v_mfma_f32_16x16x32_bf16 v[60:63], v[132:135], v[100:103], v[60:63]
	ds_read_b128 v[236:239], v249 offset:47104
	v_mfma_f32_16x16x32_bf16 v[56:59], v[120:123], v[104:107], v[56:59]
	v_mfma_f32_16x16x32_bf16 v[52:55], v[124:127], v[104:107], v[52:55]
	ds_read_b128 v[200:203], v247 offset:40960
	v_mfma_f32_16x16x32_bf16 v[48:51], v[128:131], v[104:107], v[48:51]
	v_mfma_f32_16x16x32_bf16 v[44:47], v[132:135], v[104:107], v[44:47]
	ds_read_b128 v[204:207], v247 offset:43008
	v_mfma_f32_16x16x32_bf16 v[40:43], v[120:123], v[108:111], v[40:43]
	v_mfma_f32_16x16x32_bf16 v[36:39], v[124:127], v[108:111], v[36:39]
	ds_read_b128 v[208:211], v247 offset:45056
	v_mfma_f32_16x16x32_bf16 v[32:35], v[128:131], v[108:111], v[32:35]
	v_mfma_f32_16x16x32_bf16 v[28:31], v[132:135], v[108:111], v[28:31]
	ds_read_b128 v[212:215], v247 offset:47104
	v_mfma_f32_16x16x32_bf16 v[24:27], v[120:123], v[112:115], v[24:27]
	v_mfma_f32_16x16x32_bf16 v[20:23], v[124:127], v[112:115], v[20:23]
	ds_read_b128 v[216:219], v247 offset:49152
	v_mfma_f32_16x16x32_bf16 v[16:19], v[128:131], v[112:115], v[16:19]
	v_mfma_f32_16x16x32_bf16 v[12:15], v[132:135], v[112:115], v[12:15]
	ds_read_b128 v[220:223], v247 offset:51200
	v_mfma_f32_16x16x32_bf16 v[8:11], v[120:123], v[116:119], v[8:11]
	v_mfma_f32_16x16x32_bf16 v[4:7], v[124:127], v[116:119], v[4:7]
	v_mfma_f32_16x16x32_bf16 v[0:3], v[128:131], v[116:119], v[0:3]
	v_mfma_f32_16x16x32_bf16 v[64:67], v[132:135], v[116:119], v[64:67]
	s_waitcnt lgkmcnt(0)
	v_mfma_f32_16x16x32_bf16 v[92:95], v[224:227], v[200:203], v[92:95]
	v_mfma_f32_16x16x32_bf16 v[88:91], v[228:231], v[200:203], v[88:91]
	v_mfma_f32_16x16x32_bf16 v[84:87], v[232:235], v[200:203], v[84:87]
	v_mfma_f32_16x16x32_bf16 v[80:83], v[236:239], v[200:203], v[80:83]
	v_mfma_f32_16x16x32_bf16 v[76:79], v[224:227], v[204:207], v[76:79]
	v_mfma_f32_16x16x32_bf16 v[72:75], v[228:231], v[204:207], v[72:75]
	v_mfma_f32_16x16x32_bf16 v[68:71], v[232:235], v[204:207], v[68:71]
	v_mfma_f32_16x16x32_bf16 v[60:63], v[236:239], v[204:207], v[60:63]
	v_mfma_f32_16x16x32_bf16 v[56:59], v[224:227], v[208:211], v[56:59]
	v_mfma_f32_16x16x32_bf16 v[52:55], v[228:231], v[208:211], v[52:55]
	v_mfma_f32_16x16x32_bf16 v[48:51], v[232:235], v[208:211], v[48:51]
	v_mfma_f32_16x16x32_bf16 v[44:47], v[236:239], v[208:211], v[44:47]
	v_mfma_f32_16x16x32_bf16 v[40:43], v[224:227], v[212:215], v[40:43]
	v_mfma_f32_16x16x32_bf16 v[36:39], v[228:231], v[212:215], v[36:39]
	v_mfma_f32_16x16x32_bf16 v[32:35], v[232:235], v[212:215], v[32:35]
	v_mfma_f32_16x16x32_bf16 v[28:31], v[236:239], v[212:215], v[28:31]
	v_mfma_f32_16x16x32_bf16 v[24:27], v[224:227], v[216:219], v[24:27]
	v_mfma_f32_16x16x32_bf16 v[20:23], v[228:231], v[216:219], v[20:23]
	v_mfma_f32_16x16x32_bf16 v[16:19], v[232:235], v[216:219], v[16:19]
	v_mfma_f32_16x16x32_bf16 v[12:15], v[236:239], v[216:219], v[12:15]
	v_mfma_f32_16x16x32_bf16 v[8:11], v[224:227], v[220:223], v[8:11]
	v_mfma_f32_16x16x32_bf16 v[4:7], v[228:231], v[220:223], v[4:7]
	v_mfma_f32_16x16x32_bf16 v[0:3], v[232:235], v[220:223], v[0:3]
	v_mfma_f32_16x16x32_bf16 v[64:67], v[236:239], v[220:223], v[64:67]
	s_nop 7
	s_nop 7
	s_barrier
	ds_write_b64 v252, v[250:251]
	s_add_i32 s13, s13, s12
	s_ashr_i32 s4, s13, 6
	s_mul_i32 s4, s4, s11
	s_add_i32 s8, s4, s10
	s_add_i32 s14, s14, s15
	s_add_i32 s16, s16, s17
	s_cmp_lt_i32 s8, 8
	v_cvt_pk_bf16_f32 v8, v8, v9
	v_cvt_pk_bf16_f32 v9, v10, v11
	v_cvt_pk_bf16_f32 v4, v4, v5
	v_cvt_pk_bf16_f32 v5, v6, v7
	v_add_u32_e32 v6, 0x2800, v162
	ds_write2_b64 v6, v[8:9], v[4:5] offset0:160 offset1:164
	v_cvt_pk_bf16_f32 v4, v0, v1
	v_cvt_pk_bf16_f32 v5, v2, v3
	v_cvt_pk_bf16_f32 v92, v92, v93
	v_cvt_pk_bf16_f32 v93, v94, v95
	v_cvt_pk_bf16_f32 v88, v88, v89
	v_cvt_pk_bf16_f32 v89, v90, v91
	ds_write2_b64 v162, v[92:93], v[88:89] offset1:4
	v_cvt_pk_bf16_f32 v84, v84, v85
	v_cvt_pk_bf16_f32 v85, v86, v87
	v_cvt_pk_bf16_f32 v80, v80, v81
	v_cvt_pk_bf16_f32 v81, v82, v83
	v_cvt_pk_bf16_f32 v76, v76, v77
	v_cvt_pk_bf16_f32 v77, v78, v79
	v_cvt_pk_bf16_f32 v72, v72, v73
	v_cvt_pk_bf16_f32 v73, v74, v75
	v_add_u32_e32 v74, 0x800, v162
	v_cvt_pk_bf16_f32 v68, v68, v69
	v_cvt_pk_bf16_f32 v69, v70, v71
	ds_write2_b64 v162, v[84:85], v[80:81] offset0:8 offset1:12
	v_cvt_pk_bf16_f32 v60, v60, v61
	v_cvt_pk_bf16_f32 v61, v62, v63
	ds_write2_b64 v74, v[76:77], v[72:73] offset0:32 offset1:36
	v_cvt_pk_bf16_f32 v56, v56, v57
	v_cvt_pk_bf16_f32 v57, v58, v59
	ds_write2_b64 v74, v[68:69], v[60:61] offset0:40 offset1:44
	v_cvt_pk_bf16_f32 v52, v52, v53
	v_cvt_pk_bf16_f32 v53, v54, v55
	v_add_u32_e32 v54, 0x1000, v162
	v_cvt_pk_bf16_f32 v48, v48, v49
	v_cvt_pk_bf16_f32 v49, v50, v51
	ds_write2_b64 v54, v[56:57], v[52:53] offset0:64 offset1:68
	v_cvt_pk_bf16_f32 v44, v44, v45
	v_cvt_pk_bf16_f32 v45, v46, v47
	ds_write2_b64 v54, v[48:49], v[44:45] offset0:72 offset1:76
	v_cvt_pk_bf16_f32 v40, v40, v41
	v_cvt_pk_bf16_f32 v41, v42, v43
	v_cvt_pk_bf16_f32 v36, v36, v37
	v_cvt_pk_bf16_f32 v37, v38, v39
	v_add_u32_e32 v38, 0x1800, v162
	v_cvt_pk_bf16_f32 v32, v32, v33
	v_cvt_pk_bf16_f32 v33, v34, v35
	v_cvt_pk_bf16_f32 v28, v28, v29
	v_cvt_pk_bf16_f32 v29, v30, v31
	v_cvt_pk_bf16_f32 v24, v24, v25
	v_cvt_pk_bf16_f32 v25, v26, v27
	ds_write2_b64 v38, v[40:41], v[36:37] offset0:96 offset1:100
	v_cvt_pk_bf16_f32 v20, v20, v21
	v_cvt_pk_bf16_f32 v21, v22, v23
	v_add_u32_e32 v22, 0x2000, v162
	v_cvt_pk_bf16_f32 v16, v16, v17
	v_cvt_pk_bf16_f32 v17, v18, v19
	v_mov_b32_e32 v0, v64
	v_mov_b32_e32 v1, v65
	v_mov_b32_e32 v2, v66
	v_mov_b32_e32 v3, v67
	ds_write2_b64 v38, v[32:33], v[28:29] offset0:104 offset1:108
	s_nop 2
	v_cvt_pk_bf16_f32 v12, v12, v13
	v_cvt_pk_bf16_f32 v13, v14, v15
	ds_write2_b64 v22, v[24:25], v[20:21] offset0:128 offset1:132
	ds_write2_b64 v22, v[16:17], v[12:13] offset0:136 offset1:140
	v_cvt_pk_bf16_f32 v0, v0, v1
	v_cvt_pk_bf16_f32 v1, v2, v3
	ds_write2_b64 v6, v[4:5], v[0:1] offset0:168 offset1:172
	s_waitcnt lgkmcnt(0)
	v_or_b32_e32 v0, s33, v150
	v_add_u32_e32 v12, s6, v148
	v_lshlrev_b32_e32 v136, 1, v0
	ds_read_b128 v[0:3], v163
	v_or_b32_e32 v4, v12, v149
	v_ashrrev_i32_e32 v5, 31, v4
	v_lshl_add_u64 v[8:9], s[2:3], 0, v[136:137]
	v_lshlrev_b64 v[4:5], 11, v[4:5]
	v_lshl_add_u64 v[10:11], v[8:9], 0, v[4:5]
	ds_read_b128 v[4:7], v163 offset:1152
	s_waitcnt lgkmcnt(1)
	global_store_dwordx4 v[10:11], v[0:3], off
	s_nop 1
	v_or_b32_e32 v0, v12, v151
	v_ashrrev_i32_e32 v1, 31, v0
	v_lshlrev_b64 v[0:1], 11, v[0:1]
	v_lshl_add_u64 v[0:1], v[8:9], 0, v[0:1]
	s_waitcnt lgkmcnt(0)
	global_store_dwordx4 v[0:1], v[4:7], off
	ds_read_b128 v[0:3], v163 offset:2304
	s_nop 0
	v_or_b32_e32 v4, v12, v152
	v_ashrrev_i32_e32 v5, 31, v4
	v_lshlrev_b64 v[4:5], 11, v[4:5]
	v_lshl_add_u64 v[10:11], v[8:9], 0, v[4:5]
	ds_read_b128 v[4:7], v163 offset:3456
	s_waitcnt lgkmcnt(1)
	global_store_dwordx4 v[10:11], v[0:3], off
	s_nop 1
	v_or_b32_e32 v0, v12, v153
	v_ashrrev_i32_e32 v1, 31, v0
	v_lshlrev_b64 v[0:1], 11, v[0:1]
	v_lshl_add_u64 v[0:1], v[8:9], 0, v[0:1]
	s_waitcnt lgkmcnt(0)
	global_store_dwordx4 v[0:1], v[4:7], off
	ds_read_b128 v[0:3], v163 offset:4608
	s_nop 0
	v_add_u32_e32 v4, v12, v154
	v_ashrrev_i32_e32 v5, 31, v4
	v_lshlrev_b64 v[4:5], 11, v[4:5]
	v_lshl_add_u64 v[10:11], v[8:9], 0, v[4:5]
	ds_read_b128 v[4:7], v163 offset:5760
	s_waitcnt lgkmcnt(1)
	global_store_dwordx4 v[10:11], v[0:3], off
	s_nop 1
	v_add_u32_e32 v0, v12, v155
	v_ashrrev_i32_e32 v1, 31, v0
	v_lshlrev_b64 v[0:1], 11, v[0:1]
	v_lshl_add_u64 v[0:1], v[8:9], 0, v[0:1]
	s_waitcnt lgkmcnt(0)
	global_store_dwordx4 v[0:1], v[4:7], off
	ds_read_b128 v[0:3], v163 offset:6912
	s_nop 0
	v_add_u32_e32 v4, v12, v156
	v_ashrrev_i32_e32 v5, 31, v4
	v_lshlrev_b64 v[4:5], 11, v[4:5]
	v_lshl_add_u64 v[10:11], v[8:9], 0, v[4:5]
	ds_read_b128 v[4:7], v163 offset:8064
	s_waitcnt lgkmcnt(1)
	global_store_dwordx4 v[10:11], v[0:3], off
	s_nop 1
	v_add_u32_e32 v0, v12, v157
	v_ashrrev_i32_e32 v1, 31, v0
	v_lshlrev_b64 v[0:1], 11, v[0:1]
	v_lshl_add_u64 v[0:1], v[8:9], 0, v[0:1]
	s_waitcnt lgkmcnt(0)
	global_store_dwordx4 v[0:1], v[4:7], off
	ds_read_b128 v[0:3], v163 offset:9216
	s_nop 0
	v_add_u32_e32 v4, v12, v158
	v_ashrrev_i32_e32 v5, 31, v4
	v_lshlrev_b64 v[4:5], 11, v[4:5]
	v_lshl_add_u64 v[10:11], v[8:9], 0, v[4:5]
	ds_read_b128 v[4:7], v163 offset:10368
	s_waitcnt lgkmcnt(1)
	global_store_dwordx4 v[10:11], v[0:3], off
	s_nop 1
	v_add_u32_e32 v0, v12, v159
	v_ashrrev_i32_e32 v1, 31, v0
	v_lshlrev_b64 v[0:1], 11, v[0:1]
	v_lshl_add_u64 v[0:1], v[8:9], 0, v[0:1]
	s_waitcnt lgkmcnt(0)
	global_store_dwordx4 v[0:1], v[4:7], off
	ds_read_b128 v[0:3], v163 offset:11520
	s_nop 0
	v_add_u32_e32 v4, v12, v160
	v_ashrrev_i32_e32 v5, 31, v4
	v_lshlrev_b64 v[4:5], 11, v[4:5]
	v_lshl_add_u64 v[10:11], v[8:9], 0, v[4:5]
	ds_read_b128 v[4:7], v163 offset:12672
	s_waitcnt lgkmcnt(1)
	global_store_dwordx4 v[10:11], v[0:3], off
	s_nop 1
	v_add_u32_e32 v0, v12, v161
	v_ashrrev_i32_e32 v1, 31, v0
	v_lshlrev_b64 v[0:1], 11, v[0:1]
	v_lshl_add_u64 v[0:1], v[8:9], 0, v[0:1]
	s_waitcnt lgkmcnt(0)
	global_store_dwordx4 v[0:1], v[4:7], off
	s_cbranch_scc1 .LBB0_1774

	.amdhsa_kernel _Z9mk_kernel6Params
		.amdhsa_group_segment_fixed_size 8192
		.amdhsa_private_segment_fixed_size 0
		.amdhsa_kernarg_size 656
		.amdhsa_user_sgpr_count 2
		.amdhsa_user_sgpr_dispatch_ptr 0
		.amdhsa_user_sgpr_queue_ptr 0
		.amdhsa_user_sgpr_kernarg_segment_ptr 1
		.amdhsa_user_sgpr_dispatch_id 0
		.amdhsa_user_sgpr_kernarg_preload_length 0
		.amdhsa_user_sgpr_kernarg_preload_offset 0
		.amdhsa_user_sgpr_private_segment_size 0
		.amdhsa_uses_dynamic_stack 0
		.amdhsa_enable_private_segment 0
		.amdhsa_system_sgpr_workgroup_id_x 1
		.amdhsa_system_sgpr_workgroup_id_y 0
		.amdhsa_system_sgpr_workgroup_id_z 0
		.amdhsa_system_sgpr_workgroup_info 0
		.amdhsa_system_vgpr_workitem_id 2
		.amdhsa_next_free_vgpr 256
		.amdhsa_next_free_sgpr 102
		.amdhsa_accum_offset 256
		.amdhsa_reserve_vcc 1
		.amdhsa_float_round_mode_32 0
		.amdhsa_float_round_mode_16_64 0
		.amdhsa_float_denorm_mode_32 3
		.amdhsa_float_denorm_mode_16_64 3
		.amdhsa_dx10_clamp 1
		.amdhsa_ieee_mode 1
		.amdhsa_fp16_overflow 0
		.amdhsa_tg_split 0
		.amdhsa_exception_fp_ieee_invalid_op 0
		.amdhsa_exception_fp_denorm_src 0
		.amdhsa_exception_fp_ieee_div_zero 0
		.amdhsa_exception_fp_ieee_overflow 0
		.amdhsa_exception_fp_ieee_underflow 0
		.amdhsa_exception_fp_ieee_inexact 0
		.amdhsa_exception_int_div_zero 0
	.end_amdhsa_kernel

amdhsa.kernels:
  - .agpr_count:     0
    .args:
      - .offset:         0
        .size:           400
        .value_kind:     by_value
      - .offset:         400
        .size:           4
        .value_kind:     hidden_block_count_x
      - .offset:         404
        .size:           4
        .value_kind:     hidden_block_count_y
      - .offset:         408
        .size:           4
        .value_kind:     hidden_block_count_z
      - .offset:         412
        .size:           2
        .value_kind:     hidden_group_size_x
      - .offset:         414
        .size:           2
        .value_kind:     hidden_group_size_y
      - .offset:         416
        .size:           2
        .value_kind:     hidden_group_size_z
      - .offset:         418
        .size:           2
        .value_kind:     hidden_remainder_x
      - .offset:         420
        .size:           2
        .value_kind:     hidden_remainder_y
      - .offset:         422
        .size:           2
        .value_kind:     hidden_remainder_z
      - .offset:         440
        .size:           8
        .value_kind:     hidden_global_offset_x
      - .offset:         448
        .size:           8
        .value_kind:     hidden_global_offset_y
      - .offset:         456
        .size:           8
        .value_kind:     hidden_global_offset_z
      - .offset:         464
        .size:           2
        .value_kind:     hidden_grid_dims
      - .offset:         488
        .size:           8
        .value_kind:     hidden_multigrid_sync_arg
      - .offset:         520
        .size:           4
        .value_kind:     hidden_dynamic_lds_size
    .group_segment_fixed_size: 8192
    .kernarg_segment_align: 8
    .kernarg_segment_size: 656
    .language:       OpenCL C
    .language_version:
      - 2
      - 0
    .max_flat_workgroup_size: 256
    .name:           _Z9mk_kernel6Params
    .private_segment_fixed_size: 0
    .sgpr_count:     108
    .sgpr_spill_count: 153
    .symbol:         _Z9mk_kernel6Params.kd
    .uniform_work_group_size: 1
    .uses_dynamic_stack: false
    .vgpr_count:     256
    .vgpr_spill_count: 0
    .wavefront_size: 64
